# hoist the 8 per-row-group ssq loads of P1/P4/P6/P10 epilogues before the K-loop (no serialized vmcnt(0) round trips)
# speedup vs baseline: 1.0057x; 1.0057x over previous
; __device__ __forceinline__ float row_rstd(const u64* ssq, int r) { return __builtin_amdgcn_rsqf(fx_to_pos(ssq[r]) * (1.0f / 4096.0f) + RMS_EPS); }
;     __device__ __forceinline__ void operator()(const f32x4 (&acc)[2][2][4][2], const Unit& u, int wr, int wc, int fr, int fq) const {
;     ...
;                 for (int m = 0; m < 4; ++m) { const int r = row0 + ai * HALF + m * 16; const float rs = row_rstd(ssq, r); bf16_t* rowp = Z + (size_t)r * AB_Z + col0;
; template <class Epi, class Sched, bool ALIGN_EPI = false, bool SP2 = false>
; __device__ __forceinline__ void gemm_phase(PG8_LAS unsigned char* lds, const Gemm g, const Sched& S, const Epi& E, const int wid) {
;     ...
;         for (int a = 0; a < 2; ++a)
; #pragma unroll
;             for (int b = 0; b < 2; ++b)
; #pragma unroll
;                 for (int m = 0; m < 4; ++m)
; #pragma unroll
;                     for (int n = 0; n < 2; ++n) acc[a][b][m][n] = (f32x4){0.f, 0.f, 0.f, 0.f};
;         cur = nxt; cA = nA; cB = nB; ++ui; nt = cur.kn;
.LBB0_248:
	v_lshl_add_u32 v244, s20, 8, v157
	v_ashrrev_i32_e32 v245, 31, v244
	v_lshl_add_u64 v[244:245], v[244:245], 3, s[4:5]
	global_load_dwordx2 v[230:231], v[244:245], off
	global_load_dwordx2 v[232:233], v[244:245], off offset:128
	global_load_dwordx2 v[234:235], v[244:245], off offset:256
	global_load_dwordx2 v[236:237], v[244:245], off offset:384
	global_load_dwordx2 v[238:239], v[244:245], off offset:1024
	global_load_dwordx2 v[240:241], v[244:245], off offset:1152
	global_load_dwordx2 v[242:243], v[244:245], off offset:1280
	global_load_dwordx2 v[244:245], v[244:245], off offset:1408
	s_ashr_i32 s15, s14, 31
	s_lshl_b64 s[16:17], s[14:15], 21
	s_add_u32 s16, s78, s16
	s_addc_u32 s17, s79, s17
	s_and_b64 s[18:19], s[0:1], exec
	s_cselect_b32 s15, s17, s23
	s_cselect_b32 s21, s16, s22
	s_ashr_i32 s13, s12, 31
	s_lshl_b64 s[18:19], s[12:13], 21
	s_add_u32 s18, s82, s18
	s_addc_u32 s19, s83, s19
	s_and_b64 s[26:27], s[0:1], exec
	s_cselect_b32 s13, s19, s25
	s_cselect_b32 s45, s18, s24
	s_add_u32 s22, s22, 0x100080
	s_addc_u32 s23, s23, 0
	s_add_u32 s46, s24, 0x100
	v_mov_b32_e32 v0, 0
	s_addc_u32 s47, s25, 0
	s_mov_b32 s48, -2
	v_mov_b32_e32 v1, v0
	v_mov_b32_e32 v2, v0
	v_mov_b32_e32 v3, v0
	v_mov_b32_e32 v4, v0
	v_mov_b32_e32 v5, v0
	v_mov_b32_e32 v6, v0
	v_mov_b32_e32 v7, v0
	s_waitcnt vmcnt(0)
	v_mov_b32_e32 v16, v0
	v_mov_b32_e32 v17, v0
	v_mov_b32_e32 v18, v0
	v_mov_b32_e32 v19, v0
	v_mov_b32_e32 v20, v0
	v_mov_b32_e32 v21, v0
	v_mov_b32_e32 v22, v0
	v_mov_b32_e32 v23, v0
	v_mov_b32_e32 v32, v0
	v_mov_b32_e32 v33, v0
	v_mov_b32_e32 v34, v0
	v_mov_b32_e32 v35, v0
	v_mov_b32_e32 v36, v0
	v_mov_b32_e32 v37, v0
	v_mov_b32_e32 v38, v0
	v_mov_b32_e32 v39, v0
	v_mov_b32_e32 v48, v0
	v_mov_b32_e32 v49, v0
	v_mov_b32_e32 v50, v0
	v_mov_b32_e32 v51, v0
	v_mov_b32_e32 v52, v0
	v_mov_b32_e32 v53, v0
	v_mov_b32_e32 v54, v0
	v_mov_b32_e32 v55, v0
	v_mov_b32_e32 v8, v0
	v_mov_b32_e32 v9, v0
	v_mov_b32_e32 v10, v0
	v_mov_b32_e32 v11, v0
	v_mov_b32_e32 v12, v0
	v_mov_b32_e32 v13, v0
	v_mov_b32_e32 v14, v0
	v_mov_b32_e32 v15, v0
	v_mov_b32_e32 v24, v0
	v_mov_b32_e32 v25, v0
	v_mov_b32_e32 v26, v0
	v_mov_b32_e32 v27, v0
	v_mov_b32_e32 v28, v0
	v_mov_b32_e32 v29, v0
	v_mov_b32_e32 v30, v0
	v_mov_b32_e32 v31, v0
	v_mov_b32_e32 v40, v0
	v_mov_b32_e32 v41, v0
	v_mov_b32_e32 v42, v0
	v_mov_b32_e32 v43, v0
	v_mov_b32_e32 v44, v0
	v_mov_b32_e32 v45, v0
	v_mov_b32_e32 v46, v0
	v_mov_b32_e32 v47, v0
	v_mov_b32_e32 v56, v0
	v_mov_b32_e32 v57, v0
	v_mov_b32_e32 v58, v0
	v_mov_b32_e32 v59, v0
	v_mov_b32_e32 v60, v0
	v_mov_b32_e32 v61, v0
	v_mov_b32_e32 v62, v0
	v_mov_b32_e32 v63, v0
	v_mov_b32_e32 v64, v0
	v_mov_b32_e32 v65, v0
	v_mov_b32_e32 v66, v0
	v_mov_b32_e32 v67, v0
	v_mov_b32_e32 v68, v0
	v_mov_b32_e32 v69, v0
	v_mov_b32_e32 v70, v0
	v_mov_b32_e32 v71, v0
	v_mov_b32_e32 v80, v0
	v_mov_b32_e32 v81, v0
	v_mov_b32_e32 v82, v0
	v_mov_b32_e32 v83, v0
	v_mov_b32_e32 v84, v0
	v_mov_b32_e32 v85, v0
	v_mov_b32_e32 v86, v0
	v_mov_b32_e32 v87, v0
	v_mov_b32_e32 v96, v0
	v_mov_b32_e32 v97, v0
	v_mov_b32_e32 v98, v0
	v_mov_b32_e32 v99, v0
	v_mov_b32_e32 v100, v0
	v_mov_b32_e32 v101, v0
	v_mov_b32_e32 v102, v0
	v_mov_b32_e32 v103, v0
	v_mov_b32_e32 v112, v0
	v_mov_b32_e32 v113, v0
	v_mov_b32_e32 v114, v0
	v_mov_b32_e32 v115, v0
	v_mov_b32_e32 v116, v0
	v_mov_b32_e32 v117, v0
	v_mov_b32_e32 v118, v0
	v_mov_b32_e32 v119, v0
	v_mov_b32_e32 v72, v0
	v_mov_b32_e32 v73, v0
	v_mov_b32_e32 v74, v0
	v_mov_b32_e32 v75, v0
	v_mov_b32_e32 v76, v0
	v_mov_b32_e32 v77, v0
	v_mov_b32_e32 v78, v0
	v_mov_b32_e32 v79, v0
	v_mov_b32_e32 v88, v0
	v_mov_b32_e32 v89, v0
	v_mov_b32_e32 v90, v0
	v_mov_b32_e32 v91, v0
	v_mov_b32_e32 v92, v0
	v_mov_b32_e32 v93, v0
	v_mov_b32_e32 v94, v0
	v_mov_b32_e32 v95, v0
	v_mov_b32_e32 v104, v0
	v_mov_b32_e32 v105, v0
	v_mov_b32_e32 v106, v0
	v_mov_b32_e32 v107, v0
	v_mov_b32_e32 v108, v0
	v_mov_b32_e32 v109, v0
	v_mov_b32_e32 v110, v0
	v_mov_b32_e32 v111, v0
	v_mov_b32_e32 v120, v0
	v_mov_b32_e32 v121, v0
	v_mov_b32_e32 v122, v0
	v_mov_b32_e32 v123, v0
	v_mov_b32_e32 v124, v0
	v_mov_b32_e32 v125, v0
	v_mov_b32_e32 v126, v0
	v_mov_b32_e32 v127, v0

; __device__ __forceinline__ u32x4 pack8(const f32x4 a, const f32x4 b) { u32x4 w; w.x = cvt_pk_bf16(a[0], a[1]); w.y = cvt_pk_bf16(a[2], a[3]); w.z = cvt_pk_bf16(b[0], b[1]); w.w = cvt_pk_bf16(b[2], b[3]); return w; }
; __device__ __forceinline__ float row_rstd(const u64* ssq, int r) { return __builtin_amdgcn_rsqf(fx_to_pos(ssq[r]) * (1.0f / 4096.0f) + RMS_EPS); }
;     __device__ __forceinline__ void operator()(const f32x4 (&acc)[2][2][4][2], const Unit& u, int wr, int wc, int fr, int fq) const {
;         const int row0 = u.pm * BM + wr * 64 + fr;
;         if (u.pn < 40) {
;             const int col0 = u.pn * BM + wc * 32 + 8 * fq;
; #pragma unroll
;             for (int ai = 0; ai < 2; ++ai)
; #pragma unroll
;                 for (int m = 0; m < 4; ++m) { const int r = row0 + ai * HALF + m * 16; const float rs = row_rstd(ssq, r); bf16_t* rowp = Z + (size_t)r * AB_Z + col0;
; #pragma unroll
;                     for (int bj = 0; bj < 2; ++bj) *(u32x4*)(rowp + bj * HALF) = pack8(acc[ai][bj][m][0] * rs, acc[ai][bj][m][1] * rs); }
.LBB0_258:
	v_ashrrev_i32_e32 v149, 31, v148
	v_lshl_add_u64 v[150:151], v[148:149], 3, s[4:5]
	s_sub_i32 s13, 32, s43
	v_lshl_add_u32 v164, s44, 8, v159
	v_mov_b64_e32 v[152:153], s[80:81]
	v_ashrrev_i32_e32 v165, 31, v164
	v_or_b32_e32 v166, 16, v148
	v_mad_i64_i32 v[168:169], s[20:21], v148, s42, v[152:153]
	v_ashrrev_i32_e32 v167, 31, v166
	v_mov_b32_e32 v136, v231
	v_cvt_f32_u32_e32 v149, v230
	v_lshlrev_b64 v[154:155], s43, v[136:137]
	v_min_u32_e32 v136, 1, v154
	v_or_b32_e32 v136, v155, v136
	v_cvt_f32_u32_e32 v136, v136
	v_lshlrev_b64 v[154:155], 1, v[164:165]
	v_lshl_add_u64 v[168:169], v[168:169], 0, v[154:155]
	v_lshl_add_u64 v[164:165], v[166:167], 3, s[4:5]
	v_ldexp_f32 v136, v136, s13
	v_fmac_f32_e32 v136, 0x2f800000, v149
	v_fmamk_f32 v136, v136, 0x39800000, v163
	v_rsq_f32_e32 v136, v136
	s_nop 0
	v_pk_mul_f32 v[126:127], v[126:127], v[136:137] op_sel_hi:[1,0]
	v_pk_mul_f32 v[124:125], v[124:125], v[136:137] op_sel_hi:[1,0]
	v_pk_mul_f32 v[122:123], v[122:123], v[136:137] op_sel_hi:[1,0]
	v_pk_mul_f32 v[120:121], v[120:121], v[136:137] op_sel_hi:[1,0]
	v_pk_mul_f32 v[170:171], v[114:115], v[136:137] op_sel_hi:[1,0]
	v_pk_mul_f32 v[172:173], v[112:113], v[136:137] op_sel_hi:[1,0]
	v_cvt_pk_bf16_f32 v112, v124, v125
	v_cvt_pk_bf16_f32 v113, v126, v127
	v_cvt_pk_bf16_f32 v114, v120, v121
	v_cvt_pk_bf16_f32 v115, v122, v123
	v_pk_mul_f32 v[118:119], v[118:119], v[136:137] op_sel_hi:[1,0]
	v_pk_mul_f32 v[116:117], v[116:117], v[136:137] op_sel_hi:[1,0]
	global_store_dwordx4 v[168:169], v[112:115], off
	s_nop 1
	v_cvt_pk_bf16_f32 v112, v116, v117
	v_cvt_pk_bf16_f32 v113, v118, v119
	v_cvt_pk_bf16_f32 v114, v172, v173
	v_cvt_pk_bf16_f32 v115, v170, v171
	global_store_dwordx4 v[168:169], v[112:115], off offset:256
	s_nop 1
	v_mov_b32_e32 v136, v233
	v_lshlrev_b64 v[116:117], s43, v[136:137]
	v_min_u32_e32 v113, 1, v116
	v_or_b32_e32 v113, v117, v113
	v_cvt_f32_u32_e32 v115, v113
	v_cvt_f32_u32_e32 v116, v232
	v_or_b32_e32 v114, 32, v148
	v_mad_i64_i32 v[112:113], s[20:21], v166, s42, v[152:153]
	v_ldexp_f32 v115, v115, s13
	v_fmac_f32_e32 v115, 0x2f800000, v116
	v_fmamk_f32 v115, v115, 0x39800000, v163
	v_rsq_f32_e32 v116, v115
	v_ashrrev_i32_e32 v115, 31, v114
	v_lshl_add_u64 v[112:113], v[112:113], 0, v[154:155]
	v_lshl_add_u64 v[118:119], v[114:115], 3, s[4:5]
	v_pk_mul_f32 v[110:111], v[110:111], v[116:117] op_sel_hi:[1,0]
	v_pk_mul_f32 v[108:109], v[108:109], v[116:117] op_sel_hi:[1,0]
	v_pk_mul_f32 v[106:107], v[106:107], v[116:117] op_sel_hi:[1,0]
	v_pk_mul_f32 v[104:105], v[104:105], v[116:117] op_sel_hi:[1,0]
	v_pk_mul_f32 v[102:103], v[102:103], v[116:117] op_sel_hi:[1,0]
	v_pk_mul_f32 v[100:101], v[100:101], v[116:117] op_sel_hi:[1,0]
	v_pk_mul_f32 v[120:121], v[98:99], v[116:117] op_sel_hi:[1,0]
	v_pk_mul_f32 v[116:117], v[96:97], v[116:117] op_sel_hi:[1,0]
	v_cvt_pk_bf16_f32 v96, v108, v109
	v_cvt_pk_bf16_f32 v97, v110, v111
	v_cvt_pk_bf16_f32 v98, v104, v105
	v_cvt_pk_bf16_f32 v99, v106, v107
	global_store_dwordx4 v[112:113], v[96:99], off
	s_nop 1
	v_cvt_pk_bf16_f32 v96, v100, v101
	v_cvt_pk_bf16_f32 v97, v102, v103
	v_cvt_pk_bf16_f32 v98, v116, v117
	v_cvt_pk_bf16_f32 v99, v120, v121
	global_store_dwordx4 v[112:113], v[96:99], off offset:256
	s_nop 1
	v_mov_b32_e32 v136, v235
	v_lshlrev_b64 v[100:101], s43, v[136:137]
	v_min_u32_e32 v97, 1, v100
	v_or_b32_e32 v97, v101, v97
	v_cvt_f32_u32_e32 v99, v97
	v_cvt_f32_u32_e32 v100, v234
	v_or_b32_e32 v98, 48, v148
	v_mad_i64_i32 v[96:97], s[20:21], v114, s42, v[152:153]
	v_ldexp_f32 v99, v99, s13
	v_fmac_f32_e32 v99, 0x2f800000, v100
	v_fmamk_f32 v99, v99, 0x39800000, v163
	v_rsq_f32_e32 v100, v99
	v_ashrrev_i32_e32 v99, 31, v98
	v_lshl_add_u64 v[96:97], v[96:97], 0, v[154:155]
	v_lshl_add_u64 v[102:103], v[98:99], 3, s[4:5]
	v_pk_mul_f32 v[94:95], v[94:95], v[100:101] op_sel_hi:[1,0]
	v_pk_mul_f32 v[92:93], v[92:93], v[100:101] op_sel_hi:[1,0]
	v_pk_mul_f32 v[90:91], v[90:91], v[100:101] op_sel_hi:[1,0]
	v_pk_mul_f32 v[88:89], v[88:89], v[100:101] op_sel_hi:[1,0]
	v_pk_mul_f32 v[86:87], v[86:87], v[100:101] op_sel_hi:[1,0]
	v_pk_mul_f32 v[84:85], v[84:85], v[100:101] op_sel_hi:[1,0]
	v_pk_mul_f32 v[104:105], v[82:83], v[100:101] op_sel_hi:[1,0]
	v_pk_mul_f32 v[100:101], v[80:81], v[100:101] op_sel_hi:[1,0]
	v_cvt_pk_bf16_f32 v80, v92, v93
	v_cvt_pk_bf16_f32 v81, v94, v95
	v_cvt_pk_bf16_f32 v82, v88, v89
	v_cvt_pk_bf16_f32 v83, v90, v91
	global_store_dwordx4 v[96:97], v[80:83], off
	s_nop 1
	v_cvt_pk_bf16_f32 v80, v84, v85
	v_cvt_pk_bf16_f32 v81, v86, v87
	v_cvt_pk_bf16_f32 v82, v100, v101
	v_cvt_pk_bf16_f32 v83, v104, v105
	global_store_dwordx4 v[96:97], v[80:83], off offset:256
	s_nop 1
	v_mov_b32_e32 v136, v237
	v_lshlrev_b64 v[82:83], s43, v[136:137]
	v_min_u32_e32 v81, 1, v82
	v_or_b32_e32 v81, v83, v81
	v_cvt_f32_u32_e32 v81, v81
	v_cvt_f32_u32_e32 v80, v236
	v_mad_i64_i32 v[82:83], s[20:21], v98, s42, v[152:153]
	v_ldexp_f32 v81, v81, s13
	v_fmac_f32_e32 v81, 0x2f800000, v80
	v_fmamk_f32 v80, v81, 0x39800000, v163
	v_rsq_f32_e32 v80, v80
	v_lshl_add_u64 v[82:83], v[82:83], 0, v[154:155]
	v_pk_mul_f32 v[78:79], v[78:79], v[80:81] op_sel_hi:[1,0]
	v_pk_mul_f32 v[76:77], v[76:77], v[80:81] op_sel_hi:[1,0]
	v_pk_mul_f32 v[74:75], v[74:75], v[80:81] op_sel_hi:[1,0]
	v_pk_mul_f32 v[72:73], v[72:73], v[80:81] op_sel_hi:[1,0]
	v_pk_mul_f32 v[70:71], v[70:71], v[80:81] op_sel_hi:[1,0]
	v_pk_mul_f32 v[68:69], v[68:69], v[80:81] op_sel_hi:[1,0]
	v_pk_mul_f32 v[84:85], v[66:67], v[80:81] op_sel_hi:[1,0]
	v_pk_mul_f32 v[80:81], v[64:65], v[80:81] op_sel_hi:[1,0]
	v_cvt_pk_bf16_f32 v64, v76, v77
; __device__ __forceinline__ u32x4 pack8(const f32x4 a, const f32x4 b) { u32x4 w; w.x = cvt_pk_bf16(a[0], a[1]); w.y = cvt_pk_bf16(a[2], a[3]); w.z = cvt_pk_bf16(b[0], b[1]); w.w = cvt_pk_bf16(b[2], b[3]); return w; }
; __device__ __forceinline__ float row_rstd(const u64* ssq, int r) { return __builtin_amdgcn_rsqf(fx_to_pos(ssq[r]) * (1.0f / 4096.0f) + RMS_EPS); }
;     __device__ __forceinline__ void operator()(const f32x4 (&acc)[2][2][4][2], const Unit& u, int wr, int wc, int fr, int fq) const {
;         const int row0 = u.pm * BM + wr * 64 + fr;
;         if (u.pn < 40) {
;             const int col0 = u.pn * BM + wc * 32 + 8 * fq;
; #pragma unroll
;             for (int ai = 0; ai < 2; ++ai)
; #pragma unroll
;                 for (int m = 0; m < 4; ++m) { const int r = row0 + ai * HALF + m * 16; const float rs = row_rstd(ssq, r); bf16_t* rowp = Z + (size_t)r * AB_Z + col0;
; #pragma unroll
;                     for (int bj = 0; bj < 2; ++bj) *(u32x4*)(rowp + bj * HALF) = pack8(acc[ai][bj][m][0] * rs, acc[ai][bj][m][1] * rs); }
	v_cvt_pk_bf16_f32 v65, v78, v79
	v_cvt_pk_bf16_f32 v66, v72, v73
	v_cvt_pk_bf16_f32 v67, v74, v75
	global_store_dwordx4 v[82:83], v[64:67], off
	s_nop 1
	v_cvt_pk_bf16_f32 v64, v68, v69
	v_cvt_pk_bf16_f32 v65, v70, v71
	v_cvt_pk_bf16_f32 v66, v80, v81
	v_cvt_pk_bf16_f32 v67, v84, v85
	global_store_dwordx4 v[82:83], v[64:67], off offset:256
	s_nop 1
	v_mov_b32_e32 v136, v239
	v_lshlrev_b64 v[66:67], s43, v[136:137]
	v_min_u32_e32 v65, 1, v66
	v_or_b32_e32 v65, v67, v65
	v_cvt_f32_u32_e32 v65, v65
	v_cvt_f32_u32_e32 v64, v238
	v_add_u32_e32 v66, 0x80, v148
	v_mad_i64_i32 v[66:67], s[20:21], v66, s42, v[152:153]
	v_ldexp_f32 v65, v65, s13
	v_fmac_f32_e32 v65, 0x2f800000, v64
	v_fmamk_f32 v64, v65, 0x39800000, v163
	v_rsq_f32_e32 v64, v64
	v_lshl_add_u64 v[66:67], v[66:67], 0, v[154:155]
	v_pk_mul_f32 v[62:63], v[62:63], v[64:65] op_sel_hi:[1,0]
	v_pk_mul_f32 v[60:61], v[60:61], v[64:65] op_sel_hi:[1,0]
	v_pk_mul_f32 v[58:59], v[58:59], v[64:65] op_sel_hi:[1,0]
	v_pk_mul_f32 v[56:57], v[56:57], v[64:65] op_sel_hi:[1,0]
	v_pk_mul_f32 v[54:55], v[54:55], v[64:65] op_sel_hi:[1,0]
	v_pk_mul_f32 v[52:53], v[52:53], v[64:65] op_sel_hi:[1,0]
	v_pk_mul_f32 v[68:69], v[50:51], v[64:65] op_sel_hi:[1,0]
	v_pk_mul_f32 v[64:65], v[48:49], v[64:65] op_sel_hi:[1,0]
	v_cvt_pk_bf16_f32 v48, v60, v61
	v_cvt_pk_bf16_f32 v49, v62, v63
	v_cvt_pk_bf16_f32 v50, v56, v57
	v_cvt_pk_bf16_f32 v51, v58, v59
	global_store_dwordx4 v[66:67], v[48:51], off
	s_nop 1
	v_cvt_pk_bf16_f32 v48, v52, v53
	v_cvt_pk_bf16_f32 v49, v54, v55
	v_cvt_pk_bf16_f32 v50, v64, v65
	v_cvt_pk_bf16_f32 v51, v68, v69
	global_store_dwordx4 v[66:67], v[48:51], off offset:256
	s_nop 1
	v_mov_b32_e32 v136, v241
	v_lshlrev_b64 v[50:51], s43, v[136:137]
	v_min_u32_e32 v49, 1, v50
	v_or_b32_e32 v49, v51, v49
	v_cvt_f32_u32_e32 v49, v49
	v_cvt_f32_u32_e32 v48, v240
	v_add_u32_e32 v50, 0x90, v148
	v_mad_i64_i32 v[50:51], s[20:21], v50, s42, v[152:153]
	v_ldexp_f32 v49, v49, s13
	v_fmac_f32_e32 v49, 0x2f800000, v48
	v_fmamk_f32 v48, v49, 0x39800000, v163
	v_rsq_f32_e32 v48, v48
	v_lshl_add_u64 v[50:51], v[50:51], 0, v[154:155]
	v_pk_mul_f32 v[46:47], v[46:47], v[48:49] op_sel_hi:[1,0]
	v_pk_mul_f32 v[44:45], v[44:45], v[48:49] op_sel_hi:[1,0]
	v_pk_mul_f32 v[42:43], v[42:43], v[48:49] op_sel_hi:[1,0]
	v_pk_mul_f32 v[40:41], v[40:41], v[48:49] op_sel_hi:[1,0]
	v_pk_mul_f32 v[38:39], v[38:39], v[48:49] op_sel_hi:[1,0]
	v_pk_mul_f32 v[36:37], v[36:37], v[48:49] op_sel_hi:[1,0]
	v_pk_mul_f32 v[52:53], v[34:35], v[48:49] op_sel_hi:[1,0]
	v_pk_mul_f32 v[48:49], v[32:33], v[48:49] op_sel_hi:[1,0]
	v_cvt_pk_bf16_f32 v32, v44, v45
	v_cvt_pk_bf16_f32 v33, v46, v47
	v_cvt_pk_bf16_f32 v34, v40, v41
	v_cvt_pk_bf16_f32 v35, v42, v43
	global_store_dwordx4 v[50:51], v[32:35], off
	s_nop 1
	v_cvt_pk_bf16_f32 v32, v36, v37
	v_cvt_pk_bf16_f32 v33, v38, v39
	v_cvt_pk_bf16_f32 v34, v48, v49
	v_cvt_pk_bf16_f32 v35, v52, v53
	global_store_dwordx4 v[50:51], v[32:35], off offset:256
	s_nop 1
	v_mov_b32_e32 v136, v243
	v_lshlrev_b64 v[34:35], s43, v[136:137]
	v_min_u32_e32 v33, 1, v34
	v_or_b32_e32 v33, v35, v33
	v_cvt_f32_u32_e32 v33, v33
	v_cvt_f32_u32_e32 v32, v242
	v_add_u32_e32 v34, 0xa0, v148
	v_mad_i64_i32 v[34:35], s[20:21], v34, s42, v[152:153]
	v_ldexp_f32 v33, v33, s13
	v_fmac_f32_e32 v33, 0x2f800000, v32
	v_fmamk_f32 v32, v33, 0x39800000, v163
	v_rsq_f32_e32 v32, v32
	v_lshl_add_u64 v[34:35], v[34:35], 0, v[154:155]
	v_pk_mul_f32 v[30:31], v[30:31], v[32:33] op_sel_hi:[1,0]
	v_pk_mul_f32 v[28:29], v[28:29], v[32:33] op_sel_hi:[1,0]
	v_pk_mul_f32 v[26:27], v[26:27], v[32:33] op_sel_hi:[1,0]
	v_pk_mul_f32 v[24:25], v[24:25], v[32:33] op_sel_hi:[1,0]
	v_pk_mul_f32 v[22:23], v[22:23], v[32:33] op_sel_hi:[1,0]
	v_pk_mul_f32 v[20:21], v[20:21], v[32:33] op_sel_hi:[1,0]
	v_pk_mul_f32 v[36:37], v[18:19], v[32:33] op_sel_hi:[1,0]
	v_pk_mul_f32 v[32:33], v[16:17], v[32:33] op_sel_hi:[1,0]
	v_cvt_pk_bf16_f32 v16, v28, v29
	v_cvt_pk_bf16_f32 v17, v30, v31
	v_cvt_pk_bf16_f32 v18, v24, v25
	v_cvt_pk_bf16_f32 v19, v26, v27
	global_store_dwordx4 v[34:35], v[16:19], off
	s_nop 1
	v_cvt_pk_bf16_f32 v16, v20, v21
	v_cvt_pk_bf16_f32 v17, v22, v23
	v_cvt_pk_bf16_f32 v18, v32, v33
	v_cvt_pk_bf16_f32 v19, v36, v37
	global_store_dwordx4 v[34:35], v[16:19], off offset:256
	s_nop 1
	v_mov_b32_e32 v136, v245
	v_lshlrev_b64 v[18:19], s43, v[136:137]
	v_min_u32_e32 v17, 1, v18
	v_or_b32_e32 v17, v19, v17
	v_cvt_f32_u32_e32 v17, v17
	v_cvt_f32_u32_e32 v16, v244
	v_add_u32_e32 v18, 0xb0, v148
	v_mad_i64_i32 v[18:19], s[20:21], v18, s42, v[152:153]
	v_ldexp_f32 v17, v17, s13
	v_fmac_f32_e32 v17, 0x2f800000, v16
	v_fmamk_f32 v16, v17, 0x39800000, v163
	v_rsq_f32_e32 v16, v16
	v_lshl_add_u64 v[18:19], v[18:19], 0, v[154:155]
	v_pk_mul_f32 v[14:15], v[14:15], v[16:17] op_sel_hi:[1,0]
	v_pk_mul_f32 v[12:13], v[12:13], v[16:17] op_sel_hi:[1,0]
	v_pk_mul_f32 v[10:11], v[10:11], v[16:17] op_sel_hi:[1,0]
	v_pk_mul_f32 v[8:9], v[8:9], v[16:17] op_sel_hi:[1,0]
	v_pk_mul_f32 v[6:7], v[6:7], v[16:17] op_sel_hi:[1,0]
	v_pk_mul_f32 v[4:5], v[4:5], v[16:17] op_sel_hi:[1,0]
	v_pk_mul_f32 v[20:21], v[2:3], v[16:17] op_sel_hi:[1,0]
	v_pk_mul_f32 v[16:17], v[0:1], v[16:17] op_sel_hi:[1,0]
	v_cvt_pk_bf16_f32 v0, v12, v13
	v_cvt_pk_bf16_f32 v1, v14, v15
	v_cvt_pk_bf16_f32 v2, v8, v9
	v_cvt_pk_bf16_f32 v3, v10, v11
	global_store_dwordx4 v[18:19], v[0:3], off
	s_nop 1
	v_cvt_pk_bf16_f32 v0, v4, v5
	v_cvt_pk_bf16_f32 v1, v6, v7
	v_cvt_pk_bf16_f32 v2, v16, v17
	v_cvt_pk_bf16_f32 v3, v20, v21
	global_store_dwordx4 v[18:19], v[0:3], off offset:256
	s_andn2_b64 vcc, exec, s[0:1]
	s_mov_b64 s[0:1], -1
	s_cbranch_vccnz .LBB0_241

; __device__ __forceinline__ float row_rstd(const u64* ssq, int r) { return __builtin_amdgcn_rsqf(fx_to_pos(ssq[r]) * (1.0f / 4096.0f) + RMS_EPS); }
;     __device__ __forceinline__ void operator()(const f32x4 (&acc)[2][2][4][2], const Unit& u, int wr, int wc, int fr, int fq) const {
;     ...
;             for (int m = 0; m < 4; ++m) { const int r = row0 + ai * HALF + m * 16; const float rs = row_rstd(ssq, r); f32x4 o[2];
; template <class Epi, class Sched, bool ALIGN_EPI = false, bool SP2 = false>
; __device__ __forceinline__ void gemm_phase(PG8_LAS unsigned char* lds, const Gemm g, const Sched& S, const Epi& E, const int wid) {
;     ...
;         for (int a = 0; a < 2; ++a)
; #pragma unroll
;             for (int b = 0; b < 2; ++b)
; #pragma unroll
;                 for (int m = 0; m < 4; ++m)
; #pragma unroll
;                     for (int n = 0; n < 2; ++n) acc[a][b][m][n] = (f32x4){0.f, 0.f, 0.f, 0.f};
;         cur = nxt; cA = nA; cB = nB; ++ui; nt = cur.kn;
.LBB0_962:
	v_lshl_add_u32 v244, s20, 8, v151
	v_ashrrev_i32_e32 v245, 31, v244
	v_lshl_add_u64 v[244:245], v[244:245], 3, s[2:3]
	global_load_dwordx2 v[228:229], v[244:245], off
	global_load_dwordx2 v[230:231], v[244:245], off offset:128
	global_load_dwordx2 v[232:233], v[244:245], off offset:256
	global_load_dwordx2 v[234:235], v[244:245], off offset:384
	global_load_dwordx2 v[236:237], v[244:245], off offset:1024
	global_load_dwordx2 v[238:239], v[244:245], off offset:1152
	global_load_dwordx2 v[240:241], v[244:245], off offset:1280
	global_load_dwordx2 v[242:243], v[244:245], off offset:1408
	s_ashr_i32 s15, s14, 31
	s_lshl_b64 s[16:17], s[14:15], 21
	s_add_u32 s16, s78, s16
	s_addc_u32 s17, s79, s17
	s_and_b64 s[18:19], s[0:1], exec
	s_cselect_b32 s15, s17, s23
	s_cselect_b32 s48, s16, s22
	s_ashr_i32 s13, s12, 31
	s_lshl_b64 s[18:19], s[12:13], 21
	s_add_u32 s18, s30, s18
	s_addc_u32 s19, s31, s19
	s_and_b64 s[26:27], s[0:1], exec
	s_cselect_b32 s13, s19, s25
	s_cselect_b32 s49, s18, s24
	s_add_u32 s22, s22, 0x100080
	s_addc_u32 s23, s23, 0
	s_add_u32 s50, s24, 0x100
	v_mov_b32_e32 v0, 0
	s_addc_u32 s51, s25, 0
	s_mov_b32 s52, -2
	v_mov_b32_e32 v1, v0
	v_mov_b32_e32 v2, v0
	v_mov_b32_e32 v3, v0
	v_mov_b32_e32 v4, v0
	v_mov_b32_e32 v5, v0
	v_mov_b32_e32 v6, v0
	v_mov_b32_e32 v7, v0
	v_mov_b32_e32 v16, v0
	v_mov_b32_e32 v17, v0
	v_mov_b32_e32 v18, v0
	v_mov_b32_e32 v19, v0
	v_mov_b32_e32 v20, v0
	v_mov_b32_e32 v21, v0
	v_mov_b32_e32 v22, v0
	v_mov_b32_e32 v23, v0
	v_mov_b32_e32 v32, v0
	v_mov_b32_e32 v33, v0
	v_mov_b32_e32 v34, v0
	v_mov_b32_e32 v35, v0
	v_mov_b32_e32 v36, v0
	v_mov_b32_e32 v37, v0
	v_mov_b32_e32 v38, v0
	v_mov_b32_e32 v39, v0
	v_mov_b32_e32 v48, v0
	v_mov_b32_e32 v49, v0
	v_mov_b32_e32 v50, v0
	v_mov_b32_e32 v51, v0
	v_mov_b32_e32 v52, v0
	v_mov_b32_e32 v53, v0
	v_mov_b32_e32 v54, v0
	v_mov_b32_e32 v55, v0
	v_mov_b32_e32 v8, v0
	v_mov_b32_e32 v9, v0
	v_mov_b32_e32 v10, v0
	v_mov_b32_e32 v11, v0
	v_mov_b32_e32 v12, v0
	v_mov_b32_e32 v13, v0
	v_mov_b32_e32 v14, v0
	v_mov_b32_e32 v15, v0
	v_mov_b32_e32 v24, v0
	v_mov_b32_e32 v25, v0
	v_mov_b32_e32 v26, v0
	v_mov_b32_e32 v27, v0
	v_mov_b32_e32 v28, v0
	v_mov_b32_e32 v29, v0
	v_mov_b32_e32 v30, v0
	v_mov_b32_e32 v31, v0
	v_mov_b32_e32 v40, v0
	v_mov_b32_e32 v41, v0
	v_mov_b32_e32 v42, v0
	v_mov_b32_e32 v43, v0
	v_mov_b32_e32 v44, v0
	v_mov_b32_e32 v45, v0
	v_mov_b32_e32 v46, v0
	v_mov_b32_e32 v47, v0
	v_mov_b32_e32 v56, v0
	v_mov_b32_e32 v57, v0
	v_mov_b32_e32 v58, v0
	v_mov_b32_e32 v59, v0
	v_mov_b32_e32 v60, v0
	v_mov_b32_e32 v61, v0
	v_mov_b32_e32 v62, v0
	v_mov_b32_e32 v63, v0
	v_mov_b32_e32 v64, v0
	v_mov_b32_e32 v65, v0
	v_mov_b32_e32 v66, v0
	v_mov_b32_e32 v67, v0
	v_mov_b32_e32 v68, v0
	v_mov_b32_e32 v69, v0
	v_mov_b32_e32 v70, v0
	v_mov_b32_e32 v71, v0
	v_mov_b32_e32 v80, v0
	v_mov_b32_e32 v81, v0
	v_mov_b32_e32 v82, v0
	v_mov_b32_e32 v83, v0
	v_mov_b32_e32 v84, v0
	v_mov_b32_e32 v85, v0
	v_mov_b32_e32 v86, v0
	v_mov_b32_e32 v87, v0
	v_mov_b32_e32 v96, v0
	v_mov_b32_e32 v97, v0
	v_mov_b32_e32 v98, v0
	v_mov_b32_e32 v99, v0
	v_mov_b32_e32 v100, v0
	v_mov_b32_e32 v101, v0
	v_mov_b32_e32 v102, v0
	v_mov_b32_e32 v103, v0
	v_mov_b32_e32 v112, v0
	v_mov_b32_e32 v113, v0
	v_mov_b32_e32 v114, v0
	v_mov_b32_e32 v115, v0
	v_mov_b32_e32 v116, v0
	v_mov_b32_e32 v117, v0
	v_mov_b32_e32 v118, v0
	v_mov_b32_e32 v119, v0
	v_mov_b32_e32 v72, v0
	v_mov_b32_e32 v73, v0
	v_mov_b32_e32 v74, v0
	v_mov_b32_e32 v75, v0
	v_mov_b32_e32 v76, v0
	v_mov_b32_e32 v77, v0
	v_mov_b32_e32 v78, v0
	v_mov_b32_e32 v79, v0
	v_mov_b32_e32 v88, v0
	v_mov_b32_e32 v89, v0
	v_mov_b32_e32 v90, v0
	v_mov_b32_e32 v91, v0
	v_mov_b32_e32 v92, v0
	v_mov_b32_e32 v93, v0
	v_mov_b32_e32 v94, v0
	v_mov_b32_e32 v95, v0
	v_mov_b32_e32 v104, v0
	v_mov_b32_e32 v105, v0
	v_mov_b32_e32 v106, v0
	v_mov_b32_e32 v107, v0
	v_mov_b32_e32 v108, v0
	v_mov_b32_e32 v109, v0
	v_mov_b32_e32 v110, v0
	v_mov_b32_e32 v111, v0
	v_mov_b32_e32 v120, v0
	v_mov_b32_e32 v121, v0
	v_mov_b32_e32 v122, v0
	v_mov_b32_e32 v123, v0
	v_mov_b32_e32 v124, v0
	v_mov_b32_e32 v125, v0
	v_mov_b32_e32 v126, v0
	v_mov_b32_e32 v127, v0

; __device__ __forceinline__ u32x4 pack8(const f32x4 a, const f32x4 b) { u32x4 w; w.x = cvt_pk_bf16(a[0], a[1]); w.y = cvt_pk_bf16(a[2], a[3]); w.z = cvt_pk_bf16(b[0], b[1]); w.w = cvt_pk_bf16(b[2], b[3]); return w; }
; __device__ __forceinline__ float row_rstd(const u64* ssq, int r) { return __builtin_amdgcn_rsqf(fx_to_pos(ssq[r]) * (1.0f / 4096.0f) + RMS_EPS); }
;     __device__ __forceinline__ void operator()(const f32x4 (&acc)[2][2][4][2], const Unit& u, int wr, int wc, int fr, int fq) const {
;     ...
;             for (int m = 0; m < 4; ++m) { const int r = row0 + ai * HALF + m * 16; const float rs = row_rstd(ssq, r); f32x4 o[2];
; #pragma unroll
;                 for (int n = 0; n < 2; ++n)
; #pragma unroll
;                     for (int j = 0; j < 4; ++j) { const float g = acc[ai][0][m][n][j] * rs, uu = acc[ai][1][m][n][j] * rs;
;                         o[n][j] = g * uu * __builtin_amdgcn_rcpf(1.0f + __expf(-g)); }
;                 *(u32x4*)(HID + (size_t)r * DFF + col0) = pack8(o[0], o[1]); }
.LBB0_966:
	v_lshl_add_u32 v146, s20, 8, v151
	v_ashrrev_i32_e32 v147, 31, v146
	v_lshl_add_u64 v[148:149], v[146:147], 3, s[2:3]
	v_mov_b32_e32 v164, v122
	v_mov_b32_e32 v165, v114
	v_mov_b32_e32 v114, v123
	s_sub_i32 s13, 32, s44
	v_mov_b32_e32 v162, v124
	v_mov_b32_e32 v163, v116
	v_mov_b32_e32 v116, v125
	v_mov_b32_e32 v124, v126
	v_mov_b32_e32 v125, v118
	v_mov_b32_e32 v118, v127
	v_mov_b32_e32 v126, v120
	v_mov_b32_e32 v127, v112
	v_mov_b32_e32 v112, v121
	v_lshl_add_u32 v160, s45, 7, v153
	v_mov_b64_e32 v[120:121], s[80:81]
	v_ashrrev_i32_e32 v161, 31, v160
	v_mad_i64_i32 v[166:167], s[22:23], v146, s43, v[120:121]
	s_andn2_b64 vcc, exec, s[0:1]
	s_mov_b64 s[0:1], -1
	v_mov_b32_e32 v136, v229
	v_lshlrev_b64 v[122:123], s44, v[136:137]
	v_min_u32_e32 v122, 1, v122
	v_or_b32_e32 v122, v123, v122
	v_cvt_f32_u32_e32 v136, v122
	v_cvt_f32_u32_e32 v147, v228
	v_or_b32_e32 v158, 16, v146
	v_lshlrev_b64 v[122:123], 1, v[160:161]
	v_ldexp_f32 v136, v136, s13
	v_fmac_f32_e32 v136, 0x2f800000, v147
	v_fmamk_f32 v136, v136, 0x39800000, v157
	v_rsq_f32_e32 v136, v136
	v_ashrrev_i32_e32 v159, 31, v158
	v_lshl_add_u64 v[160:161], v[166:167], 0, v[122:123]
	v_lshl_add_u64 v[166:167], v[158:159], 3, s[2:3]
	v_pk_mul_f32 v[114:115], v[114:115], v[136:137] op_sel_hi:[1,0]
	v_pk_mul_f32 v[162:163], v[162:163], v[136:137] op_sel_hi:[1,0]
	v_pk_mul_f32 v[116:117], v[116:117], v[136:137] op_sel_hi:[1,0]
	v_pk_mul_f32 v[124:125], v[124:125], v[136:137] op_sel_hi:[1,0]
	v_pk_mul_f32 v[118:119], v[118:119], v[136:137] op_sel_hi:[1,0]
	v_pk_mul_f32 v[126:127], v[126:127], v[136:137] op_sel_hi:[1,0]
	v_pk_mul_f32 v[112:113], v[112:113], v[136:137] op_sel_hi:[1,0]
	v_pk_mul_f32 v[164:165], v[164:165], v[136:137] op_sel_hi:[1,0]
	v_mul_f32_e32 v115, v114, v115
	v_mul_f32_e32 v114, 0xbfb8aa3b, v114
	v_mul_f32_e32 v136, v162, v163
	v_mul_f32_e32 v147, 0xbfb8aa3b, v162
	v_mul_f32_e32 v117, v116, v117
	v_mul_f32_e32 v116, 0xbfb8aa3b, v116
	v_mul_f32_e32 v125, v124, v125
	v_mul_f32_e32 v124, 0xbfb8aa3b, v124
	v_mul_f32_e32 v119, v118, v119
	v_mul_f32_e32 v118, 0xbfb8aa3b, v118
	v_mul_f32_e32 v127, v126, v127
	v_mul_f32_e32 v126, 0xbfb8aa3b, v126
	v_mul_f32_e32 v113, v112, v113
	v_mul_f32_e32 v112, 0xbfb8aa3b, v112
	v_mul_f32_e32 v162, 0xbfb8aa3b, v164
	v_exp_f32_e32 v114, v114
	v_exp_f32_e32 v147, v147
	v_exp_f32_e32 v116, v116
	v_exp_f32_e32 v124, v124
	v_exp_f32_e32 v118, v118
	v_exp_f32_e32 v126, v126
	v_exp_f32_e32 v112, v112
	v_exp_f32_e32 v162, v162
	v_add_f32_e32 v114, 1.0, v114
	v_add_f32_e32 v147, 1.0, v147
	v_add_f32_e32 v116, 1.0, v116
	v_add_f32_e32 v124, 1.0, v124
	v_add_f32_e32 v118, 1.0, v118
	v_add_f32_e32 v126, 1.0, v126
	v_add_f32_e32 v112, 1.0, v112
	v_add_f32_e32 v162, 1.0, v162
	v_rcp_f32_e32 v114, v114
	v_rcp_f32_e32 v147, v147
	v_rcp_f32_e32 v116, v116
	v_rcp_f32_e32 v124, v124
	v_rcp_f32_e32 v118, v118
	v_rcp_f32_e32 v126, v126
	v_rcp_f32_e32 v112, v112
	v_rcp_f32_e32 v162, v162
	v_mul_f32_e32 v159, v164, v165
	v_mul_f32_e32 v115, v115, v114
	v_mul_f32_e32 v136, v136, v147
	v_mul_f32_e32 v116, v117, v116
	v_mul_f32_e32 v117, v125, v124
	v_mul_f32_e32 v118, v119, v118
	v_mul_f32_e32 v119, v127, v126
	v_mul_f32_e32 v124, v113, v112
	v_mul_f32_e32 v125, v159, v162
	v_cvt_pk_bf16_f32 v112, v136, v116
	v_cvt_pk_bf16_f32 v113, v117, v118
	v_cvt_pk_bf16_f32 v114, v119, v124
	v_cvt_pk_bf16_f32 v115, v125, v115
	global_store_dwordx4 v[160:161], v[112:115], off
	s_nop 1
	v_mov_b32_e32 v136, v231
	v_lshlrev_b64 v[116:117], s44, v[136:137]
	v_mov_b32_e32 v115, v100
	v_mov_b32_e32 v100, v109
	v_mov_b32_e32 v109, v102
	v_mov_b32_e32 v102, v111
	v_mov_b32_e32 v111, v96
	v_mov_b32_e32 v96, v105
	v_mov_b32_e32 v105, v98
	v_mov_b32_e32 v98, v107
	v_min_u32_e32 v107, 1, v116
	v_or_b32_e32 v107, v117, v107
	v_cvt_f32_u32_e32 v107, v107
	v_cvt_f32_u32_e32 v116, v230
	v_mov_b32_e32 v114, v108
	v_mov_b32_e32 v108, v110
	v_ldexp_f32 v107, v107, s13
	v_fmac_f32_e32 v107, 0x2f800000, v116
	v_fmamk_f32 v107, v107, 0x39800000, v157
	v_rsq_f32_e32 v116, v107
	v_mov_b32_e32 v110, v104
	v_mov_b32_e32 v104, v106
	v_or_b32_e32 v106, 32, v146
	v_pk_mul_f32 v[98:99], v[98:99], v[116:117] op_sel_hi:[1,0]
	v_ashrrev_i32_e32 v107, 31, v106
	v_pk_mul_f32 v[114:115], v[114:115], v[116:117] op_sel_hi:[1,0]
	v_pk_mul_f32 v[100:101], v[100:101], v[116:117] op_sel_hi:[1,0]
	v_pk_mul_f32 v[108:109], v[108:109], v[116:117] op_sel_hi:[1,0]
	v_pk_mul_f32 v[102:103], v[102:103], v[116:117] op_sel_hi:[1,0]
	v_pk_mul_f32 v[110:111], v[110:111], v[116:117] op_sel_hi:[1,0]
	v_pk_mul_f32 v[96:97], v[96:97], v[116:117] op_sel_hi:[1,0]
	v_pk_mul_f32 v[104:105], v[104:105], v[116:117] op_sel_hi:[1,0]
	v_mul_f32_e32 v99, v98, v99
	v_mul_f32_e32 v98, 0xbfb8aa3b, v98
	v_lshl_add_u64 v[118:119], v[106:107], 3, s[2:3]
	v_mul_f32_e32 v107, v114, v115
	v_mul_f32_e32 v114, 0xbfb8aa3b, v114
	v_mul_f32_e32 v101, v100, v101
	v_mul_f32_e32 v100, 0xbfb8aa3b, v100
	v_mul_f32_e32 v109, v108, v109
	v_mul_f32_e32 v108, 0xbfb8aa3b, v108
	v_mul_f32_e32 v103, v102, v103
	v_mul_f32_e32 v102, 0xbfb8aa3b, v102
	v_mul_f32_e32 v111, v110, v111
	v_mul_f32_e32 v110, 0xbfb8aa3b, v110
	v_mul_f32_e32 v97, v96, v97
	v_mul_f32_e32 v96, 0xbfb8aa3b, v96
	v_mul_f32_e32 v105, v104, v105
	v_mul_f32_e32 v104, 0xbfb8aa3b, v104
	v_exp_f32_e32 v98, v98
	v_exp_f32_e32 v114, v114
	v_exp_f32_e32 v100, v100
	v_exp_f32_e32 v108, v108
	v_exp_f32_e32 v102, v102
	v_exp_f32_e32 v110, v110
	v_exp_f32_e32 v96, v96
	v_exp_f32_e32 v104, v104
	v_add_f32_e32 v98, 1.0, v98
	v_add_f32_e32 v114, 1.0, v114
	v_add_f32_e32 v100, 1.0, v100
	v_add_f32_e32 v108, 1.0, v108
	v_add_f32_e32 v102, 1.0, v102
	v_add_f32_e32 v110, 1.0, v110
	v_add_f32_e32 v96, 1.0, v96
; __device__ __forceinline__ u32x4 pack8(const f32x4 a, const f32x4 b) { u32x4 w; w.x = cvt_pk_bf16(a[0], a[1]); w.y = cvt_pk_bf16(a[2], a[3]); w.z = cvt_pk_bf16(b[0], b[1]); w.w = cvt_pk_bf16(b[2], b[3]); return w; }
; __device__ __forceinline__ float row_rstd(const u64* ssq, int r) { return __builtin_amdgcn_rsqf(fx_to_pos(ssq[r]) * (1.0f / 4096.0f) + RMS_EPS); }
;     __device__ __forceinline__ void operator()(const f32x4 (&acc)[2][2][4][2], const Unit& u, int wr, int wc, int fr, int fq) const {
;     ...
;             for (int m = 0; m < 4; ++m) { const int r = row0 + ai * HALF + m * 16; const float rs = row_rstd(ssq, r); f32x4 o[2];
; #pragma unroll
;                 for (int n = 0; n < 2; ++n)
; #pragma unroll
;                     for (int j = 0; j < 4; ++j) { const float g = acc[ai][0][m][n][j] * rs, uu = acc[ai][1][m][n][j] * rs;
;                         o[n][j] = g * uu * __builtin_amdgcn_rcpf(1.0f + __expf(-g)); }
;                 *(u32x4*)(HID + (size_t)r * DFF + col0) = pack8(o[0], o[1]); }
	v_add_f32_e32 v104, 1.0, v104
	v_rcp_f32_e32 v98, v98
	v_rcp_f32_e32 v114, v114
	v_rcp_f32_e32 v100, v100
	v_rcp_f32_e32 v108, v108
	v_rcp_f32_e32 v102, v102
	v_rcp_f32_e32 v110, v110
	v_rcp_f32_e32 v96, v96
	v_rcp_f32_e32 v104, v104
	v_mad_i64_i32 v[112:113], s[22:23], v158, s43, v[120:121]
	v_lshl_add_u64 v[112:113], v[112:113], 0, v[122:123]
	v_mul_f32_e32 v99, v99, v98
	v_mul_f32_e32 v107, v107, v114
	v_mul_f32_e32 v100, v101, v100
	v_mul_f32_e32 v101, v109, v108
	v_mul_f32_e32 v102, v103, v102
	v_mul_f32_e32 v103, v111, v110
	v_mul_f32_e32 v108, v97, v96
	v_mul_f32_e32 v104, v105, v104
	v_cvt_pk_bf16_f32 v96, v107, v100
	v_cvt_pk_bf16_f32 v97, v101, v102
	v_cvt_pk_bf16_f32 v98, v103, v108
	v_cvt_pk_bf16_f32 v99, v104, v99
	global_store_dwordx4 v[112:113], v[96:99], off
	s_nop 1
	v_mov_b32_e32 v136, v233
	v_lshlrev_b64 v[100:101], s44, v[136:137]
	v_mov_b32_e32 v99, v84
	v_mov_b32_e32 v84, v93
	v_mov_b32_e32 v93, v86
	v_mov_b32_e32 v86, v95
	v_mov_b32_e32 v95, v80
	v_mov_b32_e32 v80, v89
	v_mov_b32_e32 v89, v82
	v_mov_b32_e32 v82, v91
	v_min_u32_e32 v91, 1, v100
	v_or_b32_e32 v91, v101, v91
	v_cvt_f32_u32_e32 v91, v91
	v_cvt_f32_u32_e32 v100, v232
	v_mov_b32_e32 v98, v92
	v_mov_b32_e32 v92, v94
	v_ldexp_f32 v91, v91, s13
	v_fmac_f32_e32 v91, 0x2f800000, v100
	v_fmamk_f32 v91, v91, 0x39800000, v157
	v_rsq_f32_e32 v100, v91
	v_mov_b32_e32 v94, v88
	v_mov_b32_e32 v88, v90
	v_or_b32_e32 v90, 48, v146
	v_pk_mul_f32 v[82:83], v[82:83], v[100:101] op_sel_hi:[1,0]
	v_ashrrev_i32_e32 v91, 31, v90
	v_pk_mul_f32 v[98:99], v[98:99], v[100:101] op_sel_hi:[1,0]
	v_pk_mul_f32 v[84:85], v[84:85], v[100:101] op_sel_hi:[1,0]
	v_pk_mul_f32 v[92:93], v[92:93], v[100:101] op_sel_hi:[1,0]
	v_pk_mul_f32 v[86:87], v[86:87], v[100:101] op_sel_hi:[1,0]
	v_pk_mul_f32 v[94:95], v[94:95], v[100:101] op_sel_hi:[1,0]
	v_pk_mul_f32 v[80:81], v[80:81], v[100:101] op_sel_hi:[1,0]
	v_pk_mul_f32 v[88:89], v[88:89], v[100:101] op_sel_hi:[1,0]
	v_mul_f32_e32 v83, v82, v83
	v_mul_f32_e32 v82, 0xbfb8aa3b, v82
	v_lshl_add_u64 v[102:103], v[90:91], 3, s[2:3]
	v_mul_f32_e32 v91, v98, v99
	v_mul_f32_e32 v98, 0xbfb8aa3b, v98
	v_mul_f32_e32 v85, v84, v85
	v_mul_f32_e32 v84, 0xbfb8aa3b, v84
	v_mul_f32_e32 v93, v92, v93
	v_mul_f32_e32 v92, 0xbfb8aa3b, v92
	v_mul_f32_e32 v87, v86, v87
	v_mul_f32_e32 v86, 0xbfb8aa3b, v86
	v_mul_f32_e32 v95, v94, v95
	v_mul_f32_e32 v94, 0xbfb8aa3b, v94
	v_mul_f32_e32 v81, v80, v81
	v_mul_f32_e32 v80, 0xbfb8aa3b, v80
	v_mul_f32_e32 v89, v88, v89
	v_mul_f32_e32 v88, 0xbfb8aa3b, v88
	v_exp_f32_e32 v82, v82
	v_exp_f32_e32 v98, v98
	v_exp_f32_e32 v84, v84
	v_exp_f32_e32 v92, v92
	v_exp_f32_e32 v86, v86
	v_exp_f32_e32 v94, v94
	v_exp_f32_e32 v80, v80
	v_exp_f32_e32 v88, v88
	v_add_f32_e32 v82, 1.0, v82
	v_add_f32_e32 v98, 1.0, v98
	v_add_f32_e32 v84, 1.0, v84
	v_add_f32_e32 v92, 1.0, v92
	v_add_f32_e32 v86, 1.0, v86
	v_add_f32_e32 v94, 1.0, v94
	v_add_f32_e32 v80, 1.0, v80
	v_add_f32_e32 v88, 1.0, v88
	v_rcp_f32_e32 v82, v82
	v_rcp_f32_e32 v98, v98
	v_rcp_f32_e32 v84, v84
	v_rcp_f32_e32 v92, v92
	v_rcp_f32_e32 v86, v86
	v_rcp_f32_e32 v94, v94
	v_rcp_f32_e32 v80, v80
	v_rcp_f32_e32 v88, v88
	v_mad_i64_i32 v[96:97], s[22:23], v106, s43, v[120:121]
	v_lshl_add_u64 v[96:97], v[96:97], 0, v[122:123]
	v_mul_f32_e32 v83, v83, v82
	v_mul_f32_e32 v91, v91, v98
	v_mul_f32_e32 v84, v85, v84
	v_mul_f32_e32 v85, v93, v92
	v_mul_f32_e32 v86, v87, v86
	v_mul_f32_e32 v87, v95, v94
	v_mul_f32_e32 v92, v81, v80
	v_mul_f32_e32 v88, v89, v88
	v_cvt_pk_bf16_f32 v80, v91, v84
	v_cvt_pk_bf16_f32 v81, v85, v86
	v_cvt_pk_bf16_f32 v82, v87, v92
	v_cvt_pk_bf16_f32 v83, v88, v83
	global_store_dwordx4 v[96:97], v[80:83], off
	s_nop 1
	v_mov_b32_e32 v136, v235
	v_lshlrev_b64 v[84:85], s44, v[136:137]
	v_mov_b32_e32 v83, v68
	v_mov_b32_e32 v68, v77
	v_mov_b32_e32 v77, v70
	v_mov_b32_e32 v70, v79
	v_mov_b32_e32 v79, v64
	v_mov_b32_e32 v64, v73
	v_min_u32_e32 v73, 1, v84
	v_or_b32_e32 v73, v85, v73
	v_mov_b32_e32 v82, v76
	v_mov_b32_e32 v76, v78
	v_mov_b32_e32 v78, v72
	v_mov_b32_e32 v72, v74
	v_cvt_f32_u32_e32 v74, v73
	v_cvt_f32_u32_e32 v80, v234
	v_mov_b32_e32 v73, v66
	v_mov_b32_e32 v66, v75
	v_ldexp_f32 v74, v74, s13
	v_fmac_f32_e32 v74, 0x2f800000, v80
	v_fmamk_f32 v74, v74, 0x39800000, v157
	v_rsq_f32_e32 v74, v74
	v_mad_i64_i32 v[80:81], s[22:23], v90, s43, v[120:121]
	v_lshl_add_u64 v[80:81], v[80:81], 0, v[122:123]
	v_pk_mul_f32 v[66:67], v[66:67], v[74:75] op_sel_hi:[1,0]
	v_pk_mul_f32 v[82:83], v[82:83], v[74:75] op_sel_hi:[1,0]
	v_pk_mul_f32 v[68:69], v[68:69], v[74:75] op_sel_hi:[1,0]
	v_pk_mul_f32 v[76:77], v[76:77], v[74:75] op_sel_hi:[1,0]
	v_pk_mul_f32 v[70:71], v[70:71], v[74:75] op_sel_hi:[1,0]
	v_pk_mul_f32 v[78:79], v[78:79], v[74:75] op_sel_hi:[1,0]
	v_pk_mul_f32 v[64:65], v[64:65], v[74:75] op_sel_hi:[1,0]
	v_pk_mul_f32 v[72:73], v[72:73], v[74:75] op_sel_hi:[1,0]
	v_mul_f32_e32 v67, v66, v67
	v_mul_f32_e32 v66, 0xbfb8aa3b, v66
	v_mul_f32_e32 v75, 0xbfb8aa3b, v82
	v_mul_f32_e32 v69, v68, v69
	v_mul_f32_e32 v68, 0xbfb8aa3b, v68
	v_mul_f32_e32 v77, v76, v77
	v_mul_f32_e32 v76, 0xbfb8aa3b, v76
	v_mul_f32_e32 v71, v70, v71
	v_mul_f32_e32 v70, 0xbfb8aa3b, v70
	v_mul_f32_e32 v79, v78, v79
	v_mul_f32_e32 v78, 0xbfb8aa3b, v78
	v_mul_f32_e32 v65, v64, v65
	v_mul_f32_e32 v64, 0xbfb8aa3b, v64
	v_mul_f32_e32 v73, v72, v73
	v_mul_f32_e32 v72, 0xbfb8aa3b, v72
	v_exp_f32_e32 v66, v66
	v_exp_f32_e32 v75, v75
	v_exp_f32_e32 v68, v68
	v_exp_f32_e32 v76, v76
	v_exp_f32_e32 v70, v70
	v_exp_f32_e32 v78, v78
	v_exp_f32_e32 v64, v64
	v_exp_f32_e32 v72, v72
	v_add_f32_e32 v66, 1.0, v66
	v_add_f32_e32 v75, 1.0, v75
	v_add_f32_e32 v68, 1.0, v68
	v_add_f32_e32 v76, 1.0, v76
; __device__ __forceinline__ u32x4 pack8(const f32x4 a, const f32x4 b) { u32x4 w; w.x = cvt_pk_bf16(a[0], a[1]); w.y = cvt_pk_bf16(a[2], a[3]); w.z = cvt_pk_bf16(b[0], b[1]); w.w = cvt_pk_bf16(b[2], b[3]); return w; }
; __device__ __forceinline__ float row_rstd(const u64* ssq, int r) { return __builtin_amdgcn_rsqf(fx_to_pos(ssq[r]) * (1.0f / 4096.0f) + RMS_EPS); }
;     __device__ __forceinline__ void operator()(const f32x4 (&acc)[2][2][4][2], const Unit& u, int wr, int wc, int fr, int fq) const {
;     ...
;             for (int m = 0; m < 4; ++m) { const int r = row0 + ai * HALF + m * 16; const float rs = row_rstd(ssq, r); f32x4 o[2];
; #pragma unroll
;                 for (int n = 0; n < 2; ++n)
; #pragma unroll
;                     for (int j = 0; j < 4; ++j) { const float g = acc[ai][0][m][n][j] * rs, uu = acc[ai][1][m][n][j] * rs;
;                         o[n][j] = g * uu * __builtin_amdgcn_rcpf(1.0f + __expf(-g)); }
;                 *(u32x4*)(HID + (size_t)r * DFF + col0) = pack8(o[0], o[1]); }
	v_add_f32_e32 v70, 1.0, v70
	v_add_f32_e32 v78, 1.0, v78
	v_add_f32_e32 v64, 1.0, v64
	v_add_f32_e32 v72, 1.0, v72
	v_rcp_f32_e32 v66, v66
	v_rcp_f32_e32 v75, v75
	v_rcp_f32_e32 v68, v68
	v_rcp_f32_e32 v76, v76
	v_rcp_f32_e32 v70, v70
	v_rcp_f32_e32 v78, v78
	v_rcp_f32_e32 v64, v64
	v_rcp_f32_e32 v72, v72
	v_mul_f32_e32 v74, v82, v83
	v_mul_f32_e32 v67, v67, v66
	v_mul_f32_e32 v74, v74, v75
	v_mul_f32_e32 v68, v69, v68
	v_mul_f32_e32 v69, v77, v76
	v_mul_f32_e32 v70, v71, v70
	v_mul_f32_e32 v71, v79, v78
	v_mul_f32_e32 v75, v65, v64
	v_mul_f32_e32 v72, v73, v72
	v_cvt_pk_bf16_f32 v64, v74, v68
	v_cvt_pk_bf16_f32 v65, v69, v70
	v_cvt_pk_bf16_f32 v66, v71, v75
	v_cvt_pk_bf16_f32 v67, v72, v67
	global_store_dwordx4 v[80:81], v[64:67], off
	s_nop 1
	v_mov_b32_e32 v136, v237
	v_lshlrev_b64 v[68:69], s44, v[136:137]
	v_mov_b32_e32 v67, v52
	v_mov_b32_e32 v52, v61
	v_mov_b32_e32 v61, v54
	v_mov_b32_e32 v54, v63
	v_mov_b32_e32 v63, v48
	v_mov_b32_e32 v48, v57
	v_mov_b32_e32 v57, v50
	v_min_u32_e32 v50, 1, v68
	v_or_b32_e32 v50, v69, v50
	v_mov_b32_e32 v66, v60
	v_mov_b32_e32 v60, v62
	v_mov_b32_e32 v62, v56
	v_mov_b32_e32 v56, v58
	v_cvt_f32_u32_e32 v58, v50
	v_cvt_f32_u32_e32 v64, v236
	v_mov_b32_e32 v50, v59
	v_add_u32_e32 v59, 0x80, v146
	v_ldexp_f32 v58, v58, s13
	v_fmac_f32_e32 v58, 0x2f800000, v64
	v_fmamk_f32 v58, v58, 0x39800000, v157
	v_rsq_f32_e32 v58, v58
	v_mad_i64_i32 v[64:65], s[22:23], v59, s43, v[120:121]
	v_lshl_add_u64 v[64:65], v[64:65], 0, v[122:123]
	v_pk_mul_f32 v[50:51], v[50:51], v[58:59] op_sel_hi:[1,0]
	v_pk_mul_f32 v[66:67], v[66:67], v[58:59] op_sel_hi:[1,0]
	v_pk_mul_f32 v[52:53], v[52:53], v[58:59] op_sel_hi:[1,0]
	v_pk_mul_f32 v[60:61], v[60:61], v[58:59] op_sel_hi:[1,0]
	v_pk_mul_f32 v[54:55], v[54:55], v[58:59] op_sel_hi:[1,0]
	v_pk_mul_f32 v[62:63], v[62:63], v[58:59] op_sel_hi:[1,0]
	v_pk_mul_f32 v[48:49], v[48:49], v[58:59] op_sel_hi:[1,0]
	v_pk_mul_f32 v[56:57], v[56:57], v[58:59] op_sel_hi:[1,0]
	v_mul_f32_e32 v51, v50, v51
	v_mul_f32_e32 v50, 0xbfb8aa3b, v50
	v_mul_f32_e32 v59, 0xbfb8aa3b, v66
	v_mul_f32_e32 v53, v52, v53
	v_mul_f32_e32 v52, 0xbfb8aa3b, v52
	v_mul_f32_e32 v61, v60, v61
	v_mul_f32_e32 v60, 0xbfb8aa3b, v60
	v_mul_f32_e32 v55, v54, v55
	v_mul_f32_e32 v54, 0xbfb8aa3b, v54
	v_mul_f32_e32 v63, v62, v63
	v_mul_f32_e32 v62, 0xbfb8aa3b, v62
	v_mul_f32_e32 v49, v48, v49
	v_mul_f32_e32 v48, 0xbfb8aa3b, v48
	v_mul_f32_e32 v57, v56, v57
	v_mul_f32_e32 v56, 0xbfb8aa3b, v56
	v_exp_f32_e32 v50, v50
	v_exp_f32_e32 v59, v59
	v_exp_f32_e32 v52, v52
	v_exp_f32_e32 v60, v60
	v_exp_f32_e32 v54, v54
	v_exp_f32_e32 v62, v62
	v_exp_f32_e32 v48, v48
	v_exp_f32_e32 v56, v56
	v_add_f32_e32 v50, 1.0, v50
	v_add_f32_e32 v59, 1.0, v59
	v_add_f32_e32 v52, 1.0, v52
	v_add_f32_e32 v60, 1.0, v60
	v_add_f32_e32 v54, 1.0, v54
	v_add_f32_e32 v62, 1.0, v62
	v_add_f32_e32 v48, 1.0, v48
	v_add_f32_e32 v56, 1.0, v56
	v_rcp_f32_e32 v50, v50
	v_rcp_f32_e32 v59, v59
	v_rcp_f32_e32 v52, v52
	v_rcp_f32_e32 v60, v60
	v_rcp_f32_e32 v54, v54
	v_rcp_f32_e32 v62, v62
	v_rcp_f32_e32 v48, v48
	v_rcp_f32_e32 v56, v56
	v_mul_f32_e32 v58, v66, v67
	v_mul_f32_e32 v51, v51, v50
	v_mul_f32_e32 v58, v58, v59
	v_mul_f32_e32 v52, v53, v52
	v_mul_f32_e32 v53, v61, v60
	v_mul_f32_e32 v54, v55, v54
	v_mul_f32_e32 v55, v63, v62
	v_mul_f32_e32 v59, v49, v48
	v_mul_f32_e32 v56, v57, v56
	v_cvt_pk_bf16_f32 v48, v58, v52
	v_cvt_pk_bf16_f32 v49, v53, v54
	v_cvt_pk_bf16_f32 v50, v55, v59
	v_cvt_pk_bf16_f32 v51, v56, v51
	global_store_dwordx4 v[64:65], v[48:51], off
	s_nop 1
	v_mov_b32_e32 v136, v239
	v_lshlrev_b64 v[52:53], s44, v[136:137]
	v_mov_b32_e32 v51, v36
	v_mov_b32_e32 v36, v45
	v_mov_b32_e32 v45, v38
	v_mov_b32_e32 v38, v47
	v_mov_b32_e32 v47, v32
	v_mov_b32_e32 v32, v41
	v_mov_b32_e32 v41, v34
	v_min_u32_e32 v34, 1, v52
	v_or_b32_e32 v34, v53, v34
	v_mov_b32_e32 v50, v44
	v_mov_b32_e32 v44, v46
	v_mov_b32_e32 v46, v40
	v_mov_b32_e32 v40, v42
	v_cvt_f32_u32_e32 v42, v34
	v_cvt_f32_u32_e32 v48, v238
	v_mov_b32_e32 v34, v43
	v_add_u32_e32 v43, 0x90, v146
	v_ldexp_f32 v42, v42, s13
	v_fmac_f32_e32 v42, 0x2f800000, v48
	v_fmamk_f32 v42, v42, 0x39800000, v157
	v_rsq_f32_e32 v42, v42
	v_mad_i64_i32 v[48:49], s[22:23], v43, s43, v[120:121]
	v_lshl_add_u64 v[48:49], v[48:49], 0, v[122:123]
	v_pk_mul_f32 v[34:35], v[34:35], v[42:43] op_sel_hi:[1,0]
	v_pk_mul_f32 v[50:51], v[50:51], v[42:43] op_sel_hi:[1,0]
	v_pk_mul_f32 v[36:37], v[36:37], v[42:43] op_sel_hi:[1,0]
	v_pk_mul_f32 v[44:45], v[44:45], v[42:43] op_sel_hi:[1,0]
	v_pk_mul_f32 v[38:39], v[38:39], v[42:43] op_sel_hi:[1,0]
	v_pk_mul_f32 v[46:47], v[46:47], v[42:43] op_sel_hi:[1,0]
	v_pk_mul_f32 v[32:33], v[32:33], v[42:43] op_sel_hi:[1,0]
	v_pk_mul_f32 v[40:41], v[40:41], v[42:43] op_sel_hi:[1,0]
	v_mul_f32_e32 v35, v34, v35
	v_mul_f32_e32 v34, 0xbfb8aa3b, v34
	v_mul_f32_e32 v43, 0xbfb8aa3b, v50
	v_mul_f32_e32 v37, v36, v37
	v_mul_f32_e32 v36, 0xbfb8aa3b, v36
	v_mul_f32_e32 v45, v44, v45
	v_mul_f32_e32 v44, 0xbfb8aa3b, v44
	v_mul_f32_e32 v39, v38, v39
	v_mul_f32_e32 v38, 0xbfb8aa3b, v38
	v_mul_f32_e32 v47, v46, v47
	v_mul_f32_e32 v46, 0xbfb8aa3b, v46
	v_mul_f32_e32 v33, v32, v33
	v_mul_f32_e32 v32, 0xbfb8aa3b, v32
	v_mul_f32_e32 v41, v40, v41
	v_mul_f32_e32 v40, 0xbfb8aa3b, v40
	v_exp_f32_e32 v34, v34
	v_exp_f32_e32 v43, v43
	v_exp_f32_e32 v36, v36
	v_exp_f32_e32 v44, v44
	v_exp_f32_e32 v38, v38
	v_exp_f32_e32 v46, v46
	v_exp_f32_e32 v32, v32
	v_exp_f32_e32 v40, v40
	v_add_f32_e32 v34, 1.0, v34
	v_add_f32_e32 v43, 1.0, v43
	v_add_f32_e32 v36, 1.0, v36
	v_add_f32_e32 v44, 1.0, v44
	v_add_f32_e32 v38, 1.0, v38
	v_add_f32_e32 v46, 1.0, v46
	v_add_f32_e32 v32, 1.0, v32
	v_add_f32_e32 v40, 1.0, v40
; __device__ __forceinline__ u32x4 pack8(const f32x4 a, const f32x4 b) { u32x4 w; w.x = cvt_pk_bf16(a[0], a[1]); w.y = cvt_pk_bf16(a[2], a[3]); w.z = cvt_pk_bf16(b[0], b[1]); w.w = cvt_pk_bf16(b[2], b[3]); return w; }
; __device__ __forceinline__ float row_rstd(const u64* ssq, int r) { return __builtin_amdgcn_rsqf(fx_to_pos(ssq[r]) * (1.0f / 4096.0f) + RMS_EPS); }
; #define PG8_BAR __builtin_amdgcn_s_barrier()
;     __device__ __forceinline__ void operator()(const f32x4 (&acc)[2][2][4][2], const Unit& u, int wr, int wc, int fr, int fq) const {
;     ...
;             for (int m = 0; m < 4; ++m) { const int r = row0 + ai * HALF + m * 16; const float rs = row_rstd(ssq, r); f32x4 o[2];
; #pragma unroll
;                 for (int n = 0; n < 2; ++n)
; #pragma unroll
;                     for (int j = 0; j < 4; ++j) { const float g = acc[ai][0][m][n][j] * rs, uu = acc[ai][1][m][n][j] * rs;
;                         o[n][j] = g * uu * __builtin_amdgcn_rcpf(1.0f + __expf(-g)); }
;                 *(u32x4*)(HID + (size_t)r * DFF + col0) = pack8(o[0], o[1]); }
; template <class Epi, class Sched, bool ALIGN_EPI = false, bool SP2 = false>
; __device__ __forceinline__ void gemm_phase(PG8_LAS unsigned char* lds, const Gemm g, const Sched& S, const Epi& E, const int wid) {
;     ...
;         if constexpr (ALIGN_EPI) { if (wr == 0) PG8_BAR; }
;         if constexpr (!Epi::AFTER_DRAIN) { E(acc, cur, wr, wc, fr, fq); S.done(cur); }
;         if (!has_next) break;
; #pragma unroll
;         for (int a = 0; a < 2; ++a)
; #pragma unroll
;             for (int b = 0; b < 2; ++b)
; #pragma unroll
;                 for (int m = 0; m < 4; ++m)
; #pragma unroll
;                     for (int n = 0; n < 2; ++n) acc[a][b][m][n] = (f32x4){0.f, 0.f, 0.f, 0.f};
;         cur = nxt; cA = nA; cB = nB; ++ui; nt = cur.kn;
;         if constexpr (ALIGN_EPI) { if (wr == 1) PG8_BAR; }
	v_rcp_f32_e32 v34, v34
	v_rcp_f32_e32 v43, v43
	v_rcp_f32_e32 v36, v36
	v_rcp_f32_e32 v44, v44
	v_rcp_f32_e32 v38, v38
	v_rcp_f32_e32 v46, v46
	v_rcp_f32_e32 v32, v32
	v_rcp_f32_e32 v40, v40
	v_mul_f32_e32 v42, v50, v51
	v_mul_f32_e32 v35, v35, v34
	v_mul_f32_e32 v42, v42, v43
	v_mul_f32_e32 v36, v37, v36
	v_mul_f32_e32 v37, v45, v44
	v_mul_f32_e32 v38, v39, v38
	v_mul_f32_e32 v39, v47, v46
	v_mul_f32_e32 v43, v33, v32
	v_mul_f32_e32 v40, v41, v40
	v_cvt_pk_bf16_f32 v32, v42, v36
	v_cvt_pk_bf16_f32 v33, v37, v38
	v_cvt_pk_bf16_f32 v34, v39, v43
	v_cvt_pk_bf16_f32 v35, v40, v35
	global_store_dwordx4 v[48:49], v[32:35], off
	s_nop 1
	v_mov_b32_e32 v136, v241
	v_lshlrev_b64 v[36:37], s44, v[136:137]
	v_mov_b32_e32 v35, v20
	v_mov_b32_e32 v20, v29
	v_mov_b32_e32 v29, v22
	v_mov_b32_e32 v22, v31
	v_mov_b32_e32 v31, v16
	v_mov_b32_e32 v16, v25
	v_mov_b32_e32 v25, v18
	v_min_u32_e32 v18, 1, v36
	v_or_b32_e32 v18, v37, v18
	v_mov_b32_e32 v34, v28
	v_mov_b32_e32 v28, v30
	v_mov_b32_e32 v30, v24
	v_mov_b32_e32 v24, v26
	v_cvt_f32_u32_e32 v26, v18
	v_cvt_f32_u32_e32 v32, v240
	v_mov_b32_e32 v18, v27
	v_add_u32_e32 v27, 0xa0, v146
	v_ldexp_f32 v26, v26, s13
	v_fmac_f32_e32 v26, 0x2f800000, v32
	v_fmamk_f32 v26, v26, 0x39800000, v157
	v_rsq_f32_e32 v26, v26
	v_mad_i64_i32 v[32:33], s[22:23], v27, s43, v[120:121]
	v_lshl_add_u64 v[32:33], v[32:33], 0, v[122:123]
	v_pk_mul_f32 v[18:19], v[18:19], v[26:27] op_sel_hi:[1,0]
	v_pk_mul_f32 v[34:35], v[34:35], v[26:27] op_sel_hi:[1,0]
	v_pk_mul_f32 v[20:21], v[20:21], v[26:27] op_sel_hi:[1,0]
	v_pk_mul_f32 v[28:29], v[28:29], v[26:27] op_sel_hi:[1,0]
	v_pk_mul_f32 v[22:23], v[22:23], v[26:27] op_sel_hi:[1,0]
	v_pk_mul_f32 v[30:31], v[30:31], v[26:27] op_sel_hi:[1,0]
	v_pk_mul_f32 v[16:17], v[16:17], v[26:27] op_sel_hi:[1,0]
	v_pk_mul_f32 v[24:25], v[24:25], v[26:27] op_sel_hi:[1,0]
	v_mul_f32_e32 v19, v18, v19
	v_mul_f32_e32 v18, 0xbfb8aa3b, v18
	v_mul_f32_e32 v27, 0xbfb8aa3b, v34
	v_mul_f32_e32 v21, v20, v21
	v_mul_f32_e32 v20, 0xbfb8aa3b, v20
	v_mul_f32_e32 v29, v28, v29
	v_mul_f32_e32 v28, 0xbfb8aa3b, v28
	v_mul_f32_e32 v23, v22, v23
	v_mul_f32_e32 v22, 0xbfb8aa3b, v22
	v_mul_f32_e32 v31, v30, v31
	v_mul_f32_e32 v30, 0xbfb8aa3b, v30
	v_mul_f32_e32 v17, v16, v17
	v_mul_f32_e32 v16, 0xbfb8aa3b, v16
	v_mul_f32_e32 v25, v24, v25
	v_mul_f32_e32 v24, 0xbfb8aa3b, v24
	v_exp_f32_e32 v18, v18
	v_exp_f32_e32 v27, v27
	v_exp_f32_e32 v20, v20
	v_exp_f32_e32 v28, v28
	v_exp_f32_e32 v22, v22
	v_exp_f32_e32 v30, v30
	v_exp_f32_e32 v16, v16
	v_exp_f32_e32 v24, v24
	v_add_f32_e32 v18, 1.0, v18
	v_add_f32_e32 v27, 1.0, v27
	v_add_f32_e32 v20, 1.0, v20
	v_add_f32_e32 v28, 1.0, v28
	v_add_f32_e32 v22, 1.0, v22
	v_add_f32_e32 v30, 1.0, v30
	v_add_f32_e32 v16, 1.0, v16
	v_add_f32_e32 v24, 1.0, v24
	v_rcp_f32_e32 v18, v18
	v_rcp_f32_e32 v27, v27
	v_rcp_f32_e32 v20, v20
	v_rcp_f32_e32 v28, v28
	v_rcp_f32_e32 v22, v22
	v_rcp_f32_e32 v30, v30
	v_rcp_f32_e32 v16, v16
	v_rcp_f32_e32 v24, v24
	v_mul_f32_e32 v26, v34, v35
	v_mul_f32_e32 v19, v19, v18
	v_mul_f32_e32 v26, v26, v27
	v_mul_f32_e32 v20, v21, v20
	v_mul_f32_e32 v21, v29, v28
	v_mul_f32_e32 v22, v23, v22
	v_mul_f32_e32 v23, v31, v30
	v_mul_f32_e32 v27, v17, v16
	v_mul_f32_e32 v24, v25, v24
	v_cvt_pk_bf16_f32 v16, v26, v20
	v_cvt_pk_bf16_f32 v17, v21, v22
	v_cvt_pk_bf16_f32 v18, v23, v27
	v_cvt_pk_bf16_f32 v19, v24, v19
	global_store_dwordx4 v[32:33], v[16:19], off
	s_nop 1
	v_mov_b32_e32 v136, v243
	v_mov_b32_e32 v18, v12
	v_mov_b32_e32 v19, v4
	v_mov_b32_e32 v4, v13
	v_mov_b32_e32 v12, v14
	v_mov_b32_e32 v13, v6
	v_mov_b32_e32 v6, v15
	v_mov_b32_e32 v14, v8
	v_mov_b32_e32 v15, v0
	v_mov_b32_e32 v0, v9
	v_mov_b32_e32 v8, v10
	v_mov_b32_e32 v9, v2
	v_mov_b32_e32 v2, v11
	v_lshlrev_b64 v[10:11], s44, v[136:137]
	v_min_u32_e32 v10, 1, v10
	v_or_b32_e32 v10, v11, v10
	v_cvt_f32_u32_e32 v10, v10
	v_cvt_f32_u32_e32 v11, v242
	v_add_u32_e32 v16, 0xb0, v146
	v_mad_i64_i32 v[16:17], s[22:23], v16, s43, v[120:121]
	v_ldexp_f32 v10, v10, s13
	v_fmac_f32_e32 v10, 0x2f800000, v11
	v_fmamk_f32 v10, v10, 0x39800000, v157
	v_rsq_f32_e32 v10, v10
	v_lshl_add_u64 v[16:17], v[16:17], 0, v[122:123]
	v_pk_mul_f32 v[2:3], v[2:3], v[10:11] op_sel_hi:[1,0]
	v_pk_mul_f32 v[18:19], v[18:19], v[10:11] op_sel_hi:[1,0]
	v_pk_mul_f32 v[4:5], v[4:5], v[10:11] op_sel_hi:[1,0]
	v_pk_mul_f32 v[12:13], v[12:13], v[10:11] op_sel_hi:[1,0]
	v_pk_mul_f32 v[6:7], v[6:7], v[10:11] op_sel_hi:[1,0]
	v_pk_mul_f32 v[14:15], v[14:15], v[10:11] op_sel_hi:[1,0]
	v_pk_mul_f32 v[0:1], v[0:1], v[10:11] op_sel_hi:[1,0]
	v_pk_mul_f32 v[8:9], v[8:9], v[10:11] op_sel_hi:[1,0]
	v_mul_f32_e32 v3, v2, v3
	v_mul_f32_e32 v2, 0xbfb8aa3b, v2
	v_mul_f32_e32 v11, 0xbfb8aa3b, v18
	v_mul_f32_e32 v5, v4, v5
	v_mul_f32_e32 v4, 0xbfb8aa3b, v4
	v_mul_f32_e32 v13, v12, v13
	v_mul_f32_e32 v12, 0xbfb8aa3b, v12
	v_mul_f32_e32 v7, v6, v7
	v_mul_f32_e32 v6, 0xbfb8aa3b, v6
	v_mul_f32_e32 v15, v14, v15
	v_mul_f32_e32 v14, 0xbfb8aa3b, v14
	v_mul_f32_e32 v1, v0, v1
	v_mul_f32_e32 v0, 0xbfb8aa3b, v0
	v_mul_f32_e32 v9, v8, v9
	v_mul_f32_e32 v8, 0xbfb8aa3b, v8
	v_exp_f32_e32 v2, v2
	v_exp_f32_e32 v11, v11
	v_exp_f32_e32 v4, v4
	v_exp_f32_e32 v12, v12
	v_exp_f32_e32 v6, v6
	v_exp_f32_e32 v14, v14
	v_exp_f32_e32 v0, v0
	v_exp_f32_e32 v8, v8
	v_add_f32_e32 v2, 1.0, v2
	v_add_f32_e32 v11, 1.0, v11
	v_add_f32_e32 v4, 1.0, v4
	v_add_f32_e32 v12, 1.0, v12
	v_add_f32_e32 v6, 1.0, v6
	v_add_f32_e32 v14, 1.0, v14
	v_add_f32_e32 v0, 1.0, v0
	v_add_f32_e32 v8, 1.0, v8
	v_rcp_f32_e32 v2, v2
	v_rcp_f32_e32 v11, v11
	v_rcp_f32_e32 v4, v4
	v_rcp_f32_e32 v12, v12
	v_rcp_f32_e32 v6, v6
	v_rcp_f32_e32 v14, v14
	v_rcp_f32_e32 v0, v0
	v_rcp_f32_e32 v8, v8
	v_mul_f32_e32 v10, v18, v19
	v_mul_f32_e32 v3, v3, v2
	v_mul_f32_e32 v10, v10, v11
	v_mul_f32_e32 v4, v5, v4
	v_mul_f32_e32 v5, v13, v12
	v_mul_f32_e32 v6, v7, v6
	v_mul_f32_e32 v7, v15, v14
	v_mul_f32_e32 v11, v1, v0
	v_mul_f32_e32 v8, v9, v8
	v_cvt_pk_bf16_f32 v0, v10, v4
	v_cvt_pk_bf16_f32 v1, v5, v6
	v_cvt_pk_bf16_f32 v2, v7, v11
	v_cvt_pk_bf16_f32 v3, v8, v3
	global_store_dwordx4 v[16:17], v[0:3], off
	s_cbranch_vccnz .LBB0_955
	s_andn2_b64 vcc, exec, s[6:7]
	s_cbranch_vccnz .LBB0_954
	s_barrier
	s_branch .LBB0_954

; __device__ __forceinline__ float row_rstd(const u64* ssq, int r) { return __builtin_amdgcn_rsqf(fx_to_pos(ssq[r]) * (1.0f / 4096.0f) + RMS_EPS); }
;     __device__ __forceinline__ void operator()(const f32x4 (&acc)[2][2][4][2], const Unit& u, int wr, int wc, int fr, int fq) const {
;     ...
;                 for (int m = 0; m < 4; ++m) { const int r = row0 + ai * HALF + m * 16; const float rs = row_rstd(ssq, r) * sc;
; template <class Epi, class Sched, bool ALIGN_EPI = false, bool SP2 = false>
; __device__ __forceinline__ void gemm_phase(PG8_LAS unsigned char* lds, const Gemm g, const Sched& S, const Epi& E, const int wid) {
;     ...
;         for (int a = 0; a < 2; ++a)
; #pragma unroll
;             for (int b = 0; b < 2; ++b)
; #pragma unroll
;                 for (int m = 0; m < 4; ++m)
; #pragma unroll
;                     for (int n = 0; n < 2; ++n) acc[a][b][m][n] = (f32x4){0.f, 0.f, 0.f, 0.f};
;         cur = nxt; cA = nA; cB = nB; ++ui; nt = cur.kn;
.LBB0_1249:
	v_lshl_add_u32 v254, s18, 8, v164
	v_ashrrev_i32_e32 v255, 31, v254
	v_lshl_add_u64 v[254:255], v[254:255], 3, s[4:5]
	global_load_dwordx2 v[238:239], v[254:255], off
	global_load_dwordx2 v[240:241], v[254:255], off offset:128
	global_load_dwordx2 v[242:243], v[254:255], off offset:256
	global_load_dwordx2 v[244:245], v[254:255], off offset:384
	global_load_dwordx2 v[248:249], v[254:255], off offset:1024
	global_load_dwordx2 v[250:251], v[254:255], off offset:1152
	global_load_dwordx2 v[252:253], v[254:255], off offset:1280
	global_load_dwordx2 v[254:255], v[254:255], off offset:1408
	s_ashr_i32 s13, s12, 31
	s_lshl_b64 s[14:15], s[12:13], 21
	s_add_u32 s14, s78, s14
	s_addc_u32 s15, s79, s15
	s_and_b64 s[16:17], s[0:1], exec
	s_cselect_b32 s13, s15, s21
	s_cselect_b32 s19, s14, s20
	s_ashr_i32 s11, s10, 31
	s_lshl_b64 s[16:17], s[10:11], 21
	s_add_u32 s16, s26, s16
	s_addc_u32 s17, s27, s17
	s_and_b64 s[24:25], s[0:1], exec
	s_cselect_b32 s11, s17, s23
	s_cselect_b32 s57, s16, s22
	s_add_u32 s20, s20, 0x100080
	s_addc_u32 s21, s21, 0
	s_add_u32 s58, s22, 0x100
	v_mov_b32_e32 v0, 0
	s_addc_u32 s59, s23, 0
	s_mov_b32 s60, -2
	v_mov_b32_e32 v1, v0
	v_mov_b32_e32 v2, v0
	v_mov_b32_e32 v3, v0
	v_mov_b32_e32 v8, v0
	v_mov_b32_e32 v9, v0
	v_mov_b32_e32 v10, v0
	v_mov_b32_e32 v11, v0
	v_mov_b32_e32 v16, v0
	v_mov_b32_e32 v17, v0
	v_mov_b32_e32 v18, v0
	v_mov_b32_e32 v19, v0
	v_mov_b32_e32 v24, v0
	v_mov_b32_e32 v25, v0
	v_mov_b32_e32 v26, v0
	v_mov_b32_e32 v27, v0
	v_mov_b32_e32 v32, v0
	v_mov_b32_e32 v33, v0
	v_mov_b32_e32 v34, v0
	v_mov_b32_e32 v35, v0
	v_mov_b32_e32 v40, v0
	v_mov_b32_e32 v41, v0
	v_mov_b32_e32 v42, v0
	v_mov_b32_e32 v43, v0
	v_mov_b32_e32 v48, v0
	v_mov_b32_e32 v49, v0
	v_mov_b32_e32 v50, v0
	v_mov_b32_e32 v51, v0
	v_mov_b32_e32 v56, v0
	v_mov_b32_e32 v57, v0
	v_mov_b32_e32 v58, v0
	v_mov_b32_e32 v59, v0
	v_mov_b32_e32 v4, v0
	v_mov_b32_e32 v5, v0
	v_mov_b32_e32 v6, v0
	v_mov_b32_e32 v7, v0
	v_mov_b32_e32 v12, v0
	v_mov_b32_e32 v13, v0
	v_mov_b32_e32 v14, v0
	v_mov_b32_e32 v15, v0
	v_mov_b32_e32 v20, v0
	v_mov_b32_e32 v21, v0
	v_mov_b32_e32 v22, v0
	v_mov_b32_e32 v23, v0
	v_mov_b32_e32 v28, v0
	v_mov_b32_e32 v29, v0
	v_mov_b32_e32 v30, v0
	v_mov_b32_e32 v31, v0
	v_mov_b32_e32 v36, v0
	v_mov_b32_e32 v37, v0
	v_mov_b32_e32 v38, v0
	v_mov_b32_e32 v39, v0
	v_mov_b32_e32 v44, v0
	v_mov_b32_e32 v45, v0
	v_mov_b32_e32 v46, v0
	v_mov_b32_e32 v47, v0
	v_mov_b32_e32 v52, v0
	v_mov_b32_e32 v53, v0
	v_mov_b32_e32 v54, v0
	v_mov_b32_e32 v55, v0
	v_mov_b32_e32 v60, v0
	v_mov_b32_e32 v61, v0
	v_mov_b32_e32 v62, v0
	v_mov_b32_e32 v63, v0
	v_mov_b32_e32 v64, v0
	v_mov_b32_e32 v65, v0
	v_mov_b32_e32 v66, v0
	v_mov_b32_e32 v67, v0
	v_mov_b32_e32 v72, v0
	v_mov_b32_e32 v73, v0
	v_mov_b32_e32 v74, v0
	v_mov_b32_e32 v75, v0
	v_mov_b32_e32 v80, v0
	v_mov_b32_e32 v81, v0
	v_mov_b32_e32 v82, v0
	v_mov_b32_e32 v83, v0
	v_mov_b32_e32 v88, v0
	v_mov_b32_e32 v89, v0
	v_mov_b32_e32 v90, v0
	v_mov_b32_e32 v91, v0
	v_mov_b32_e32 v96, v0
	v_mov_b32_e32 v97, v0
	v_mov_b32_e32 v98, v0
	v_mov_b32_e32 v99, v0
	v_mov_b32_e32 v104, v0
	v_mov_b32_e32 v105, v0
	v_mov_b32_e32 v106, v0
	v_mov_b32_e32 v107, v0
	v_mov_b32_e32 v112, v0
	v_mov_b32_e32 v113, v0
	v_mov_b32_e32 v114, v0
	v_mov_b32_e32 v115, v0
	v_mov_b32_e32 v120, v0
	v_mov_b32_e32 v121, v0
	v_mov_b32_e32 v122, v0
	v_mov_b32_e32 v123, v0
	v_mov_b32_e32 v68, v0
	v_mov_b32_e32 v69, v0
	v_mov_b32_e32 v70, v0
	v_mov_b32_e32 v71, v0
	v_mov_b32_e32 v76, v0
	v_mov_b32_e32 v77, v0
	v_mov_b32_e32 v78, v0
	v_mov_b32_e32 v79, v0
	v_mov_b32_e32 v84, v0
	v_mov_b32_e32 v85, v0
	v_mov_b32_e32 v86, v0
	v_mov_b32_e32 v87, v0
	v_mov_b32_e32 v92, v0
	v_mov_b32_e32 v93, v0
	v_mov_b32_e32 v94, v0
	v_mov_b32_e32 v95, v0
	v_mov_b32_e32 v100, v0
	v_mov_b32_e32 v101, v0
	v_mov_b32_e32 v102, v0
	v_mov_b32_e32 v103, v0
	v_mov_b32_e32 v108, v0
	v_mov_b32_e32 v109, v0
	v_mov_b32_e32 v110, v0
	v_mov_b32_e32 v111, v0
	v_mov_b32_e32 v116, v0
	v_mov_b32_e32 v117, v0
	v_mov_b32_e32 v118, v0
	v_mov_b32_e32 v119, v0
	v_mov_b32_e32 v124, v0
	v_mov_b32_e32 v125, v0
	v_mov_b32_e32 v126, v0
	v_mov_b32_e32 v127, v0

; __device__ __forceinline__ u32x4 pack8(const f32x4 a, const f32x4 b) { u32x4 w; w.x = cvt_pk_bf16(a[0], a[1]); w.y = cvt_pk_bf16(a[2], a[3]); w.z = cvt_pk_bf16(b[0], b[1]); w.w = cvt_pk_bf16(b[2], b[3]); return w; }
; __device__ __forceinline__ float row_rstd(const u64* ssq, int r) { return __builtin_amdgcn_rsqf(fx_to_pos(ssq[r]) * (1.0f / 4096.0f) + RMS_EPS); }
;     __device__ __forceinline__ void operator()(const f32x4 (&acc)[2][2][4][2], const Unit& u, int wr, int wc, int fr, int fq) const {
;     ...
;             for (int ai = 0; ai < 2; ++ai)
; #pragma unroll
;                 for (int m = 0; m < 4; ++m) { const int r = row0 + ai * HALF + m * 16; const float rs = row_rstd(ssq, r); bf16_t* rowp = Z + (size_t)r * RET_IN + col0;
; #pragma unroll
;                     for (int bj = 0; bj < 2; ++bj) *(u32x4*)(rowp + bj * HALF) = pack8(acc[ai][bj][m][0] * rs, acc[ai][bj][m][1] * rs); }
.LBB0_1256:
	v_lshl_add_u64 v[128:129], v[150:151], 3, s[4:5]
	s_min_u32 s11, s55, 32
	s_sub_i32 s13, 32, s11
	v_mov_b64_e32 v[130:131], s[80:81]
	v_lshlrev_b64 v[160:161], 1, v[158:159]
	v_lshl_add_u64 v[188:189], v[156:157], 3, s[4:5]
	v_mov_b32_e32 v140, v239
	v_lshlrev_b64 v[186:187], s11, v[140:141]
	v_min_u32_e32 v140, 1, v186
	v_or_b32_e32 v140, v187, v140
	v_cvt_f32_u32_e32 v140, v140
	v_cvt_f32_u32_e32 v184, v238
	v_ldexp_f32 v140, v140, s13
	v_fmac_f32_e32 v140, 0x2f800000, v184
	v_fmamk_f32 v140, v140, 0x39800000, v178
	v_rsq_f32_e32 v140, v140
	v_mad_i64_i32 v[184:185], s[18:19], v150, s44, v[130:131]
	v_lshl_add_u64 v[190:191], v[184:185], 0, v[160:161]
	v_pk_mul_f32 v[186:187], v[126:127], v[140:141] op_sel_hi:[1,0]
	v_pk_mul_f32 v[184:185], v[124:125], v[140:141] op_sel_hi:[1,0]
	v_pk_mul_f32 v[192:193], v[118:119], v[140:141] op_sel_hi:[1,0]
	v_pk_mul_f32 v[194:195], v[116:117], v[140:141] op_sel_hi:[1,0]
	v_cvt_pk_bf16_f32 v184, v184, v185
	v_cvt_pk_bf16_f32 v185, v186, v187
	v_pk_mul_f32 v[196:197], v[122:123], v[140:141] op_sel_hi:[1,0]
	v_cvt_pk_bf16_f32 v186, v194, v195
	v_cvt_pk_bf16_f32 v187, v192, v193
	v_pk_mul_f32 v[198:199], v[120:121], v[140:141] op_sel_hi:[1,0]
	v_pk_mul_f32 v[200:201], v[114:115], v[140:141] op_sel_hi:[1,0]
	v_pk_mul_f32 v[202:203], v[112:113], v[140:141] op_sel_hi:[1,0]
	global_store_dwordx4 v[190:191], v[184:187], off
	s_nop 1
	v_cvt_pk_bf16_f32 v184, v198, v199
	v_cvt_pk_bf16_f32 v185, v196, v197
	v_cvt_pk_bf16_f32 v186, v202, v203
	v_cvt_pk_bf16_f32 v187, v200, v201
	global_store_dwordx4 v[190:191], v[184:187], off offset:256
	v_lshl_add_u64 v[188:189], v[154:155], 3, s[4:5]
	s_nop 1
	v_mov_b32_e32 v140, v241
	v_lshlrev_b64 v[186:187], s11, v[140:141]
	v_min_u32_e32 v140, 1, v186
	v_or_b32_e32 v140, v187, v140
	v_cvt_f32_u32_e32 v140, v140
	v_cvt_f32_u32_e32 v184, v240
	v_ldexp_f32 v140, v140, s13
	v_fmac_f32_e32 v140, 0x2f800000, v184
	v_fmamk_f32 v140, v140, 0x39800000, v178
	v_rsq_f32_e32 v140, v140
	v_mad_i64_i32 v[184:185], s[18:19], v156, s44, v[130:131]
	v_lshl_add_u64 v[190:191], v[184:185], 0, v[160:161]
	v_pk_mul_f32 v[186:187], v[110:111], v[140:141] op_sel_hi:[1,0]
	v_pk_mul_f32 v[184:185], v[108:109], v[140:141] op_sel_hi:[1,0]
	v_pk_mul_f32 v[192:193], v[102:103], v[140:141] op_sel_hi:[1,0]
	v_pk_mul_f32 v[194:195], v[100:101], v[140:141] op_sel_hi:[1,0]
	v_cvt_pk_bf16_f32 v184, v184, v185
	v_cvt_pk_bf16_f32 v185, v186, v187
	v_pk_mul_f32 v[196:197], v[106:107], v[140:141] op_sel_hi:[1,0]
	v_cvt_pk_bf16_f32 v186, v194, v195
	v_cvt_pk_bf16_f32 v187, v192, v193
	v_pk_mul_f32 v[198:199], v[104:105], v[140:141] op_sel_hi:[1,0]
	v_pk_mul_f32 v[200:201], v[98:99], v[140:141] op_sel_hi:[1,0]
	v_pk_mul_f32 v[202:203], v[96:97], v[140:141] op_sel_hi:[1,0]
	global_store_dwordx4 v[190:191], v[184:187], off
	s_nop 1
	v_cvt_pk_bf16_f32 v184, v198, v199
	v_cvt_pk_bf16_f32 v185, v196, v197
	v_cvt_pk_bf16_f32 v186, v202, v203
	v_cvt_pk_bf16_f32 v187, v200, v201
	global_store_dwordx4 v[190:191], v[184:187], off offset:256
	v_lshl_add_u64 v[188:189], v[152:153], 3, s[4:5]
	s_nop 1
	v_mov_b32_e32 v140, v243
	v_lshlrev_b64 v[186:187], s11, v[140:141]
	v_min_u32_e32 v140, 1, v186
	v_or_b32_e32 v140, v187, v140
	v_cvt_f32_u32_e32 v140, v140
	v_cvt_f32_u32_e32 v184, v242
	v_ldexp_f32 v140, v140, s13
	v_fmac_f32_e32 v140, 0x2f800000, v184
	v_fmamk_f32 v140, v140, 0x39800000, v178
	v_rsq_f32_e32 v140, v140
	v_mad_i64_i32 v[184:185], s[18:19], v154, s44, v[130:131]
	v_lshl_add_u64 v[190:191], v[184:185], 0, v[160:161]
	v_pk_mul_f32 v[186:187], v[94:95], v[140:141] op_sel_hi:[1,0]
	v_pk_mul_f32 v[184:185], v[92:93], v[140:141] op_sel_hi:[1,0]
	v_pk_mul_f32 v[192:193], v[86:87], v[140:141] op_sel_hi:[1,0]
	v_pk_mul_f32 v[194:195], v[84:85], v[140:141] op_sel_hi:[1,0]
	v_cvt_pk_bf16_f32 v184, v184, v185
	v_cvt_pk_bf16_f32 v185, v186, v187
	v_pk_mul_f32 v[196:197], v[90:91], v[140:141] op_sel_hi:[1,0]
	v_cvt_pk_bf16_f32 v186, v194, v195
	v_cvt_pk_bf16_f32 v187, v192, v193
	v_pk_mul_f32 v[198:199], v[88:89], v[140:141] op_sel_hi:[1,0]
	v_pk_mul_f32 v[200:201], v[82:83], v[140:141] op_sel_hi:[1,0]
	v_pk_mul_f32 v[202:203], v[80:81], v[140:141] op_sel_hi:[1,0]
	global_store_dwordx4 v[190:191], v[184:187], off
	s_nop 1
	v_cvt_pk_bf16_f32 v184, v198, v199
	v_cvt_pk_bf16_f32 v185, v196, v197
	v_cvt_pk_bf16_f32 v186, v202, v203
	v_cvt_pk_bf16_f32 v187, v200, v201
	global_store_dwordx4 v[190:191], v[184:187], off offset:256
	s_nop 1
	v_mov_b32_e32 v140, v245
	v_lshlrev_b64 v[186:187], s11, v[140:141]
	v_min_u32_e32 v140, 1, v186
	v_or_b32_e32 v140, v187, v140
	v_cvt_f32_u32_e32 v140, v140
	v_cvt_f32_u32_e32 v184, v244
	v_ldexp_f32 v140, v140, s13
	v_fmac_f32_e32 v140, 0x2f800000, v184
	v_fmamk_f32 v140, v140, 0x39800000, v178
	v_rsq_f32_e32 v140, v140
	v_mad_i64_i32 v[184:185], s[18:19], v152, s44, v[130:131]
	v_lshl_add_u64 v[188:189], v[184:185], 0, v[160:161]
	v_pk_mul_f32 v[186:187], v[78:79], v[140:141] op_sel_hi:[1,0]
	v_pk_mul_f32 v[184:185], v[76:77], v[140:141] op_sel_hi:[1,0]
	v_pk_mul_f32 v[190:191], v[70:71], v[140:141] op_sel_hi:[1,0]
	v_pk_mul_f32 v[192:193], v[68:69], v[140:141] op_sel_hi:[1,0]
	v_cvt_pk_bf16_f32 v184, v184, v185
	v_cvt_pk_bf16_f32 v185, v186, v187
	v_pk_mul_f32 v[194:195], v[74:75], v[140:141] op_sel_hi:[1,0]
	v_cvt_pk_bf16_f32 v186, v192, v193
	v_cvt_pk_bf16_f32 v187, v190, v191
	v_pk_mul_f32 v[196:197], v[72:73], v[140:141] op_sel_hi:[1,0]
	v_pk_mul_f32 v[198:199], v[66:67], v[140:141] op_sel_hi:[1,0]
	v_pk_mul_f32 v[200:201], v[64:65], v[140:141] op_sel_hi:[1,0]
	global_store_dwordx4 v[188:189], v[184:187], off
	s_nop 1
	v_cvt_pk_bf16_f32 v184, v196, v197
; __device__ __forceinline__ u32x4 pack8(const f32x4 a, const f32x4 b) { u32x4 w; w.x = cvt_pk_bf16(a[0], a[1]); w.y = cvt_pk_bf16(a[2], a[3]); w.z = cvt_pk_bf16(b[0], b[1]); w.w = cvt_pk_bf16(b[2], b[3]); return w; }
; __device__ __forceinline__ float row_rstd(const u64* ssq, int r) { return __builtin_amdgcn_rsqf(fx_to_pos(ssq[r]) * (1.0f / 4096.0f) + RMS_EPS); }
;     __device__ __forceinline__ void operator()(const f32x4 (&acc)[2][2][4][2], const Unit& u, int wr, int wc, int fr, int fq) const {
;     ...
;             for (int ai = 0; ai < 2; ++ai)
; #pragma unroll
;                 for (int m = 0; m < 4; ++m) { const int r = row0 + ai * HALF + m * 16; const float rs = row_rstd(ssq, r); bf16_t* rowp = Z + (size_t)r * RET_IN + col0;
; #pragma unroll
;                     for (int bj = 0; bj < 2; ++bj) *(u32x4*)(rowp + bj * HALF) = pack8(acc[ai][bj][m][0] * rs, acc[ai][bj][m][1] * rs); }
	v_cvt_pk_bf16_f32 v185, v194, v195
	v_cvt_pk_bf16_f32 v186, v200, v201
	v_cvt_pk_bf16_f32 v187, v198, v199
	global_store_dwordx4 v[188:189], v[184:187], off offset:256
	s_nop 1
	v_mov_b32_e32 v140, v249
	v_lshlrev_b64 v[186:187], s11, v[140:141]
	v_min_u32_e32 v140, 1, v186
	v_or_b32_e32 v140, v187, v140
	v_cvt_f32_u32_e32 v140, v140
	v_cvt_f32_u32_e32 v184, v248
	v_ldexp_f32 v140, v140, s13
	v_fmac_f32_e32 v140, 0x2f800000, v184
	v_fmamk_f32 v140, v140, 0x39800000, v178
	v_rsq_f32_e32 v140, v140
	v_mad_i64_i32 v[184:185], s[18:19], v183, s44, v[130:131]
	v_lshl_add_u64 v[188:189], v[184:185], 0, v[160:161]
	v_pk_mul_f32 v[186:187], v[62:63], v[140:141] op_sel_hi:[1,0]
	v_pk_mul_f32 v[184:185], v[60:61], v[140:141] op_sel_hi:[1,0]
	v_pk_mul_f32 v[190:191], v[54:55], v[140:141] op_sel_hi:[1,0]
	v_pk_mul_f32 v[192:193], v[52:53], v[140:141] op_sel_hi:[1,0]
	v_cvt_pk_bf16_f32 v184, v184, v185
	v_cvt_pk_bf16_f32 v185, v186, v187
	v_pk_mul_f32 v[194:195], v[58:59], v[140:141] op_sel_hi:[1,0]
	v_cvt_pk_bf16_f32 v186, v192, v193
	v_cvt_pk_bf16_f32 v187, v190, v191
	v_pk_mul_f32 v[196:197], v[56:57], v[140:141] op_sel_hi:[1,0]
	v_pk_mul_f32 v[198:199], v[50:51], v[140:141] op_sel_hi:[1,0]
	v_pk_mul_f32 v[200:201], v[48:49], v[140:141] op_sel_hi:[1,0]
	global_store_dwordx4 v[188:189], v[184:187], off
	s_nop 1
	v_cvt_pk_bf16_f32 v184, v196, v197
	v_cvt_pk_bf16_f32 v185, v194, v195
	v_cvt_pk_bf16_f32 v186, v200, v201
	v_cvt_pk_bf16_f32 v187, v198, v199
	global_store_dwordx4 v[188:189], v[184:187], off offset:256
	s_nop 1
	v_mov_b32_e32 v140, v251
	v_lshlrev_b64 v[186:187], s11, v[140:141]
	v_min_u32_e32 v140, 1, v186
	v_or_b32_e32 v140, v187, v140
	v_cvt_f32_u32_e32 v140, v140
	v_cvt_f32_u32_e32 v184, v250
	v_ldexp_f32 v140, v140, s13
	v_fmac_f32_e32 v140, 0x2f800000, v184
	v_fmamk_f32 v140, v140, 0x39800000, v178
	v_rsq_f32_e32 v140, v140
	v_mad_i64_i32 v[184:185], s[18:19], v182, s44, v[130:131]
	v_lshl_add_u64 v[188:189], v[184:185], 0, v[160:161]
	v_pk_mul_f32 v[186:187], v[46:47], v[140:141] op_sel_hi:[1,0]
	v_pk_mul_f32 v[184:185], v[44:45], v[140:141] op_sel_hi:[1,0]
	v_pk_mul_f32 v[190:191], v[38:39], v[140:141] op_sel_hi:[1,0]
	v_pk_mul_f32 v[192:193], v[36:37], v[140:141] op_sel_hi:[1,0]
	v_cvt_pk_bf16_f32 v184, v184, v185
	v_cvt_pk_bf16_f32 v185, v186, v187
	v_pk_mul_f32 v[194:195], v[42:43], v[140:141] op_sel_hi:[1,0]
	v_cvt_pk_bf16_f32 v186, v192, v193
	v_cvt_pk_bf16_f32 v187, v190, v191
	v_pk_mul_f32 v[196:197], v[40:41], v[140:141] op_sel_hi:[1,0]
	v_pk_mul_f32 v[198:199], v[34:35], v[140:141] op_sel_hi:[1,0]
	v_pk_mul_f32 v[200:201], v[32:33], v[140:141] op_sel_hi:[1,0]
	global_store_dwordx4 v[188:189], v[184:187], off
	s_nop 1
	v_cvt_pk_bf16_f32 v184, v196, v197
	v_cvt_pk_bf16_f32 v185, v194, v195
	v_cvt_pk_bf16_f32 v186, v200, v201
	v_cvt_pk_bf16_f32 v187, v198, v199
	global_store_dwordx4 v[188:189], v[184:187], off offset:256
	s_nop 1
	v_mov_b32_e32 v140, v253
	v_lshlrev_b64 v[186:187], s11, v[140:141]
	v_min_u32_e32 v140, 1, v186
	v_or_b32_e32 v140, v187, v140
	v_cvt_f32_u32_e32 v140, v140
	v_cvt_f32_u32_e32 v184, v252
	v_ldexp_f32 v140, v140, s13
	v_fmac_f32_e32 v140, 0x2f800000, v184
	v_fmamk_f32 v140, v140, 0x39800000, v178
	v_rsq_f32_e32 v140, v140
	v_mad_i64_i32 v[184:185], s[18:19], v181, s44, v[130:131]
	v_lshl_add_u64 v[188:189], v[184:185], 0, v[160:161]
	v_pk_mul_f32 v[186:187], v[30:31], v[140:141] op_sel_hi:[1,0]
	v_pk_mul_f32 v[184:185], v[28:29], v[140:141] op_sel_hi:[1,0]
	v_pk_mul_f32 v[190:191], v[22:23], v[140:141] op_sel_hi:[1,0]
	v_pk_mul_f32 v[192:193], v[20:21], v[140:141] op_sel_hi:[1,0]
	v_cvt_pk_bf16_f32 v184, v184, v185
	v_cvt_pk_bf16_f32 v185, v186, v187
	v_pk_mul_f32 v[194:195], v[26:27], v[140:141] op_sel_hi:[1,0]
	v_cvt_pk_bf16_f32 v186, v192, v193
	v_cvt_pk_bf16_f32 v187, v190, v191
	v_pk_mul_f32 v[196:197], v[24:25], v[140:141] op_sel_hi:[1,0]
	v_pk_mul_f32 v[198:199], v[18:19], v[140:141] op_sel_hi:[1,0]
	v_pk_mul_f32 v[200:201], v[16:17], v[140:141] op_sel_hi:[1,0]
	global_store_dwordx4 v[188:189], v[184:187], off
	v_mad_i64_i32 v[130:131], s[18:19], v180, s44, v[130:131]
	s_nop 0
	v_cvt_pk_bf16_f32 v184, v196, v197
	v_cvt_pk_bf16_f32 v185, v194, v195
	v_cvt_pk_bf16_f32 v186, v200, v201
	v_cvt_pk_bf16_f32 v187, v198, v199
	global_store_dwordx4 v[188:189], v[184:187], off offset:256
	v_lshl_add_u64 v[160:161], v[130:131], 0, v[160:161]
	s_nop 1
	v_mov_b32_e32 v140, v255
	v_lshlrev_b64 v[184:185], s11, v[140:141]
	v_min_u32_e32 v129, 1, v184
	v_or_b32_e32 v129, v185, v129
	v_cvt_f32_u32_e32 v129, v129
	v_cvt_f32_u32_e32 v128, v254
	v_ldexp_f32 v129, v129, s13
	v_fmac_f32_e32 v129, 0x2f800000, v128
	v_fmamk_f32 v128, v129, 0x39800000, v178
	v_rsq_f32_e32 v128, v128
	s_nop 0
	v_pk_mul_f32 v[130:131], v[14:15], v[128:129] op_sel_hi:[1,0]
	v_pk_mul_f32 v[184:185], v[12:13], v[128:129] op_sel_hi:[1,0]
	v_pk_mul_f32 v[186:187], v[6:7], v[128:129] op_sel_hi:[1,0]
	v_pk_mul_f32 v[188:189], v[4:5], v[128:129] op_sel_hi:[1,0]
	v_pk_mul_f32 v[190:191], v[10:11], v[128:129] op_sel_hi:[1,0]
	v_pk_mul_f32 v[192:193], v[8:9], v[128:129] op_sel_hi:[1,0]
	v_pk_mul_f32 v[194:195], v[2:3], v[128:129] op_sel_hi:[1,0]
	v_pk_mul_f32 v[196:197], v[0:1], v[128:129] op_sel_hi:[1,0]
	v_cvt_pk_bf16_f32 v128, v184, v185
	v_cvt_pk_bf16_f32 v129, v130, v131
	v_cvt_pk_bf16_f32 v130, v188, v189
	v_cvt_pk_bf16_f32 v131, v186, v187
	global_store_dwordx4 v[160:161], v[128:131], off
	s_nop 1
	v_cvt_pk_bf16_f32 v128, v192, v193
	v_cvt_pk_bf16_f32 v129, v190, v191
	v_cvt_pk_bf16_f32 v130, v196, v197
	v_cvt_pk_bf16_f32 v131, v194, v195
	s_cbranch_execnz .LBB0_1255
; __device__ __forceinline__ u32x4 pack8(const f32x4 a, const f32x4 b) { u32x4 w; w.x = cvt_pk_bf16(a[0], a[1]); w.y = cvt_pk_bf16(a[2], a[3]); w.z = cvt_pk_bf16(b[0], b[1]); w.w = cvt_pk_bf16(b[2], b[3]); return w; }
; __device__ __forceinline__ float row_rstd(const u64* ssq, int r) { return __builtin_amdgcn_rsqf(fx_to_pos(ssq[r]) * (1.0f / 4096.0f) + RMS_EPS); }
;     __device__ __forceinline__ void operator()(const f32x4 (&acc)[2][2][4][2], const Unit& u, int wr, int wc, int fr, int fq) const {
;     ...
;         if (u.pn < 32) {
;             const float sc = u.pn < 16 ? 1.0f : 0.0625f;
;             float inv[2][4];
; #pragma unroll
;             for (int n = 0; n < 2; ++n)
; #pragma unroll
;                 for (int j = 0; j < 4; ++j) inv[n][j] = exp2f(-(float)(wc * 32 + 8 * fq + 4 * n + j) * (13.287712379549449f / 128.0f));
; #pragma unroll
;             for (int ai = 0; ai < 2; ++ai)
; #pragma unroll
;                 for (int m = 0; m < 4; ++m) { const int r = row0 + ai * HALF + m * 16; const float rs = row_rstd(ssq, r) * sc;
;                     const float t = (float)(r < MTOK ? NMETA + (r & (SEQ - 1)) : ((r - MTOK) & 15));
;                     f32x4 o1[2], o2[2];
; #pragma unroll
;                     for (int n = 0; n < 2; ++n)
; #pragma unroll
;                         for (int j = 0; j < 4; ++j) { const float x1 = acc[ai][0][m][n][j] * rs, x2 = acc[ai][1][m][n][j] * rs;
;                             const float ang = t * inv[n][j]; float rev = ang * 0.15915494309189535f; rev = rev - floorf(rev);
;                             const float c = __builtin_amdgcn_cosf(rev), s = __builtin_amdgcn_sinf(rev);
;                             o1[n][j] = x1 * c - x2 * s; o2[n][j] = x1 * s + x2 * c; }
;                     bf16_t* rowp = Z + (size_t)r * RET_IN + col0;
;                     *(u32x4*)(rowp) = pack8(o1[0], o1[1]); *(u32x4*)(rowp + HALF) = pack8(o2[0], o2[1]); }
.LBB0_1257:
	v_lshl_add_u64 v[128:129], v[150:151], 3, s[4:5]
	v_and_or_b32 v140, v150, s45, 16
	v_cmp_gt_i32_e32 vcc, s37, v150
	v_mov_b32_e32 v161, v120
	v_mov_b32_e32 v120, v125
	v_mov_b32_e32 v125, v122
	v_mov_b32_e32 v122, v127
	v_mov_b32_e32 v127, v112
	v_cndmask_b32_e32 v112, v163, v140, vcc
	v_cvt_f32_u32_e32 v151, v112
	s_cmp_lt_i32 s56, 16
	s_cselect_b64 s[18:19], -1, 0
	s_min_u32 s13, s55, 32
	v_mul_f32_e32 v140, v168, v151
	v_mul_f32_e32 v186, v171, v151
	v_mul_f32_e32 v187, v172, v151
	v_mul_f32_e32 v189, 0.15915494, v140
	v_mul_f32_e32 v112, v167, v151
	v_mul_f32_e32 v192, 0.15915494, v186
	v_mul_f32_e32 v193, 0.15915494, v187
	v_floor_f32_e32 v189, v189
	v_mul_f32_e32 v184, v169, v151
	v_mul_f32_e32 v185, v170, v151
	v_mul_f32_e32 v188, 0.15915494, v112
	v_floor_f32_e32 v192, v192
	v_floor_f32_e32 v193, v193
	v_fma_f32 v140, v140, 0.15915494, -v189
	v_mul_f32_e32 v190, 0.15915494, v184
	v_mul_f32_e32 v191, 0.15915494, v185
	v_floor_f32_e32 v188, v188
	v_fma_f32 v194, v186, 0.15915494, -v192
	v_fma_f32 v195, v187, 0.15915494, -v193
	v_cos_f32_e32 v186, v140
	v_sin_f32_e32 v187, v140
	v_floor_f32_e32 v190, v190
	v_floor_f32_e32 v191, v191
	v_fma_f32 v112, v112, 0.15915494, -v188
	v_fma_f32 v189, v184, 0.15915494, -v190
	v_fma_f32 v191, v185, 0.15915494, -v191
	v_cos_f32_e32 v184, v112
	v_sin_f32_e32 v185, v112
	s_sub_i32 s11, 32, s13
	v_mov_b32_e32 v160, v124
	v_mov_b32_e32 v124, v126
	v_mov_b32_e32 v126, v116
	v_cndmask_b32_e64 v116, v179, 1.0, s[18:19]
	v_cos_f32_e32 v192, v194
	v_sin_f32_e32 v193, v194
	v_cos_f32_e32 v194, v195
	v_sin_f32_e32 v195, v195
	v_cos_f32_e32 v190, v191
	v_sin_f32_e32 v191, v191
	v_mov_b32_e32 v198, v187
	v_mov_b32_e32 v199, v186
	v_mov_b32_e32 v196, v185
	v_mov_b32_e32 v197, v184
	v_cos_f32_e32 v188, v189
	v_sin_f32_e32 v189, v189
	v_cmp_gt_i32_e32 vcc, s37, v156
	v_mov_b32_e32 v201, v188
	v_mov_b32_e32 v200, v189
	v_mov_b32_e32 v140, v239
	v_lshlrev_b64 v[202:203], s13, v[140:141]
	v_min_u32_e32 v112, 1, v202
	v_or_b32_e32 v112, v203, v112
	v_cvt_f32_u32_e32 v112, v112
	v_cvt_f32_u32_e32 v131, v238
	v_mov_b32_e32 v130, v191
	v_mov_b32_e32 v202, v193
	v_ldexp_f32 v112, v112, s11
	v_fmac_f32_e32 v112, 0x2f800000, v131
	v_fmamk_f32 v112, v112, 0x39800000, v178
	v_rsq_f32_e32 v112, v112
	v_mov_b32_e32 v131, v190
	v_mov_b32_e32 v203, v192
	v_mul_f32_e32 v140, v116, v112
	v_pk_mul_f32 v[160:161], v[160:161], v[140:141] op_sel_hi:[1,0]
	v_pk_mul_f32 v[120:121], v[120:121], v[140:141] op_sel_hi:[1,0]
	v_mov_b32_e32 v112, v117
	v_pk_mul_f32 v[184:185], v[184:185], v[160:161]
	v_pk_mul_f32 v[186:187], v[186:187], v[120:121]
	v_pk_mul_f32 v[120:121], v[198:199], v[120:121]
	v_pk_mul_f32 v[112:113], v[112:113], v[140:141] op_sel_hi:[1,0]
	v_sub_f32_e32 v184, v184, v185
	v_add_f32_e32 v185, v120, v121
	v_pk_mul_f32 v[120:121], v[194:195], v[112:113]
	v_pk_mul_f32 v[122:123], v[122:123], v[140:141] op_sel_hi:[1,0]
	v_pk_mul_f32 v[126:127], v[126:127], v[140:141] op_sel_hi:[1,0]
	v_sub_f32_e32 v117, v120, v121
	v_mov_b32_e32 v120, v195
	v_mov_b32_e32 v121, v194
	v_pk_mul_f32 v[190:191], v[190:191], v[122:123]
	v_pk_mul_f32 v[122:123], v[130:131], v[122:123]
	v_pk_mul_f32 v[130:131], v[192:193], v[126:127]
	v_pk_mul_f32 v[126:127], v[202:203], v[126:127]
	v_pk_mul_f32 v[112:113], v[120:121], v[112:113]
	v_add_f32_e32 v126, v126, v127
	v_add_f32_e32 v127, v112, v113
	v_mul_f32_e32 v112, v173, v151
	v_mul_f32_e32 v113, 0.15915494, v112
	v_floor_f32_e32 v113, v113
	v_fma_f32 v113, v112, 0.15915494, -v113
	v_cos_f32_e32 v112, v113
	v_sin_f32_e32 v113, v113
	v_mov_b32_e32 v120, v118
	v_mov_b32_e32 v121, v114
	v_mul_f32_e32 v114, v174, v151
	v_pk_mul_f32 v[160:161], v[196:197], v[160:161]
	v_pk_mul_f32 v[120:121], v[120:121], v[140:141] op_sel_hi:[1,0]
	v_mul_f32_e32 v118, 0.15915494, v114
	v_add_f32_e32 v160, v160, v161
	v_sub_f32_e32 v161, v186, v187
	v_add_f32_e32 v187, v122, v123
	v_pk_mul_f32 v[122:123], v[112:113], v[120:121]
	v_floor_f32_e32 v118, v118
	v_sub_f32_e32 v130, v130, v131
	v_sub_f32_e32 v131, v122, v123
	v_mov_b32_e32 v122, v113
	v_mov_b32_e32 v123, v112
	v_fma_f32 v114, v114, 0.15915494, -v118
	v_pk_mul_f32 v[112:113], v[122:123], v[120:121]
	v_cos_f32_e32 v120, v114
	v_sin_f32_e32 v121, v114
	v_mov_b32_e32 v114, v119
	v_add_f32_e32 v151, v112, v113
	v_pk_mul_f32 v[112:113], v[114:115], v[140:141] op_sel_hi:[1,0]
	v_pk_mul_f32 v[124:125], v[124:125], v[140:141] op_sel_hi:[1,0]
	v_pk_mul_f32 v[114:115], v[120:121], v[112:113]
	v_pk_mul_f32 v[188:189], v[188:189], v[124:125]
	v_sub_f32_e32 v140, v114, v115
	v_mov_b32_e32 v114, v121
	v_mov_b32_e32 v115, v120
	v_pk_mul_f32 v[112:113], v[114:115], v[112:113]
	v_sub_f32_e32 v186, v188, v189
	v_add_f32_e32 v188, v112, v113
	v_mov_b64_e32 v[112:113], s[80:81]
	v_pk_mul_f32 v[124:125], v[200:201], v[124:125]
	v_mad_i64_i32 v[118:119], s[18:19], v150, s44, v[112:113]
	v_lshlrev_b64 v[114:115], 1, v[158:159]
	v_add_f32_e32 v124, v124, v125
	v_sub_f32_e32 v125, v190, v191
	v_lshl_add_u64 v[122:123], v[118:119], 0, v[114:115]
	v_cvt_pk_bf16_f32 v118, v184, v161
	v_cvt_pk_bf16_f32 v119, v186, v125
	v_cvt_pk_bf16_f32 v120, v130, v117
	v_cvt_pk_bf16_f32 v121, v131, v140
	global_store_dwordx4 v[122:123], v[118:121], off
	v_bitop3_b32 v117, v150, s48, 16 bitop3:0xc8
	v_add_u32_e32 v117, 16, v117
	v_cvt_pk_bf16_f32 v118, v160, v185
	v_cvt_pk_bf16_f32 v119, v124, v187
	v_cvt_pk_bf16_f32 v120, v126, v127
	v_cvt_pk_bf16_f32 v121, v151, v188
	global_store_dwordx4 v[122:123], v[118:121], off offset:256
	v_cndmask_b32_e32 v117, v163, v117, vcc
	v_cvt_f32_u32_e32 v117, v117
	v_lshl_add_u64 v[118:119], v[156:157], 3, s[4:5]
	v_mov_b32_e32 v120, v108
	v_mov_b32_e32 v121, v104
; __device__ __forceinline__ u32x4 pack8(const f32x4 a, const f32x4 b) { u32x4 w; w.x = cvt_pk_bf16(a[0], a[1]); w.y = cvt_pk_bf16(a[2], a[3]); w.z = cvt_pk_bf16(b[0], b[1]); w.w = cvt_pk_bf16(b[2], b[3]); return w; }
; __device__ __forceinline__ float row_rstd(const u64* ssq, int r) { return __builtin_amdgcn_rsqf(fx_to_pos(ssq[r]) * (1.0f / 4096.0f) + RMS_EPS); }
;     __device__ __forceinline__ void operator()(const f32x4 (&acc)[2][2][4][2], const Unit& u, int wr, int wc, int fr, int fq) const {
;     ...
;                 for (int m = 0; m < 4; ++m) { const int r = row0 + ai * HALF + m * 16; const float rs = row_rstd(ssq, r) * sc;
;                     const float t = (float)(r < MTOK ? NMETA + (r & (SEQ - 1)) : ((r - MTOK) & 15));
;                     f32x4 o1[2], o2[2];
; #pragma unroll
;                     for (int n = 0; n < 2; ++n)
; #pragma unroll
;                         for (int j = 0; j < 4; ++j) { const float x1 = acc[ai][0][m][n][j] * rs, x2 = acc[ai][1][m][n][j] * rs;
;                             const float ang = t * inv[n][j]; float rev = ang * 0.15915494309189535f; rev = rev - floorf(rev);
;                             const float c = __builtin_amdgcn_cosf(rev), s = __builtin_amdgcn_sinf(rev);
;                             o1[n][j] = x1 * c - x2 * s; o2[n][j] = x1 * s + x2 * c; }
;                     bf16_t* rowp = Z + (size_t)r * RET_IN + col0;
;                     *(u32x4*)(rowp) = pack8(o1[0], o1[1]); *(u32x4*)(rowp + HALF) = pack8(o2[0], o2[1]); }
	v_mov_b32_e32 v104, v109
	v_mul_f32_e32 v108, v167, v117
	v_mul_f32_e32 v109, v168, v117
	v_mul_f32_e32 v122, 0.15915494, v108
	v_mul_f32_e32 v123, 0.15915494, v109
	v_floor_f32_e32 v122, v122
	v_floor_f32_e32 v123, v123
	v_fma_f32 v122, v108, 0.15915494, -v122
	v_fma_f32 v123, v109, 0.15915494, -v123
	v_cos_f32_e32 v108, v122
	v_sin_f32_e32 v109, v122
	v_cos_f32_e32 v122, v123
	v_sin_f32_e32 v123, v123
	v_mul_f32_e32 v127, v169, v117
	v_mul_f32_e32 v130, 0.15915494, v127
	v_cmp_gt_i32_e32 vcc, s37, v154
	s_nop 1
	v_mov_b32_e32 v140, v241
	v_lshlrev_b64 v[124:125], s13, v[140:141]
	v_min_u32_e32 v119, 1, v124
	v_or_b32_e32 v119, v125, v119
	v_cvt_f32_u32_e32 v119, v119
	v_cvt_f32_u32_e32 v124, v240
	v_mov_b32_e32 v118, v109
	v_mov_b32_e32 v125, v122
	v_ldexp_f32 v119, v119, s11
	v_fmac_f32_e32 v119, 0x2f800000, v124
	v_fmamk_f32 v119, v119, 0x39800000, v178
	v_rsq_f32_e32 v126, v119
	v_mov_b32_e32 v119, v108
	v_mov_b32_e32 v124, v123
	v_mul_f32_e32 v126, v116, v126
	v_pk_mul_f32 v[120:121], v[120:121], v[126:127] op_sel_hi:[1,0]
	v_pk_mul_f32 v[104:105], v[104:105], v[126:127] op_sel_hi:[1,0]
	v_pk_mul_f32 v[108:109], v[108:109], v[120:121]
	v_pk_mul_f32 v[118:119], v[118:119], v[120:121]
	v_pk_mul_f32 v[120:121], v[122:123], v[104:105]
	v_pk_mul_f32 v[104:105], v[124:125], v[104:105]
	v_sub_f32_e32 v120, v120, v121
	v_add_f32_e32 v121, v104, v105
	v_floor_f32_e32 v104, v130
	v_fma_f32 v105, v127, 0.15915494, -v104
	v_cos_f32_e32 v104, v105
	v_sin_f32_e32 v105, v105
	v_sub_f32_e32 v122, v108, v109
	v_mov_b32_e32 v108, v110
	v_mov_b32_e32 v109, v106
	v_pk_mul_f32 v[108:109], v[108:109], v[126:127] op_sel_hi:[1,0]
	v_add_f32_e32 v123, v118, v119
	v_pk_mul_f32 v[118:119], v[104:105], v[108:109]
	v_mul_f32_e32 v106, v170, v117
	v_sub_f32_e32 v110, v118, v119
	v_mov_b32_e32 v118, v105
	v_mov_b32_e32 v119, v104
	v_pk_mul_f32 v[104:105], v[118:119], v[108:109]
	v_mul_f32_e32 v108, 0.15915494, v106
	v_floor_f32_e32 v108, v108
	v_fma_f32 v106, v106, 0.15915494, -v108
	v_cos_f32_e32 v108, v106
	v_sin_f32_e32 v109, v106
	v_mov_b32_e32 v106, v111
	v_add_f32_e32 v118, v104, v105
	v_pk_mul_f32 v[104:105], v[106:107], v[126:127] op_sel_hi:[1,0]
	s_nop 0
	v_pk_mul_f32 v[106:107], v[108:109], v[104:105]
	s_nop 0
	v_sub_f32_e32 v111, v106, v107
	v_mov_b32_e32 v106, v109
	v_mov_b32_e32 v107, v108
	v_pk_mul_f32 v[104:105], v[106:107], v[104:105]
	v_mov_b32_e32 v106, v100
	v_add_f32_e32 v119, v104, v105
	v_mul_f32_e32 v104, v171, v117
	v_mul_f32_e32 v105, 0.15915494, v104
	v_floor_f32_e32 v105, v105
	v_fma_f32 v105, v104, 0.15915494, -v105
	v_cos_f32_e32 v104, v105
	v_sin_f32_e32 v105, v105
	v_mov_b32_e32 v107, v96
	v_mul_f32_e32 v96, v172, v117
	v_pk_mul_f32 v[106:107], v[106:107], v[126:127] op_sel_hi:[1,0]
	v_mul_f32_e32 v100, 0.15915494, v96
	v_pk_mul_f32 v[108:109], v[104:105], v[106:107]
	v_floor_f32_e32 v100, v100
	v_sub_f32_e32 v124, v108, v109
	v_mov_b32_e32 v108, v105
	v_mov_b32_e32 v109, v104
	v_fma_f32 v96, v96, 0.15915494, -v100
	v_pk_mul_f32 v[104:105], v[108:109], v[106:107]
	v_cos_f32_e32 v106, v96
	v_sin_f32_e32 v107, v96
	v_mov_b32_e32 v96, v101
	v_pk_mul_f32 v[96:97], v[96:97], v[126:127] op_sel_hi:[1,0]
	v_add_f32_e32 v108, v104, v105
	v_pk_mul_f32 v[100:101], v[106:107], v[96:97]
	s_nop 0
	v_sub_f32_e32 v109, v100, v101
	v_mov_b32_e32 v100, v107
	v_mov_b32_e32 v101, v106
	v_pk_mul_f32 v[96:97], v[100:101], v[96:97]
	v_mov_b32_e32 v100, v102
	v_add_f32_e32 v106, v96, v97
	v_mul_f32_e32 v96, v173, v117
	v_mul_f32_e32 v97, 0.15915494, v96
	v_floor_f32_e32 v97, v97
	v_fma_f32 v97, v96, 0.15915494, -v97
	v_cos_f32_e32 v96, v97
	v_sin_f32_e32 v97, v97
	v_mov_b32_e32 v101, v98
	v_pk_mul_f32 v[100:101], v[100:101], v[126:127] op_sel_hi:[1,0]
	v_mul_f32_e32 v98, v174, v117
	v_pk_mul_f32 v[104:105], v[96:97], v[100:101]
	s_nop 0
	v_sub_f32_e32 v102, v104, v105
	v_mov_b32_e32 v104, v97
	v_mov_b32_e32 v105, v96
	v_pk_mul_f32 v[96:97], v[104:105], v[100:101]
	v_mul_f32_e32 v100, 0.15915494, v98
	v_floor_f32_e32 v100, v100
	v_fma_f32 v98, v98, 0.15915494, -v100
	v_cos_f32_e32 v100, v98
	v_sin_f32_e32 v101, v98
	v_mov_b32_e32 v98, v103
	v_add_f32_e32 v104, v96, v97
	v_pk_mul_f32 v[96:97], v[98:99], v[126:127] op_sel_hi:[1,0]
	s_nop 0
	v_pk_mul_f32 v[98:99], v[100:101], v[96:97]
	s_nop 0
	v_sub_f32_e32 v103, v98, v99
	v_mov_b32_e32 v98, v101
	v_mov_b32_e32 v99, v100
	v_pk_mul_f32 v[96:97], v[98:99], v[96:97]
	s_nop 0
	v_add_f32_e32 v105, v96, v97
	v_mad_i64_i32 v[96:97], s[18:19], v156, s44, v[112:113]
	v_lshl_add_u64 v[100:101], v[96:97], 0, v[114:115]
	v_cvt_pk_bf16_f32 v96, v122, v120
	v_cvt_pk_bf16_f32 v97, v110, v111
	v_cvt_pk_bf16_f32 v98, v124, v109
	v_cvt_pk_bf16_f32 v99, v102, v103
	global_store_dwordx4 v[100:101], v[96:99], off
	s_nop 1
	v_cvt_pk_bf16_f32 v96, v123, v121
	v_cvt_pk_bf16_f32 v97, v118, v119
	v_cvt_pk_bf16_f32 v98, v108, v106
	v_cvt_pk_bf16_f32 v99, v104, v105
	global_store_dwordx4 v[100:101], v[96:99], off offset:256
	v_mov_b32_e32 v100, v92
	v_mov_b32_e32 v101, v88
	v_lshl_add_u64 v[96:97], v[154:155], 3, s[4:5]
	s_nop 1
	v_mov_b32_e32 v140, v243
	v_lshlrev_b64 v[98:99], s13, v[140:141]
	v_min_u32_e32 v97, 1, v98
	v_or_b32_e32 v97, v99, v97
	v_cvt_f32_u32_e32 v97, v97
	v_cvt_f32_u32_e32 v96, v242
	v_ldexp_f32 v97, v97, s11
	v_fmac_f32_e32 v97, 0x2f800000, v96
	v_fmamk_f32 v96, v97, 0x39800000, v178
	v_and_or_b32 v97, v154, s49, 16
	v_cndmask_b32_e32 v97, v163, v97, vcc
	v_cvt_f32_u32_e32 v97, v97
	v_rsq_f32_e32 v96, v96
	v_cmp_gt_i32_e32 vcc, s37, v152
	v_mul_f32_e32 v98, v167, v97
	v_mul_f32_e32 v99, 0.15915494, v98
	v_floor_f32_e32 v99, v99
	v_fma_f32 v99, v98, 0.15915494, -v99
	v_cos_f32_e32 v98, v99
	v_sin_f32_e32 v99, v99
; __device__ __forceinline__ u32x4 pack8(const f32x4 a, const f32x4 b) { u32x4 w; w.x = cvt_pk_bf16(a[0], a[1]); w.y = cvt_pk_bf16(a[2], a[3]); w.z = cvt_pk_bf16(b[0], b[1]); w.w = cvt_pk_bf16(b[2], b[3]); return w; }
; __device__ __forceinline__ float row_rstd(const u64* ssq, int r) { return __builtin_amdgcn_rsqf(fx_to_pos(ssq[r]) * (1.0f / 4096.0f) + RMS_EPS); }
;     __device__ __forceinline__ void operator()(const f32x4 (&acc)[2][2][4][2], const Unit& u, int wr, int wc, int fr, int fq) const {
;     ...
;                 for (int m = 0; m < 4; ++m) { const int r = row0 + ai * HALF + m * 16; const float rs = row_rstd(ssq, r) * sc;
;                     const float t = (float)(r < MTOK ? NMETA + (r & (SEQ - 1)) : ((r - MTOK) & 15));
;                     f32x4 o1[2], o2[2];
; #pragma unroll
;                     for (int n = 0; n < 2; ++n)
; #pragma unroll
;                         for (int j = 0; j < 4; ++j) { const float x1 = acc[ai][0][m][n][j] * rs, x2 = acc[ai][1][m][n][j] * rs;
;                             const float ang = t * inv[n][j]; float rev = ang * 0.15915494309189535f; rev = rev - floorf(rev);
;                             const float c = __builtin_amdgcn_cosf(rev), s = __builtin_amdgcn_sinf(rev);
;                             o1[n][j] = x1 * c - x2 * s; o2[n][j] = x1 * s + x2 * c; }
;                     bf16_t* rowp = Z + (size_t)r * RET_IN + col0;
;                     *(u32x4*)(rowp) = pack8(o1[0], o1[1]); *(u32x4*)(rowp + HALF) = pack8(o2[0], o2[1]); }
	v_mul_f32_e32 v96, v116, v96
	v_mul_f32_e32 v88, v168, v97
	v_pk_mul_f32 v[100:101], v[100:101], v[96:97] op_sel_hi:[1,0]
	v_mul_f32_e32 v92, 0.15915494, v88
	v_pk_mul_f32 v[102:103], v[98:99], v[100:101]
	v_floor_f32_e32 v92, v92
	v_sub_f32_e32 v104, v102, v103
	v_mov_b32_e32 v102, v99
	v_mov_b32_e32 v103, v98
	v_fma_f32 v88, v88, 0.15915494, -v92
	v_pk_mul_f32 v[98:99], v[102:103], v[100:101]
	v_cos_f32_e32 v100, v88
	v_sin_f32_e32 v101, v88
	v_mov_b32_e32 v88, v93
	v_pk_mul_f32 v[88:89], v[88:89], v[96:97] op_sel_hi:[1,0]
	v_add_f32_e32 v102, v98, v99
	v_pk_mul_f32 v[92:93], v[100:101], v[88:89]
	s_nop 0
	v_sub_f32_e32 v103, v92, v93
	v_mov_b32_e32 v92, v101
	v_mov_b32_e32 v93, v100
	v_pk_mul_f32 v[88:89], v[92:93], v[88:89]
	v_mov_b32_e32 v92, v94
	v_add_f32_e32 v100, v88, v89
	v_mul_f32_e32 v88, v169, v97
	v_mul_f32_e32 v89, 0.15915494, v88
	v_floor_f32_e32 v89, v89
	v_fma_f32 v89, v88, 0.15915494, -v89
	v_cos_f32_e32 v88, v89
	v_sin_f32_e32 v89, v89
	v_mov_b32_e32 v93, v90
	v_pk_mul_f32 v[92:93], v[92:93], v[96:97] op_sel_hi:[1,0]
	v_mul_f32_e32 v90, v170, v97
	v_pk_mul_f32 v[98:99], v[88:89], v[92:93]
	s_nop 0
	v_sub_f32_e32 v94, v98, v99
	v_mov_b32_e32 v98, v89
	v_mov_b32_e32 v99, v88
	v_pk_mul_f32 v[88:89], v[98:99], v[92:93]
	v_mul_f32_e32 v92, 0.15915494, v90
	v_floor_f32_e32 v92, v92
	v_fma_f32 v90, v90, 0.15915494, -v92
	v_cos_f32_e32 v92, v90
	v_sin_f32_e32 v93, v90
	v_mov_b32_e32 v90, v95
	v_add_f32_e32 v98, v88, v89
	v_pk_mul_f32 v[88:89], v[90:91], v[96:97] op_sel_hi:[1,0]
	s_nop 0
	v_pk_mul_f32 v[90:91], v[92:93], v[88:89]
	s_nop 0
	v_sub_f32_e32 v95, v90, v91
	v_mov_b32_e32 v90, v93
	v_mov_b32_e32 v91, v92
	v_pk_mul_f32 v[88:89], v[90:91], v[88:89]
	v_mov_b32_e32 v90, v84
	v_add_f32_e32 v99, v88, v89
	v_mul_f32_e32 v88, v171, v97
	v_mul_f32_e32 v89, 0.15915494, v88
	v_floor_f32_e32 v89, v89
	v_fma_f32 v89, v88, 0.15915494, -v89
	v_cos_f32_e32 v88, v89
	v_sin_f32_e32 v89, v89
	v_mov_b32_e32 v91, v80
	v_mul_f32_e32 v80, v172, v97
	v_pk_mul_f32 v[90:91], v[90:91], v[96:97] op_sel_hi:[1,0]
	v_mul_f32_e32 v84, 0.15915494, v80
	v_pk_mul_f32 v[92:93], v[88:89], v[90:91]
	v_floor_f32_e32 v84, v84
	v_sub_f32_e32 v101, v92, v93
	v_mov_b32_e32 v92, v89
	v_mov_b32_e32 v93, v88
	v_fma_f32 v80, v80, 0.15915494, -v84
	v_pk_mul_f32 v[88:89], v[92:93], v[90:91]
	v_cos_f32_e32 v90, v80
	v_sin_f32_e32 v91, v80
	v_mov_b32_e32 v80, v85
	v_pk_mul_f32 v[80:81], v[80:81], v[96:97] op_sel_hi:[1,0]
	v_add_f32_e32 v92, v88, v89
	v_pk_mul_f32 v[84:85], v[90:91], v[80:81]
	s_nop 0
	v_sub_f32_e32 v93, v84, v85
	v_mov_b32_e32 v84, v91
	v_mov_b32_e32 v85, v90
	v_pk_mul_f32 v[80:81], v[84:85], v[80:81]
	v_mov_b32_e32 v84, v86
	v_add_f32_e32 v90, v80, v81
	v_mul_f32_e32 v80, v173, v97
	v_mul_f32_e32 v81, 0.15915494, v80
	v_floor_f32_e32 v81, v81
	v_fma_f32 v81, v80, 0.15915494, -v81
	v_cos_f32_e32 v80, v81
	v_sin_f32_e32 v81, v81
	v_mov_b32_e32 v85, v82
	v_pk_mul_f32 v[84:85], v[84:85], v[96:97] op_sel_hi:[1,0]
	v_mul_f32_e32 v82, v174, v97
	v_pk_mul_f32 v[88:89], v[80:81], v[84:85]
	s_nop 0
	v_sub_f32_e32 v86, v88, v89
	v_mov_b32_e32 v88, v81
	v_mov_b32_e32 v89, v80
	v_pk_mul_f32 v[80:81], v[88:89], v[84:85]
	v_mul_f32_e32 v84, 0.15915494, v82
	v_floor_f32_e32 v84, v84
	v_fma_f32 v82, v82, 0.15915494, -v84
	v_cos_f32_e32 v84, v82
	v_sin_f32_e32 v85, v82
	v_mov_b32_e32 v82, v87
	v_add_f32_e32 v88, v80, v81
	v_pk_mul_f32 v[80:81], v[82:83], v[96:97] op_sel_hi:[1,0]
	s_nop 0
	v_pk_mul_f32 v[82:83], v[84:85], v[80:81]
	s_nop 0
	v_sub_f32_e32 v87, v82, v83
	v_mov_b32_e32 v82, v85
	v_mov_b32_e32 v83, v84
	v_pk_mul_f32 v[80:81], v[82:83], v[80:81]
	s_nop 0
	v_add_f32_e32 v89, v80, v81
	v_mad_i64_i32 v[80:81], s[18:19], v154, s44, v[112:113]
	v_lshl_add_u64 v[84:85], v[80:81], 0, v[114:115]
	v_cvt_pk_bf16_f32 v80, v104, v103
	v_cvt_pk_bf16_f32 v81, v94, v95
	v_cvt_pk_bf16_f32 v82, v101, v93
	v_cvt_pk_bf16_f32 v83, v86, v87
	global_store_dwordx4 v[84:85], v[80:83], off
	s_nop 1
	v_cvt_pk_bf16_f32 v80, v102, v100
	v_cvt_pk_bf16_f32 v81, v98, v99
	v_cvt_pk_bf16_f32 v82, v92, v90
	v_cvt_pk_bf16_f32 v83, v88, v89
	global_store_dwordx4 v[84:85], v[80:83], off offset:256
	v_mov_b32_e32 v84, v76
	v_mov_b32_e32 v85, v72
	v_lshl_add_u64 v[80:81], v[152:153], 3, s[4:5]
	s_nop 1
	v_mov_b32_e32 v140, v245
	v_lshlrev_b64 v[82:83], s13, v[140:141]
	v_min_u32_e32 v81, 1, v82
	v_or_b32_e32 v81, v83, v81
	v_cvt_f32_u32_e32 v81, v81
	v_cvt_f32_u32_e32 v80, v244
	v_ldexp_f32 v81, v81, s11
	v_fmac_f32_e32 v81, 0x2f800000, v80
	v_fmamk_f32 v80, v81, 0x39800000, v178
	v_bitop3_b32 v81, v150, s50, 48 bitop3:0xc8
	v_add_u32_e32 v81, 16, v81
	v_cndmask_b32_e32 v81, v163, v81, vcc
	v_cvt_f32_u32_e32 v81, v81
	v_rsq_f32_e32 v80, v80
	v_cmp_gt_i32_e32 vcc, s51, v150
	v_mul_f32_e32 v82, v167, v81
	v_mul_f32_e32 v83, 0.15915494, v82
	v_floor_f32_e32 v83, v83
	v_fma_f32 v83, v82, 0.15915494, -v83
	v_cos_f32_e32 v82, v83
	v_sin_f32_e32 v83, v83
	v_mul_f32_e32 v80, v116, v80
	v_mul_f32_e32 v72, v168, v81
	v_pk_mul_f32 v[84:85], v[84:85], v[80:81] op_sel_hi:[1,0]
	v_mul_f32_e32 v76, 0.15915494, v72
	v_pk_mul_f32 v[86:87], v[82:83], v[84:85]
	v_floor_f32_e32 v76, v76
	v_sub_f32_e32 v88, v86, v87
	v_mov_b32_e32 v86, v83
	v_mov_b32_e32 v87, v82
	v_fma_f32 v72, v72, 0.15915494, -v76
	v_pk_mul_f32 v[82:83], v[86:87], v[84:85]
	v_cos_f32_e32 v84, v72
	v_sin_f32_e32 v85, v72
	v_mov_b32_e32 v72, v77
	v_pk_mul_f32 v[72:73], v[72:73], v[80:81] op_sel_hi:[1,0]
	v_add_f32_e32 v86, v82, v83
	v_pk_mul_f32 v[76:77], v[84:85], v[72:73]
	s_nop 0
	v_sub_f32_e32 v87, v76, v77
	v_mov_b32_e32 v76, v85
	v_mov_b32_e32 v77, v84
	v_pk_mul_f32 v[72:73], v[76:77], v[72:73]
	v_mov_b32_e32 v76, v78
	v_add_f32_e32 v84, v72, v73
; __device__ __forceinline__ u32x4 pack8(const f32x4 a, const f32x4 b) { u32x4 w; w.x = cvt_pk_bf16(a[0], a[1]); w.y = cvt_pk_bf16(a[2], a[3]); w.z = cvt_pk_bf16(b[0], b[1]); w.w = cvt_pk_bf16(b[2], b[3]); return w; }
; __device__ __forceinline__ float row_rstd(const u64* ssq, int r) { return __builtin_amdgcn_rsqf(fx_to_pos(ssq[r]) * (1.0f / 4096.0f) + RMS_EPS); }
;     __device__ __forceinline__ void operator()(const f32x4 (&acc)[2][2][4][2], const Unit& u, int wr, int wc, int fr, int fq) const {
;     ...
;                 for (int m = 0; m < 4; ++m) { const int r = row0 + ai * HALF + m * 16; const float rs = row_rstd(ssq, r) * sc;
;                     const float t = (float)(r < MTOK ? NMETA + (r & (SEQ - 1)) : ((r - MTOK) & 15));
;                     f32x4 o1[2], o2[2];
; #pragma unroll
;                     for (int n = 0; n < 2; ++n)
; #pragma unroll
;                         for (int j = 0; j < 4; ++j) { const float x1 = acc[ai][0][m][n][j] * rs, x2 = acc[ai][1][m][n][j] * rs;
;                             const float ang = t * inv[n][j]; float rev = ang * 0.15915494309189535f; rev = rev - floorf(rev);
;                             const float c = __builtin_amdgcn_cosf(rev), s = __builtin_amdgcn_sinf(rev);
;                             o1[n][j] = x1 * c - x2 * s; o2[n][j] = x1 * s + x2 * c; }
;                     bf16_t* rowp = Z + (size_t)r * RET_IN + col0;
;                     *(u32x4*)(rowp) = pack8(o1[0], o1[1]); *(u32x4*)(rowp + HALF) = pack8(o2[0], o2[1]); }
	v_mul_f32_e32 v72, v169, v81
	v_mul_f32_e32 v73, 0.15915494, v72
	v_floor_f32_e32 v73, v73
	v_fma_f32 v73, v72, 0.15915494, -v73
	v_cos_f32_e32 v72, v73
	v_sin_f32_e32 v73, v73
	v_mov_b32_e32 v77, v74
	v_pk_mul_f32 v[76:77], v[76:77], v[80:81] op_sel_hi:[1,0]
	v_mul_f32_e32 v74, v170, v81
	v_pk_mul_f32 v[82:83], v[72:73], v[76:77]
	s_nop 0
	v_sub_f32_e32 v78, v82, v83
	v_mov_b32_e32 v82, v73
	v_mov_b32_e32 v83, v72
	v_pk_mul_f32 v[72:73], v[82:83], v[76:77]
	v_mul_f32_e32 v76, 0.15915494, v74
	v_floor_f32_e32 v76, v76
	v_fma_f32 v74, v74, 0.15915494, -v76
	v_cos_f32_e32 v76, v74
	v_sin_f32_e32 v77, v74
	v_mov_b32_e32 v74, v79
	v_add_f32_e32 v82, v72, v73
	v_pk_mul_f32 v[72:73], v[74:75], v[80:81] op_sel_hi:[1,0]
	s_nop 0
	v_pk_mul_f32 v[74:75], v[76:77], v[72:73]
	s_nop 0
	v_sub_f32_e32 v79, v74, v75
	v_mov_b32_e32 v74, v77
	v_mov_b32_e32 v75, v76
	v_pk_mul_f32 v[72:73], v[74:75], v[72:73]
	v_mov_b32_e32 v74, v68
	v_add_f32_e32 v83, v72, v73
	v_mul_f32_e32 v72, v171, v81
	v_mul_f32_e32 v73, 0.15915494, v72
	v_floor_f32_e32 v73, v73
	v_fma_f32 v73, v72, 0.15915494, -v73
	v_cos_f32_e32 v72, v73
	v_sin_f32_e32 v73, v73
	v_mov_b32_e32 v75, v64
	v_mul_f32_e32 v64, v172, v81
	v_pk_mul_f32 v[74:75], v[74:75], v[80:81] op_sel_hi:[1,0]
	v_mul_f32_e32 v68, 0.15915494, v64
	v_pk_mul_f32 v[76:77], v[72:73], v[74:75]
	v_floor_f32_e32 v68, v68
	v_sub_f32_e32 v85, v76, v77
	v_mov_b32_e32 v76, v73
	v_mov_b32_e32 v77, v72
	v_fma_f32 v64, v64, 0.15915494, -v68
	v_pk_mul_f32 v[72:73], v[76:77], v[74:75]
	v_cos_f32_e32 v74, v64
	v_sin_f32_e32 v75, v64
	v_mov_b32_e32 v64, v69
	v_pk_mul_f32 v[64:65], v[64:65], v[80:81] op_sel_hi:[1,0]
	v_add_f32_e32 v76, v72, v73
	v_pk_mul_f32 v[68:69], v[74:75], v[64:65]
	s_nop 0
	v_sub_f32_e32 v77, v68, v69
	v_mov_b32_e32 v68, v75
	v_mov_b32_e32 v69, v74
	v_pk_mul_f32 v[64:65], v[68:69], v[64:65]
	v_mov_b32_e32 v68, v70
	v_add_f32_e32 v74, v64, v65
	v_mul_f32_e32 v64, v173, v81
	v_mul_f32_e32 v65, 0.15915494, v64
	v_floor_f32_e32 v65, v65
	v_fma_f32 v65, v64, 0.15915494, -v65
	v_cos_f32_e32 v64, v65
	v_sin_f32_e32 v65, v65
	v_mov_b32_e32 v69, v66
	v_pk_mul_f32 v[68:69], v[68:69], v[80:81] op_sel_hi:[1,0]
	v_mul_f32_e32 v66, v174, v81
	v_pk_mul_f32 v[72:73], v[64:65], v[68:69]
	s_nop 0
	v_sub_f32_e32 v70, v72, v73
	v_mov_b32_e32 v72, v65
	v_mov_b32_e32 v73, v64
	v_pk_mul_f32 v[64:65], v[72:73], v[68:69]
	v_mul_f32_e32 v68, 0.15915494, v66
	v_floor_f32_e32 v68, v68
	v_fma_f32 v66, v66, 0.15915494, -v68
	v_cos_f32_e32 v68, v66
	v_sin_f32_e32 v69, v66
	v_mov_b32_e32 v66, v71
	v_add_f32_e32 v72, v64, v65
	v_pk_mul_f32 v[64:65], v[66:67], v[80:81] op_sel_hi:[1,0]
	s_nop 0
	v_pk_mul_f32 v[66:67], v[68:69], v[64:65]
	s_nop 0
	v_sub_f32_e32 v71, v66, v67
	v_mov_b32_e32 v66, v69
	v_mov_b32_e32 v67, v68
	v_pk_mul_f32 v[64:65], v[66:67], v[64:65]
	s_nop 0
	v_add_f32_e32 v73, v64, v65
	v_mad_i64_i32 v[64:65], s[18:19], v152, s44, v[112:113]
	v_lshl_add_u64 v[68:69], v[64:65], 0, v[114:115]
	v_cvt_pk_bf16_f32 v64, v88, v87
	v_cvt_pk_bf16_f32 v65, v78, v79
	v_cvt_pk_bf16_f32 v66, v85, v77
	v_cvt_pk_bf16_f32 v67, v70, v71
	global_store_dwordx4 v[68:69], v[64:67], off
	s_nop 1
	v_cvt_pk_bf16_f32 v64, v86, v84
	v_cvt_pk_bf16_f32 v65, v82, v83
	v_cvt_pk_bf16_f32 v66, v76, v74
	v_cvt_pk_bf16_f32 v67, v72, v73
	global_store_dwordx4 v[68:69], v[64:67], off offset:256
	v_mov_b32_e32 v68, v60
	v_mov_b32_e32 v69, v56
	s_nop 1
	v_mov_b32_e32 v140, v249
	v_lshlrev_b64 v[66:67], s13, v[140:141]
	v_min_u32_e32 v65, 1, v66
	v_or_b32_e32 v65, v67, v65
	v_cvt_f32_u32_e32 v65, v65
	v_cvt_f32_u32_e32 v64, v248
	v_ldexp_f32 v65, v65, s11
	v_fmac_f32_e32 v65, 0x2f800000, v64
	v_fmamk_f32 v64, v65, 0x39800000, v178
	v_and_or_b32 v65, v183, s45, 16
	v_cndmask_b32_e32 v65, v163, v65, vcc
	v_cvt_f32_u32_e32 v65, v65
	v_rsq_f32_e32 v64, v64
	v_cmp_gt_i32_e32 vcc, s52, v150
	v_mul_f32_e32 v66, v167, v65
	v_mul_f32_e32 v67, 0.15915494, v66
	v_floor_f32_e32 v67, v67
	v_fma_f32 v67, v66, 0.15915494, -v67
	v_cos_f32_e32 v66, v67
	v_sin_f32_e32 v67, v67
	v_mul_f32_e32 v64, v116, v64
	v_mul_f32_e32 v56, v168, v65
	v_pk_mul_f32 v[68:69], v[68:69], v[64:65] op_sel_hi:[1,0]
	v_mul_f32_e32 v60, 0.15915494, v56
	v_pk_mul_f32 v[70:71], v[66:67], v[68:69]
	v_floor_f32_e32 v60, v60
	v_sub_f32_e32 v72, v70, v71
	v_mov_b32_e32 v70, v67
	v_mov_b32_e32 v71, v66
	v_fma_f32 v56, v56, 0.15915494, -v60
	v_pk_mul_f32 v[66:67], v[70:71], v[68:69]
	v_cos_f32_e32 v68, v56
	v_sin_f32_e32 v69, v56
	v_mov_b32_e32 v56, v61
	v_pk_mul_f32 v[56:57], v[56:57], v[64:65] op_sel_hi:[1,0]
	v_add_f32_e32 v70, v66, v67
	v_pk_mul_f32 v[60:61], v[68:69], v[56:57]
	s_nop 0
	v_sub_f32_e32 v71, v60, v61
	v_mov_b32_e32 v60, v69
	v_mov_b32_e32 v61, v68
	v_pk_mul_f32 v[56:57], v[60:61], v[56:57]
	v_mov_b32_e32 v60, v62
	v_add_f32_e32 v68, v56, v57
	v_mul_f32_e32 v56, v169, v65
	v_mul_f32_e32 v57, 0.15915494, v56
	v_floor_f32_e32 v57, v57
	v_fma_f32 v57, v56, 0.15915494, -v57
	v_cos_f32_e32 v56, v57
	v_sin_f32_e32 v57, v57
	v_mov_b32_e32 v61, v58
	v_pk_mul_f32 v[60:61], v[60:61], v[64:65] op_sel_hi:[1,0]
	v_mul_f32_e32 v58, v170, v65
	v_pk_mul_f32 v[66:67], v[56:57], v[60:61]
	s_nop 0
	v_sub_f32_e32 v62, v66, v67
	v_mov_b32_e32 v66, v57
	v_mov_b32_e32 v67, v56
	v_pk_mul_f32 v[56:57], v[66:67], v[60:61]
	v_mul_f32_e32 v60, 0.15915494, v58
	v_floor_f32_e32 v60, v60
	v_fma_f32 v58, v58, 0.15915494, -v60
	v_cos_f32_e32 v60, v58
	v_sin_f32_e32 v61, v58
	v_mov_b32_e32 v58, v63
	v_add_f32_e32 v66, v56, v57
	v_pk_mul_f32 v[56:57], v[58:59], v[64:65] op_sel_hi:[1,0]
	s_nop 0
	v_pk_mul_f32 v[58:59], v[60:61], v[56:57]
	s_nop 0
	v_sub_f32_e32 v63, v58, v59
	v_mov_b32_e32 v58, v61
	v_mov_b32_e32 v59, v60
; __device__ __forceinline__ u32x4 pack8(const f32x4 a, const f32x4 b) { u32x4 w; w.x = cvt_pk_bf16(a[0], a[1]); w.y = cvt_pk_bf16(a[2], a[3]); w.z = cvt_pk_bf16(b[0], b[1]); w.w = cvt_pk_bf16(b[2], b[3]); return w; }
; __device__ __forceinline__ float row_rstd(const u64* ssq, int r) { return __builtin_amdgcn_rsqf(fx_to_pos(ssq[r]) * (1.0f / 4096.0f) + RMS_EPS); }
;     __device__ __forceinline__ void operator()(const f32x4 (&acc)[2][2][4][2], const Unit& u, int wr, int wc, int fr, int fq) const {
;     ...
;                 for (int m = 0; m < 4; ++m) { const int r = row0 + ai * HALF + m * 16; const float rs = row_rstd(ssq, r) * sc;
;                     const float t = (float)(r < MTOK ? NMETA + (r & (SEQ - 1)) : ((r - MTOK) & 15));
;                     f32x4 o1[2], o2[2];
; #pragma unroll
;                     for (int n = 0; n < 2; ++n)
; #pragma unroll
;                         for (int j = 0; j < 4; ++j) { const float x1 = acc[ai][0][m][n][j] * rs, x2 = acc[ai][1][m][n][j] * rs;
;                             const float ang = t * inv[n][j]; float rev = ang * 0.15915494309189535f; rev = rev - floorf(rev);
;                             const float c = __builtin_amdgcn_cosf(rev), s = __builtin_amdgcn_sinf(rev);
;                             o1[n][j] = x1 * c - x2 * s; o2[n][j] = x1 * s + x2 * c; }
;                     bf16_t* rowp = Z + (size_t)r * RET_IN + col0;
;                     *(u32x4*)(rowp) = pack8(o1[0], o1[1]); *(u32x4*)(rowp + HALF) = pack8(o2[0], o2[1]); }
	v_pk_mul_f32 v[56:57], v[58:59], v[56:57]
	v_mov_b32_e32 v58, v52
	v_add_f32_e32 v67, v56, v57
	v_mul_f32_e32 v56, v171, v65
	v_mul_f32_e32 v57, 0.15915494, v56
	v_floor_f32_e32 v57, v57
	v_fma_f32 v57, v56, 0.15915494, -v57
	v_cos_f32_e32 v56, v57
	v_sin_f32_e32 v57, v57
	v_mov_b32_e32 v59, v48
	v_mul_f32_e32 v48, v172, v65
	v_pk_mul_f32 v[58:59], v[58:59], v[64:65] op_sel_hi:[1,0]
	v_mul_f32_e32 v52, 0.15915494, v48
	v_pk_mul_f32 v[60:61], v[56:57], v[58:59]
	v_floor_f32_e32 v52, v52
	v_sub_f32_e32 v69, v60, v61
	v_mov_b32_e32 v60, v57
	v_mov_b32_e32 v61, v56
	v_fma_f32 v48, v48, 0.15915494, -v52
	v_pk_mul_f32 v[56:57], v[60:61], v[58:59]
	v_cos_f32_e32 v58, v48
	v_sin_f32_e32 v59, v48
	v_mov_b32_e32 v48, v53
	v_pk_mul_f32 v[48:49], v[48:49], v[64:65] op_sel_hi:[1,0]
	v_add_f32_e32 v60, v56, v57
	v_pk_mul_f32 v[52:53], v[58:59], v[48:49]
	s_nop 0
	v_sub_f32_e32 v61, v52, v53
	v_mov_b32_e32 v52, v59
	v_mov_b32_e32 v53, v58
	v_pk_mul_f32 v[48:49], v[52:53], v[48:49]
	v_mov_b32_e32 v52, v54
	v_add_f32_e32 v58, v48, v49
	v_mul_f32_e32 v48, v173, v65
	v_mul_f32_e32 v49, 0.15915494, v48
	v_floor_f32_e32 v49, v49
	v_fma_f32 v49, v48, 0.15915494, -v49
	v_cos_f32_e32 v48, v49
	v_sin_f32_e32 v49, v49
	v_mov_b32_e32 v53, v50
	v_pk_mul_f32 v[52:53], v[52:53], v[64:65] op_sel_hi:[1,0]
	v_mul_f32_e32 v50, v174, v65
	v_pk_mul_f32 v[56:57], v[48:49], v[52:53]
	s_nop 0
	v_sub_f32_e32 v54, v56, v57
	v_mov_b32_e32 v56, v49
	v_mov_b32_e32 v57, v48
	v_pk_mul_f32 v[48:49], v[56:57], v[52:53]
	v_mul_f32_e32 v52, 0.15915494, v50
	v_floor_f32_e32 v52, v52
	v_fma_f32 v50, v50, 0.15915494, -v52
	v_cos_f32_e32 v52, v50
	v_sin_f32_e32 v53, v50
	v_mov_b32_e32 v50, v55
	v_add_f32_e32 v56, v48, v49
	v_pk_mul_f32 v[48:49], v[50:51], v[64:65] op_sel_hi:[1,0]
	s_nop 0
	v_pk_mul_f32 v[50:51], v[52:53], v[48:49]
	s_nop 0
	v_sub_f32_e32 v55, v50, v51
	v_mov_b32_e32 v50, v53
	v_mov_b32_e32 v51, v52
	v_pk_mul_f32 v[48:49], v[50:51], v[48:49]
	s_nop 0
	v_add_f32_e32 v57, v48, v49
	v_mad_i64_i32 v[48:49], s[18:19], v183, s44, v[112:113]
	v_lshl_add_u64 v[52:53], v[48:49], 0, v[114:115]
	v_cvt_pk_bf16_f32 v48, v72, v71
	v_cvt_pk_bf16_f32 v49, v62, v63
	v_cvt_pk_bf16_f32 v50, v69, v61
	v_cvt_pk_bf16_f32 v51, v54, v55
	global_store_dwordx4 v[52:53], v[48:51], off
	s_nop 1
	v_cvt_pk_bf16_f32 v48, v70, v68
	v_cvt_pk_bf16_f32 v49, v66, v67
	v_cvt_pk_bf16_f32 v50, v60, v58
	v_cvt_pk_bf16_f32 v51, v56, v57
	global_store_dwordx4 v[52:53], v[48:51], off offset:256
	v_mov_b32_e32 v52, v44
	v_mov_b32_e32 v53, v40
	s_nop 1
	v_mov_b32_e32 v140, v251
	v_lshlrev_b64 v[50:51], s13, v[140:141]
	v_min_u32_e32 v49, 1, v50
	v_or_b32_e32 v49, v51, v49
	v_cvt_f32_u32_e32 v49, v49
	v_cvt_f32_u32_e32 v48, v250
	v_ldexp_f32 v49, v49, s11
	v_fmac_f32_e32 v49, 0x2f800000, v48
	v_fmamk_f32 v48, v49, 0x39800000, v178
	v_and_b32_e32 v49, 0xfdf, v182
	v_add_u32_e32 v49, 16, v49
	v_cndmask_b32_e32 v49, v163, v49, vcc
	v_cvt_f32_u32_e32 v49, v49
	v_rsq_f32_e32 v48, v48
	v_cmp_gt_i32_e32 vcc, s53, v150
	v_mul_f32_e32 v50, v167, v49
	v_mul_f32_e32 v51, 0.15915494, v50
	v_floor_f32_e32 v51, v51
	v_fma_f32 v51, v50, 0.15915494, -v51
	v_cos_f32_e32 v50, v51
	v_sin_f32_e32 v51, v51
	v_mul_f32_e32 v48, v116, v48
	v_mul_f32_e32 v40, v168, v49
	v_pk_mul_f32 v[52:53], v[52:53], v[48:49] op_sel_hi:[1,0]
	v_mul_f32_e32 v44, 0.15915494, v40
	v_pk_mul_f32 v[54:55], v[50:51], v[52:53]
	v_floor_f32_e32 v44, v44
	v_sub_f32_e32 v56, v54, v55
	v_mov_b32_e32 v54, v51
	v_mov_b32_e32 v55, v50
	v_fma_f32 v40, v40, 0.15915494, -v44
	v_pk_mul_f32 v[50:51], v[54:55], v[52:53]
	v_cos_f32_e32 v52, v40
	v_sin_f32_e32 v53, v40
	v_mov_b32_e32 v40, v45
	v_pk_mul_f32 v[40:41], v[40:41], v[48:49] op_sel_hi:[1,0]
	v_add_f32_e32 v54, v50, v51
	v_pk_mul_f32 v[44:45], v[52:53], v[40:41]
	s_nop 0
	v_sub_f32_e32 v55, v44, v45
	v_mov_b32_e32 v44, v53
	v_mov_b32_e32 v45, v52
	v_pk_mul_f32 v[40:41], v[44:45], v[40:41]
	v_mov_b32_e32 v44, v46
	v_add_f32_e32 v52, v40, v41
	v_mul_f32_e32 v40, v169, v49
	v_mul_f32_e32 v41, 0.15915494, v40
	v_floor_f32_e32 v41, v41
	v_fma_f32 v41, v40, 0.15915494, -v41
	v_cos_f32_e32 v40, v41
	v_sin_f32_e32 v41, v41
	v_mov_b32_e32 v45, v42
	v_pk_mul_f32 v[44:45], v[44:45], v[48:49] op_sel_hi:[1,0]
	v_mul_f32_e32 v42, v170, v49
	v_pk_mul_f32 v[50:51], v[40:41], v[44:45]
	s_nop 0
	v_sub_f32_e32 v46, v50, v51
	v_mov_b32_e32 v50, v41
	v_mov_b32_e32 v51, v40
	v_pk_mul_f32 v[40:41], v[50:51], v[44:45]
	v_mul_f32_e32 v44, 0.15915494, v42
	v_floor_f32_e32 v44, v44
	v_fma_f32 v42, v42, 0.15915494, -v44
	v_cos_f32_e32 v44, v42
	v_sin_f32_e32 v45, v42
	v_mov_b32_e32 v42, v47
	v_add_f32_e32 v50, v40, v41
	v_pk_mul_f32 v[40:41], v[42:43], v[48:49] op_sel_hi:[1,0]
	s_nop 0
	v_pk_mul_f32 v[42:43], v[44:45], v[40:41]
	s_nop 0
	v_sub_f32_e32 v47, v42, v43
	v_mov_b32_e32 v42, v45
	v_mov_b32_e32 v43, v44
	v_pk_mul_f32 v[40:41], v[42:43], v[40:41]
	v_mov_b32_e32 v42, v36
	v_add_f32_e32 v51, v40, v41
	v_mul_f32_e32 v40, v171, v49
	v_mul_f32_e32 v41, 0.15915494, v40
	v_floor_f32_e32 v41, v41
	v_fma_f32 v41, v40, 0.15915494, -v41
	v_cos_f32_e32 v40, v41
	v_sin_f32_e32 v41, v41
	v_mov_b32_e32 v43, v32
	v_mul_f32_e32 v32, v172, v49
	v_pk_mul_f32 v[42:43], v[42:43], v[48:49] op_sel_hi:[1,0]
	v_mul_f32_e32 v36, 0.15915494, v32
	v_pk_mul_f32 v[44:45], v[40:41], v[42:43]
	v_floor_f32_e32 v36, v36
	v_sub_f32_e32 v53, v44, v45
	v_mov_b32_e32 v44, v41
	v_mov_b32_e32 v45, v40
	v_fma_f32 v32, v32, 0.15915494, -v36
	v_pk_mul_f32 v[40:41], v[44:45], v[42:43]
	v_cos_f32_e32 v42, v32
	v_sin_f32_e32 v43, v32
	v_mov_b32_e32 v32, v37
	v_pk_mul_f32 v[32:33], v[32:33], v[48:49] op_sel_hi:[1,0]
	v_add_f32_e32 v44, v40, v41
	v_pk_mul_f32 v[36:37], v[42:43], v[32:33]
; __device__ __forceinline__ u32x4 pack8(const f32x4 a, const f32x4 b) { u32x4 w; w.x = cvt_pk_bf16(a[0], a[1]); w.y = cvt_pk_bf16(a[2], a[3]); w.z = cvt_pk_bf16(b[0], b[1]); w.w = cvt_pk_bf16(b[2], b[3]); return w; }
; __device__ __forceinline__ float row_rstd(const u64* ssq, int r) { return __builtin_amdgcn_rsqf(fx_to_pos(ssq[r]) * (1.0f / 4096.0f) + RMS_EPS); }
;     __device__ __forceinline__ void operator()(const f32x4 (&acc)[2][2][4][2], const Unit& u, int wr, int wc, int fr, int fq) const {
;     ...
;                 for (int m = 0; m < 4; ++m) { const int r = row0 + ai * HALF + m * 16; const float rs = row_rstd(ssq, r) * sc;
;                     const float t = (float)(r < MTOK ? NMETA + (r & (SEQ - 1)) : ((r - MTOK) & 15));
;                     f32x4 o1[2], o2[2];
; #pragma unroll
;                     for (int n = 0; n < 2; ++n)
; #pragma unroll
;                         for (int j = 0; j < 4; ++j) { const float x1 = acc[ai][0][m][n][j] * rs, x2 = acc[ai][1][m][n][j] * rs;
;                             const float ang = t * inv[n][j]; float rev = ang * 0.15915494309189535f; rev = rev - floorf(rev);
;                             const float c = __builtin_amdgcn_cosf(rev), s = __builtin_amdgcn_sinf(rev);
;                             o1[n][j] = x1 * c - x2 * s; o2[n][j] = x1 * s + x2 * c; }
;                     bf16_t* rowp = Z + (size_t)r * RET_IN + col0;
;                     *(u32x4*)(rowp) = pack8(o1[0], o1[1]); *(u32x4*)(rowp + HALF) = pack8(o2[0], o2[1]); }
	s_nop 0
	v_sub_f32_e32 v45, v36, v37
	v_mov_b32_e32 v36, v43
	v_mov_b32_e32 v37, v42
	v_pk_mul_f32 v[32:33], v[36:37], v[32:33]
	v_mov_b32_e32 v36, v38
	v_add_f32_e32 v42, v32, v33
	v_mul_f32_e32 v32, v173, v49
	v_mul_f32_e32 v33, 0.15915494, v32
	v_floor_f32_e32 v33, v33
	v_fma_f32 v33, v32, 0.15915494, -v33
	v_cos_f32_e32 v32, v33
	v_sin_f32_e32 v33, v33
	v_mov_b32_e32 v37, v34
	v_pk_mul_f32 v[36:37], v[36:37], v[48:49] op_sel_hi:[1,0]
	v_mul_f32_e32 v34, v174, v49
	v_pk_mul_f32 v[40:41], v[32:33], v[36:37]
	s_nop 0
	v_sub_f32_e32 v38, v40, v41
	v_mov_b32_e32 v40, v33
	v_mov_b32_e32 v41, v32
	v_pk_mul_f32 v[32:33], v[40:41], v[36:37]
	v_mul_f32_e32 v36, 0.15915494, v34
	v_floor_f32_e32 v36, v36
	v_fma_f32 v34, v34, 0.15915494, -v36
	v_cos_f32_e32 v36, v34
	v_sin_f32_e32 v37, v34
	v_mov_b32_e32 v34, v39
	v_add_f32_e32 v40, v32, v33
	v_pk_mul_f32 v[32:33], v[34:35], v[48:49] op_sel_hi:[1,0]
	s_nop 0
	v_pk_mul_f32 v[34:35], v[36:37], v[32:33]
	s_nop 0
	v_sub_f32_e32 v39, v34, v35
	v_mov_b32_e32 v34, v37
	v_mov_b32_e32 v35, v36
	v_pk_mul_f32 v[32:33], v[34:35], v[32:33]
	s_nop 0
	v_add_f32_e32 v41, v32, v33
	v_mad_i64_i32 v[32:33], s[18:19], v182, s44, v[112:113]
	v_lshl_add_u64 v[36:37], v[32:33], 0, v[114:115]
	v_cvt_pk_bf16_f32 v32, v56, v55
	v_cvt_pk_bf16_f32 v33, v46, v47
	v_cvt_pk_bf16_f32 v34, v53, v45
	v_cvt_pk_bf16_f32 v35, v38, v39
	global_store_dwordx4 v[36:37], v[32:35], off
	s_nop 1
	v_cvt_pk_bf16_f32 v32, v54, v52
	v_cvt_pk_bf16_f32 v33, v50, v51
	v_cvt_pk_bf16_f32 v34, v44, v42
	v_cvt_pk_bf16_f32 v35, v40, v41
	global_store_dwordx4 v[36:37], v[32:35], off offset:256
	v_mov_b32_e32 v36, v28
	v_mov_b32_e32 v37, v24
	s_nop 1
	v_mov_b32_e32 v140, v253
	v_lshlrev_b64 v[34:35], s13, v[140:141]
	v_min_u32_e32 v33, 1, v34
	v_or_b32_e32 v33, v35, v33
	v_cvt_f32_u32_e32 v33, v33
	v_cvt_f32_u32_e32 v32, v252
	v_ldexp_f32 v33, v33, s11
	v_fmac_f32_e32 v33, 0x2f800000, v32
	v_fmamk_f32 v32, v33, 0x39800000, v178
	v_and_or_b32 v33, v181, s49, 16
	v_cndmask_b32_e32 v33, v163, v33, vcc
	v_cvt_f32_u32_e32 v33, v33
	v_rsq_f32_e32 v32, v32
	v_cmp_gt_i32_e32 vcc, s54, v150
	v_mul_f32_e32 v34, v167, v33
	v_mul_f32_e32 v35, 0.15915494, v34
	v_floor_f32_e32 v35, v35
	v_fma_f32 v35, v34, 0.15915494, -v35
	v_cos_f32_e32 v34, v35
	v_sin_f32_e32 v35, v35
	v_mul_f32_e32 v32, v116, v32
	v_mul_f32_e32 v24, v168, v33
	v_pk_mul_f32 v[36:37], v[36:37], v[32:33] op_sel_hi:[1,0]
	v_mul_f32_e32 v28, 0.15915494, v24
	v_pk_mul_f32 v[38:39], v[34:35], v[36:37]
	v_floor_f32_e32 v28, v28
	v_sub_f32_e32 v40, v38, v39
	v_mov_b32_e32 v38, v35
	v_mov_b32_e32 v39, v34
	v_fma_f32 v24, v24, 0.15915494, -v28
	v_pk_mul_f32 v[34:35], v[38:39], v[36:37]
	v_cos_f32_e32 v36, v24
	v_sin_f32_e32 v37, v24
	v_mov_b32_e32 v24, v29
	v_pk_mul_f32 v[24:25], v[24:25], v[32:33] op_sel_hi:[1,0]
	v_add_f32_e32 v38, v34, v35
	v_pk_mul_f32 v[28:29], v[36:37], v[24:25]
	s_nop 0
	v_sub_f32_e32 v39, v28, v29
	v_mov_b32_e32 v28, v37
	v_mov_b32_e32 v29, v36
	v_pk_mul_f32 v[24:25], v[28:29], v[24:25]
	v_mov_b32_e32 v28, v30
	v_add_f32_e32 v36, v24, v25
	v_mul_f32_e32 v24, v169, v33
	v_mul_f32_e32 v25, 0.15915494, v24
	v_floor_f32_e32 v25, v25
	v_fma_f32 v25, v24, 0.15915494, -v25
	v_cos_f32_e32 v24, v25
	v_sin_f32_e32 v25, v25
	v_mov_b32_e32 v29, v26
	v_pk_mul_f32 v[28:29], v[28:29], v[32:33] op_sel_hi:[1,0]
	v_mul_f32_e32 v26, v170, v33
	v_pk_mul_f32 v[34:35], v[24:25], v[28:29]
	s_nop 0
	v_sub_f32_e32 v30, v34, v35
	v_mov_b32_e32 v34, v25
	v_mov_b32_e32 v35, v24
	v_pk_mul_f32 v[24:25], v[34:35], v[28:29]
	v_mul_f32_e32 v28, 0.15915494, v26
	v_floor_f32_e32 v28, v28
	v_fma_f32 v26, v26, 0.15915494, -v28
	v_cos_f32_e32 v28, v26
	v_sin_f32_e32 v29, v26
	v_mov_b32_e32 v26, v31
	v_add_f32_e32 v34, v24, v25
	v_pk_mul_f32 v[24:25], v[26:27], v[32:33] op_sel_hi:[1,0]
	s_nop 0
	v_pk_mul_f32 v[26:27], v[28:29], v[24:25]
	s_nop 0
	v_sub_f32_e32 v31, v26, v27
	v_mov_b32_e32 v26, v29
	v_mov_b32_e32 v27, v28
	v_pk_mul_f32 v[24:25], v[26:27], v[24:25]
	v_mov_b32_e32 v26, v20
	v_add_f32_e32 v35, v24, v25
	v_mul_f32_e32 v24, v171, v33
	v_mul_f32_e32 v25, 0.15915494, v24
	v_floor_f32_e32 v25, v25
	v_fma_f32 v25, v24, 0.15915494, -v25
	v_cos_f32_e32 v24, v25
	v_sin_f32_e32 v25, v25
	v_mov_b32_e32 v27, v16
	v_mul_f32_e32 v16, v172, v33
	v_pk_mul_f32 v[26:27], v[26:27], v[32:33] op_sel_hi:[1,0]
	v_mul_f32_e32 v20, 0.15915494, v16
	v_pk_mul_f32 v[28:29], v[24:25], v[26:27]
	v_floor_f32_e32 v20, v20
	v_sub_f32_e32 v37, v28, v29
	v_mov_b32_e32 v28, v25
	v_mov_b32_e32 v29, v24
	v_fma_f32 v16, v16, 0.15915494, -v20
	v_pk_mul_f32 v[24:25], v[28:29], v[26:27]
	v_cos_f32_e32 v26, v16
	v_sin_f32_e32 v27, v16
	v_mov_b32_e32 v16, v21
	v_pk_mul_f32 v[16:17], v[16:17], v[32:33] op_sel_hi:[1,0]
	v_add_f32_e32 v28, v24, v25
	v_pk_mul_f32 v[20:21], v[26:27], v[16:17]
	s_nop 0
	v_sub_f32_e32 v29, v20, v21
	v_mov_b32_e32 v20, v27
	v_mov_b32_e32 v21, v26
	v_pk_mul_f32 v[16:17], v[20:21], v[16:17]
	v_mov_b32_e32 v20, v22
	v_add_f32_e32 v26, v16, v17
	v_mul_f32_e32 v16, v173, v33
	v_mul_f32_e32 v17, 0.15915494, v16
	v_floor_f32_e32 v17, v17
	v_fma_f32 v17, v16, 0.15915494, -v17
	v_cos_f32_e32 v16, v17
	v_sin_f32_e32 v17, v17
	v_mov_b32_e32 v21, v18
	v_pk_mul_f32 v[20:21], v[20:21], v[32:33] op_sel_hi:[1,0]
	v_mul_f32_e32 v18, v174, v33
	v_pk_mul_f32 v[24:25], v[16:17], v[20:21]
	s_nop 0
	v_sub_f32_e32 v22, v24, v25
	v_mov_b32_e32 v24, v17
	v_mov_b32_e32 v25, v16
	v_pk_mul_f32 v[16:17], v[24:25], v[20:21]
	v_mul_f32_e32 v20, 0.15915494, v18
	v_floor_f32_e32 v20, v20
	v_fma_f32 v18, v18, 0.15915494, -v20
; __device__ __forceinline__ u32x4 pack8(const f32x4 a, const f32x4 b) { u32x4 w; w.x = cvt_pk_bf16(a[0], a[1]); w.y = cvt_pk_bf16(a[2], a[3]); w.z = cvt_pk_bf16(b[0], b[1]); w.w = cvt_pk_bf16(b[2], b[3]); return w; }
; __device__ __forceinline__ float row_rstd(const u64* ssq, int r) { return __builtin_amdgcn_rsqf(fx_to_pos(ssq[r]) * (1.0f / 4096.0f) + RMS_EPS); }
;     __device__ __forceinline__ void operator()(const f32x4 (&acc)[2][2][4][2], const Unit& u, int wr, int wc, int fr, int fq) const {
;     ...
;                 for (int m = 0; m < 4; ++m) { const int r = row0 + ai * HALF + m * 16; const float rs = row_rstd(ssq, r) * sc;
;                     const float t = (float)(r < MTOK ? NMETA + (r & (SEQ - 1)) : ((r - MTOK) & 15));
;                     f32x4 o1[2], o2[2];
; #pragma unroll
;                     for (int n = 0; n < 2; ++n)
; #pragma unroll
;                         for (int j = 0; j < 4; ++j) { const float x1 = acc[ai][0][m][n][j] * rs, x2 = acc[ai][1][m][n][j] * rs;
;                             const float ang = t * inv[n][j]; float rev = ang * 0.15915494309189535f; rev = rev - floorf(rev);
;                             const float c = __builtin_amdgcn_cosf(rev), s = __builtin_amdgcn_sinf(rev);
;                             o1[n][j] = x1 * c - x2 * s; o2[n][j] = x1 * s + x2 * c; }
;                     bf16_t* rowp = Z + (size_t)r * RET_IN + col0;
;                     *(u32x4*)(rowp) = pack8(o1[0], o1[1]); *(u32x4*)(rowp + HALF) = pack8(o2[0], o2[1]); }
	v_cos_f32_e32 v20, v18
	v_sin_f32_e32 v21, v18
	v_mov_b32_e32 v18, v23
	v_add_f32_e32 v24, v16, v17
	v_pk_mul_f32 v[16:17], v[18:19], v[32:33] op_sel_hi:[1,0]
	s_nop 0
	v_pk_mul_f32 v[18:19], v[20:21], v[16:17]
	s_nop 0
	v_sub_f32_e32 v23, v18, v19
	v_mov_b32_e32 v18, v21
	v_mov_b32_e32 v19, v20
	v_pk_mul_f32 v[16:17], v[18:19], v[16:17]
	s_nop 0
	v_add_f32_e32 v25, v16, v17
	v_mad_i64_i32 v[16:17], s[18:19], v181, s44, v[112:113]
	v_lshl_add_u64 v[20:21], v[16:17], 0, v[114:115]
	v_cvt_pk_bf16_f32 v16, v40, v39
	v_cvt_pk_bf16_f32 v17, v30, v31
	v_cvt_pk_bf16_f32 v18, v37, v29
	v_cvt_pk_bf16_f32 v19, v22, v23
	global_store_dwordx4 v[20:21], v[16:19], off
	s_nop 1
	v_cvt_pk_bf16_f32 v16, v38, v36
	v_cvt_pk_bf16_f32 v17, v34, v35
	v_cvt_pk_bf16_f32 v18, v28, v26
	v_cvt_pk_bf16_f32 v19, v24, v25
	global_store_dwordx4 v[20:21], v[16:19], off offset:256
	v_mov_b32_e32 v20, v12
	v_mov_b32_e32 v21, v8
	s_nop 1
	v_mov_b32_e32 v140, v255
	v_lshlrev_b64 v[18:19], s13, v[140:141]
	v_min_u32_e32 v17, 1, v18
	v_or_b32_e32 v17, v19, v17
	v_cvt_f32_u32_e32 v17, v17
	v_cvt_f32_u32_e32 v16, v254
	v_ldexp_f32 v17, v17, s11
	v_fmac_f32_e32 v17, 0x2f800000, v16
	v_fmamk_f32 v16, v17, 0x39800000, v178
	v_and_b32_e32 v17, 0xfff, v180
	v_add_u32_e32 v17, 16, v17
	v_cndmask_b32_e32 v17, v163, v17, vcc
	v_cvt_f32_u32_e32 v17, v17
	v_rsq_f32_e32 v16, v16
	v_mul_f32_e32 v18, v167, v17
	v_mul_f32_e32 v19, 0.15915494, v18
	v_floor_f32_e32 v19, v19
	v_fma_f32 v19, v18, 0.15915494, -v19
	v_cos_f32_e32 v18, v19
	v_sin_f32_e32 v19, v19
	v_mul_f32_e32 v16, v116, v16
	v_mul_f32_e32 v8, v168, v17
	v_pk_mul_f32 v[20:21], v[20:21], v[16:17] op_sel_hi:[1,0]
	v_mul_f32_e32 v12, 0.15915494, v8
	v_pk_mul_f32 v[22:23], v[18:19], v[20:21]
	v_floor_f32_e32 v12, v12
	v_sub_f32_e32 v24, v22, v23
	v_mov_b32_e32 v22, v19
	v_mov_b32_e32 v23, v18
	v_fma_f32 v8, v8, 0.15915494, -v12
	v_pk_mul_f32 v[18:19], v[22:23], v[20:21]
	v_cos_f32_e32 v20, v8
	v_sin_f32_e32 v21, v8
	v_mov_b32_e32 v8, v13
	v_pk_mul_f32 v[8:9], v[8:9], v[16:17] op_sel_hi:[1,0]
	v_add_f32_e32 v22, v18, v19
	v_pk_mul_f32 v[12:13], v[20:21], v[8:9]
	s_nop 0
	v_sub_f32_e32 v23, v12, v13
	v_mov_b32_e32 v12, v21
	v_mov_b32_e32 v13, v20
	v_pk_mul_f32 v[8:9], v[12:13], v[8:9]
	v_mov_b32_e32 v12, v14
	v_add_f32_e32 v20, v8, v9
	v_mul_f32_e32 v8, v169, v17
	v_mul_f32_e32 v9, 0.15915494, v8
	v_floor_f32_e32 v9, v9
	v_fma_f32 v9, v8, 0.15915494, -v9
	v_cos_f32_e32 v8, v9
	v_sin_f32_e32 v9, v9
	v_mov_b32_e32 v13, v10
	v_pk_mul_f32 v[12:13], v[12:13], v[16:17] op_sel_hi:[1,0]
	v_mul_f32_e32 v10, v170, v17
	v_pk_mul_f32 v[18:19], v[8:9], v[12:13]
	s_nop 0
	v_sub_f32_e32 v14, v18, v19
	v_mov_b32_e32 v18, v9
	v_mov_b32_e32 v19, v8
	v_pk_mul_f32 v[8:9], v[18:19], v[12:13]
	v_mul_f32_e32 v12, 0.15915494, v10
	v_floor_f32_e32 v12, v12
	v_fma_f32 v10, v10, 0.15915494, -v12
	v_cos_f32_e32 v12, v10
	v_sin_f32_e32 v13, v10
	v_mov_b32_e32 v10, v15
	v_add_f32_e32 v18, v8, v9
	v_pk_mul_f32 v[8:9], v[10:11], v[16:17] op_sel_hi:[1,0]
	s_nop 0
	v_pk_mul_f32 v[10:11], v[12:13], v[8:9]
	s_nop 0
	v_sub_f32_e32 v15, v10, v11
	v_mov_b32_e32 v10, v13
	v_mov_b32_e32 v11, v12
	v_pk_mul_f32 v[8:9], v[10:11], v[8:9]
	v_mov_b32_e32 v10, v4
	v_add_f32_e32 v19, v8, v9
	v_mul_f32_e32 v8, v171, v17
	v_mul_f32_e32 v9, 0.15915494, v8
	v_floor_f32_e32 v9, v9
	v_fma_f32 v9, v8, 0.15915494, -v9
	v_cos_f32_e32 v8, v9
	v_sin_f32_e32 v9, v9
	v_mov_b32_e32 v11, v0
	v_mul_f32_e32 v0, v172, v17
	v_pk_mul_f32 v[10:11], v[10:11], v[16:17] op_sel_hi:[1,0]
	v_mul_f32_e32 v4, 0.15915494, v0
	v_pk_mul_f32 v[12:13], v[8:9], v[10:11]
	v_floor_f32_e32 v4, v4
	v_sub_f32_e32 v21, v12, v13
	v_mov_b32_e32 v12, v9
	v_mov_b32_e32 v13, v8
	v_fma_f32 v0, v0, 0.15915494, -v4
	v_pk_mul_f32 v[8:9], v[12:13], v[10:11]
	v_cos_f32_e32 v10, v0
	v_sin_f32_e32 v11, v0
	v_mov_b32_e32 v0, v5
	v_pk_mul_f32 v[0:1], v[0:1], v[16:17] op_sel_hi:[1,0]
	v_add_f32_e32 v12, v8, v9
	v_pk_mul_f32 v[4:5], v[10:11], v[0:1]
	s_nop 0
	v_sub_f32_e32 v13, v4, v5
	v_mov_b32_e32 v4, v11
	v_mov_b32_e32 v5, v10
	v_pk_mul_f32 v[0:1], v[4:5], v[0:1]
	v_mov_b32_e32 v4, v6
	v_add_f32_e32 v10, v0, v1
	v_mul_f32_e32 v0, v173, v17
	v_mul_f32_e32 v1, 0.15915494, v0
	v_floor_f32_e32 v1, v1
	v_fma_f32 v1, v0, 0.15915494, -v1
	v_cos_f32_e32 v0, v1
	v_sin_f32_e32 v1, v1
	v_mov_b32_e32 v5, v2
	v_pk_mul_f32 v[4:5], v[4:5], v[16:17] op_sel_hi:[1,0]
	v_mul_f32_e32 v2, v174, v17
	v_pk_mul_f32 v[8:9], v[0:1], v[4:5]
	s_nop 0
	v_sub_f32_e32 v6, v8, v9
	v_mov_b32_e32 v8, v1
	v_mov_b32_e32 v9, v0
	v_pk_mul_f32 v[0:1], v[8:9], v[4:5]
	v_mul_f32_e32 v4, 0.15915494, v2
	v_floor_f32_e32 v4, v4
	v_fma_f32 v2, v2, 0.15915494, -v4
	v_cos_f32_e32 v4, v2
	v_sin_f32_e32 v5, v2
	v_mov_b32_e32 v2, v7
	v_add_f32_e32 v8, v0, v1
	v_pk_mul_f32 v[0:1], v[2:3], v[16:17] op_sel_hi:[1,0]
	s_nop 0
	v_pk_mul_f32 v[2:3], v[4:5], v[0:1]
	s_nop 0
	v_sub_f32_e32 v7, v2, v3
	v_mov_b32_e32 v2, v5
	v_mov_b32_e32 v3, v4
	v_pk_mul_f32 v[0:1], v[2:3], v[0:1]
	s_nop 0
	v_add_f32_e32 v4, v0, v1
	v_mad_i64_i32 v[0:1], s[18:19], v180, s44, v[112:113]
	v_lshl_add_u64 v[160:161], v[0:1], 0, v[114:115]
	v_cvt_pk_bf16_f32 v0, v24, v23
	v_cvt_pk_bf16_f32 v1, v14, v15
	v_cvt_pk_bf16_f32 v2, v21, v13
	v_cvt_pk_bf16_f32 v3, v6, v7
	global_store_dwordx4 v[160:161], v[0:3], off
	v_cvt_pk_bf16_f32 v128, v22, v20
	v_cvt_pk_bf16_f32 v129, v18, v19
	v_cvt_pk_bf16_f32 v130, v12, v10
	v_cvt_pk_bf16_f32 v131, v8, v4
	s_andn2_b64 vcc, exec, s[0:1]
	s_mov_b64 s[0:1], -1
	global_store_dwordx4 v[160:161], v[128:131], off offset:256
	s_cbranch_vccnz .LBB0_1246

; __device__ __forceinline__ float row_rstd(const u64* ssq, int r) { return __builtin_amdgcn_rsqf(fx_to_pos(ssq[r]) * (1.0f / 4096.0f) + RMS_EPS); }
;     __device__ __forceinline__ void operator()(const f32x4 (&acc)[2][2][4][2], const Unit& u, int wr, int wc, int fr, int fq) const {
;     ...
;             for (int m = 0; m < 4; ++m) { const int r = row0 + ai * HALF + m * 16; const float rs = row_rstd(ssq, r); f32x4 o[2];
; template <class Epi, class Sched, bool ALIGN_EPI = false, bool SP2 = false>
; __device__ __forceinline__ void gemm_phase(PG8_LAS unsigned char* lds, const Gemm g, const Sched& S, const Epi& E, const int wid) {
;     ...
;         for (int a = 0; a < 2; ++a)
; #pragma unroll
;             for (int b = 0; b < 2; ++b)
; #pragma unroll
;                 for (int m = 0; m < 4; ++m)
; #pragma unroll
;                     for (int n = 0; n < 2; ++n) acc[a][b][m][n] = (f32x4){0.f, 0.f, 0.f, 0.f};
;         cur = nxt; cA = nA; cB = nB; ++ui; nt = cur.kn;
.LBB0_1763:
	v_lshl_add_u32 v244, s20, 8, v151
	v_ashrrev_i32_e32 v245, 31, v244
	v_lshl_add_u64 v[244:245], v[244:245], 3, s[4:5]
	global_load_dwordx2 v[228:229], v[244:245], off
	global_load_dwordx2 v[230:231], v[244:245], off offset:128
	global_load_dwordx2 v[232:233], v[244:245], off offset:256
	global_load_dwordx2 v[234:235], v[244:245], off offset:384
	global_load_dwordx2 v[236:237], v[244:245], off offset:1024
	global_load_dwordx2 v[238:239], v[244:245], off offset:1152
	global_load_dwordx2 v[240:241], v[244:245], off offset:1280
	global_load_dwordx2 v[242:243], v[244:245], off offset:1408
	s_ashr_i32 s15, s14, 31
	s_lshl_b64 s[16:17], s[14:15], 21
	s_add_u32 s16, s78, s16
	s_addc_u32 s17, s79, s17
	s_and_b64 s[18:19], s[0:1], exec
	s_cselect_b32 s15, s17, s23
	s_cselect_b32 s47, s16, s22
	s_ashr_i32 s13, s12, 31
	s_lshl_b64 s[18:19], s[12:13], 21
	s_add_u32 s18, s38, s18
	s_addc_u32 s19, s39, s19
	s_and_b64 s[26:27], s[0:1], exec
	s_cselect_b32 s13, s19, s25
	s_cselect_b32 s48, s18, s24
	s_add_u32 s22, s22, 0x100080
	s_addc_u32 s23, s23, 0
	s_add_u32 s49, s24, 0x100
	v_mov_b32_e32 v0, 0
	s_addc_u32 s50, s25, 0
	s_mov_b32 s51, -2
	v_mov_b32_e32 v1, v0
	v_mov_b32_e32 v2, v0
	v_mov_b32_e32 v3, v0
	v_mov_b32_e32 v4, v0
	v_mov_b32_e32 v5, v0
	v_mov_b32_e32 v6, v0
	v_mov_b32_e32 v7, v0
	v_mov_b32_e32 v16, v0
	v_mov_b32_e32 v17, v0
	v_mov_b32_e32 v18, v0
	v_mov_b32_e32 v19, v0
	v_mov_b32_e32 v20, v0
	v_mov_b32_e32 v21, v0
	v_mov_b32_e32 v22, v0
	v_mov_b32_e32 v23, v0
	v_mov_b32_e32 v32, v0
	v_mov_b32_e32 v33, v0
	v_mov_b32_e32 v34, v0
	v_mov_b32_e32 v35, v0
	v_mov_b32_e32 v36, v0
	v_mov_b32_e32 v37, v0
	v_mov_b32_e32 v38, v0
	v_mov_b32_e32 v39, v0
	v_mov_b32_e32 v48, v0
	v_mov_b32_e32 v49, v0
	v_mov_b32_e32 v50, v0
	v_mov_b32_e32 v51, v0
	v_mov_b32_e32 v52, v0
	v_mov_b32_e32 v53, v0
	v_mov_b32_e32 v54, v0
	v_mov_b32_e32 v55, v0
	v_mov_b32_e32 v8, v0
	v_mov_b32_e32 v9, v0
	v_mov_b32_e32 v10, v0
	v_mov_b32_e32 v11, v0
	v_mov_b32_e32 v12, v0
	v_mov_b32_e32 v13, v0
	v_mov_b32_e32 v14, v0
	v_mov_b32_e32 v15, v0
	v_mov_b32_e32 v24, v0
	v_mov_b32_e32 v25, v0
	v_mov_b32_e32 v26, v0
	v_mov_b32_e32 v27, v0
	v_mov_b32_e32 v28, v0
	v_mov_b32_e32 v29, v0
	v_mov_b32_e32 v30, v0
	v_mov_b32_e32 v31, v0
	v_mov_b32_e32 v40, v0
	v_mov_b32_e32 v41, v0
	v_mov_b32_e32 v42, v0
	v_mov_b32_e32 v43, v0
	v_mov_b32_e32 v44, v0
	v_mov_b32_e32 v45, v0
	v_mov_b32_e32 v46, v0
	v_mov_b32_e32 v47, v0
	v_mov_b32_e32 v56, v0
	v_mov_b32_e32 v57, v0
	v_mov_b32_e32 v58, v0
	v_mov_b32_e32 v59, v0
	v_mov_b32_e32 v60, v0
	v_mov_b32_e32 v61, v0
	v_mov_b32_e32 v62, v0
	v_mov_b32_e32 v63, v0
	v_mov_b32_e32 v64, v0
	v_mov_b32_e32 v65, v0
	v_mov_b32_e32 v66, v0
	v_mov_b32_e32 v67, v0
	v_mov_b32_e32 v68, v0
	v_mov_b32_e32 v69, v0
	v_mov_b32_e32 v70, v0
	v_mov_b32_e32 v71, v0
	v_mov_b32_e32 v80, v0
	v_mov_b32_e32 v81, v0
	v_mov_b32_e32 v82, v0
	v_mov_b32_e32 v83, v0
	v_mov_b32_e32 v84, v0
	v_mov_b32_e32 v85, v0
	v_mov_b32_e32 v86, v0
	v_mov_b32_e32 v87, v0
	v_mov_b32_e32 v96, v0
	v_mov_b32_e32 v97, v0
	v_mov_b32_e32 v98, v0
	v_mov_b32_e32 v99, v0
	v_mov_b32_e32 v100, v0
	v_mov_b32_e32 v101, v0
	v_mov_b32_e32 v102, v0
	v_mov_b32_e32 v103, v0
	v_mov_b32_e32 v112, v0
	v_mov_b32_e32 v113, v0
	v_mov_b32_e32 v114, v0
	v_mov_b32_e32 v115, v0
	v_mov_b32_e32 v116, v0
	v_mov_b32_e32 v117, v0
	v_mov_b32_e32 v118, v0
	v_mov_b32_e32 v119, v0
	v_mov_b32_e32 v72, v0
	v_mov_b32_e32 v73, v0
	v_mov_b32_e32 v74, v0
	v_mov_b32_e32 v75, v0
	v_mov_b32_e32 v76, v0
	v_mov_b32_e32 v77, v0
	v_mov_b32_e32 v78, v0
	v_mov_b32_e32 v79, v0
	v_mov_b32_e32 v88, v0
	v_mov_b32_e32 v89, v0
	v_mov_b32_e32 v90, v0
	v_mov_b32_e32 v91, v0
	v_mov_b32_e32 v92, v0
	v_mov_b32_e32 v93, v0
	v_mov_b32_e32 v94, v0
	v_mov_b32_e32 v95, v0
	v_mov_b32_e32 v104, v0
	v_mov_b32_e32 v105, v0
	v_mov_b32_e32 v106, v0
	v_mov_b32_e32 v107, v0
	v_mov_b32_e32 v108, v0
	v_mov_b32_e32 v109, v0
	v_mov_b32_e32 v110, v0
	v_mov_b32_e32 v111, v0
	v_mov_b32_e32 v120, v0
	v_mov_b32_e32 v121, v0
	v_mov_b32_e32 v122, v0
	v_mov_b32_e32 v123, v0
	v_mov_b32_e32 v124, v0
	v_mov_b32_e32 v125, v0
	v_mov_b32_e32 v126, v0
	v_mov_b32_e32 v127, v0

; __device__ __forceinline__ u32x4 pack8(const f32x4 a, const f32x4 b) { u32x4 w; w.x = cvt_pk_bf16(a[0], a[1]); w.y = cvt_pk_bf16(a[2], a[3]); w.z = cvt_pk_bf16(b[0], b[1]); w.w = cvt_pk_bf16(b[2], b[3]); return w; }
; __device__ __forceinline__ float row_rstd(const u64* ssq, int r) { return __builtin_amdgcn_rsqf(fx_to_pos(ssq[r]) * (1.0f / 4096.0f) + RMS_EPS); }
;     __device__ __forceinline__ void operator()(const f32x4 (&acc)[2][2][4][2], const Unit& u, int wr, int wc, int fr, int fq) const {
;     ...
;             for (int m = 0; m < 4; ++m) { const int r = row0 + ai * HALF + m * 16; const float rs = row_rstd(ssq, r); f32x4 o[2];
; #pragma unroll
;                 for (int n = 0; n < 2; ++n)
; #pragma unroll
;                     for (int j = 0; j < 4; ++j) { const float g = acc[ai][0][m][n][j] * rs, uu = acc[ai][1][m][n][j] * rs;
;                         o[n][j] = g * uu * __builtin_amdgcn_rcpf(1.0f + __expf(-g)); }
;                 *(u32x4*)(HID + (size_t)r * DFF + col0) = pack8(o[0], o[1]); }
.LBB0_1767:
	v_lshl_add_u32 v146, s20, 8, v151
	v_ashrrev_i32_e32 v147, 31, v146
	v_lshl_add_u64 v[148:149], v[146:147], 3, s[4:5]
	v_mov_b32_e32 v164, v122
	v_mov_b32_e32 v165, v114
	v_mov_b32_e32 v114, v123
	s_sub_i32 s13, 32, s45
	v_mov_b32_e32 v162, v124
	v_mov_b32_e32 v163, v116
	v_mov_b32_e32 v116, v125
	v_mov_b32_e32 v124, v126
	v_mov_b32_e32 v125, v118
	v_mov_b32_e32 v118, v127
	v_mov_b32_e32 v126, v120
	v_mov_b32_e32 v127, v112
	v_mov_b32_e32 v112, v121
	v_lshl_add_u32 v160, s46, 7, v153
	v_mov_b64_e32 v[120:121], s[80:81]
	v_ashrrev_i32_e32 v161, 31, v160
	v_mad_i64_i32 v[166:167], s[22:23], v146, s44, v[120:121]
	s_andn2_b64 vcc, exec, s[0:1]
	s_mov_b64 s[0:1], -1
	v_mov_b32_e32 v136, v229
	v_lshlrev_b64 v[122:123], s45, v[136:137]
	v_min_u32_e32 v122, 1, v122
	v_or_b32_e32 v122, v123, v122
	v_cvt_f32_u32_e32 v136, v122
	v_cvt_f32_u32_e32 v147, v228
	v_or_b32_e32 v158, 16, v146
	v_lshlrev_b64 v[122:123], 1, v[160:161]
	v_ldexp_f32 v136, v136, s13
	v_fmac_f32_e32 v136, 0x2f800000, v147
	v_fmamk_f32 v136, v136, 0x39800000, v157
	v_rsq_f32_e32 v136, v136
	v_ashrrev_i32_e32 v159, 31, v158
	v_lshl_add_u64 v[160:161], v[166:167], 0, v[122:123]
	v_lshl_add_u64 v[166:167], v[158:159], 3, s[4:5]
	v_pk_mul_f32 v[114:115], v[114:115], v[136:137] op_sel_hi:[1,0]
	v_pk_mul_f32 v[162:163], v[162:163], v[136:137] op_sel_hi:[1,0]
	v_pk_mul_f32 v[116:117], v[116:117], v[136:137] op_sel_hi:[1,0]
	v_pk_mul_f32 v[124:125], v[124:125], v[136:137] op_sel_hi:[1,0]
	v_pk_mul_f32 v[118:119], v[118:119], v[136:137] op_sel_hi:[1,0]
	v_pk_mul_f32 v[126:127], v[126:127], v[136:137] op_sel_hi:[1,0]
	v_pk_mul_f32 v[112:113], v[112:113], v[136:137] op_sel_hi:[1,0]
	v_pk_mul_f32 v[164:165], v[164:165], v[136:137] op_sel_hi:[1,0]
	v_mul_f32_e32 v115, v114, v115
	v_mul_f32_e32 v114, 0xbfb8aa3b, v114
	v_mul_f32_e32 v136, v162, v163
	v_mul_f32_e32 v147, 0xbfb8aa3b, v162
	v_mul_f32_e32 v117, v116, v117
	v_mul_f32_e32 v116, 0xbfb8aa3b, v116
	v_mul_f32_e32 v125, v124, v125
	v_mul_f32_e32 v124, 0xbfb8aa3b, v124
	v_mul_f32_e32 v119, v118, v119
	v_mul_f32_e32 v118, 0xbfb8aa3b, v118
	v_mul_f32_e32 v127, v126, v127
	v_mul_f32_e32 v126, 0xbfb8aa3b, v126
	v_mul_f32_e32 v113, v112, v113
	v_mul_f32_e32 v112, 0xbfb8aa3b, v112
	v_mul_f32_e32 v162, 0xbfb8aa3b, v164
	v_exp_f32_e32 v114, v114
	v_exp_f32_e32 v147, v147
	v_exp_f32_e32 v116, v116
	v_exp_f32_e32 v124, v124
	v_exp_f32_e32 v118, v118
	v_exp_f32_e32 v126, v126
	v_exp_f32_e32 v112, v112
	v_exp_f32_e32 v162, v162
	v_add_f32_e32 v114, 1.0, v114
	v_add_f32_e32 v147, 1.0, v147
	v_add_f32_e32 v116, 1.0, v116
	v_add_f32_e32 v124, 1.0, v124
	v_add_f32_e32 v118, 1.0, v118
	v_add_f32_e32 v126, 1.0, v126
	v_add_f32_e32 v112, 1.0, v112
	v_add_f32_e32 v162, 1.0, v162
	v_rcp_f32_e32 v114, v114
	v_rcp_f32_e32 v147, v147
	v_rcp_f32_e32 v116, v116
	v_rcp_f32_e32 v124, v124
	v_rcp_f32_e32 v118, v118
	v_rcp_f32_e32 v126, v126
	v_rcp_f32_e32 v112, v112
	v_rcp_f32_e32 v162, v162
	v_mul_f32_e32 v159, v164, v165
	v_mul_f32_e32 v115, v115, v114
	v_mul_f32_e32 v136, v136, v147
	v_mul_f32_e32 v116, v117, v116
	v_mul_f32_e32 v117, v125, v124
	v_mul_f32_e32 v118, v119, v118
	v_mul_f32_e32 v119, v127, v126
	v_mul_f32_e32 v124, v113, v112
	v_mul_f32_e32 v125, v159, v162
	v_cvt_pk_bf16_f32 v112, v136, v116
	v_cvt_pk_bf16_f32 v113, v117, v118
	v_cvt_pk_bf16_f32 v114, v119, v124
	v_cvt_pk_bf16_f32 v115, v125, v115
	global_store_dwordx4 v[160:161], v[112:115], off
	s_nop 1
	v_mov_b32_e32 v136, v231
	v_lshlrev_b64 v[116:117], s45, v[136:137]
	v_mov_b32_e32 v115, v100
	v_mov_b32_e32 v100, v109
	v_mov_b32_e32 v109, v102
	v_mov_b32_e32 v102, v111
	v_mov_b32_e32 v111, v96
	v_mov_b32_e32 v96, v105
	v_mov_b32_e32 v105, v98
	v_mov_b32_e32 v98, v107
	v_min_u32_e32 v107, 1, v116
	v_or_b32_e32 v107, v117, v107
	v_cvt_f32_u32_e32 v107, v107
	v_cvt_f32_u32_e32 v116, v230
	v_mov_b32_e32 v114, v108
	v_mov_b32_e32 v108, v110
	v_ldexp_f32 v107, v107, s13
	v_fmac_f32_e32 v107, 0x2f800000, v116
	v_fmamk_f32 v107, v107, 0x39800000, v157
	v_rsq_f32_e32 v116, v107
	v_mov_b32_e32 v110, v104
	v_mov_b32_e32 v104, v106
	v_or_b32_e32 v106, 32, v146
	v_pk_mul_f32 v[98:99], v[98:99], v[116:117] op_sel_hi:[1,0]
	v_ashrrev_i32_e32 v107, 31, v106
	v_pk_mul_f32 v[114:115], v[114:115], v[116:117] op_sel_hi:[1,0]
	v_pk_mul_f32 v[100:101], v[100:101], v[116:117] op_sel_hi:[1,0]
	v_pk_mul_f32 v[108:109], v[108:109], v[116:117] op_sel_hi:[1,0]
	v_pk_mul_f32 v[102:103], v[102:103], v[116:117] op_sel_hi:[1,0]
	v_pk_mul_f32 v[110:111], v[110:111], v[116:117] op_sel_hi:[1,0]
	v_pk_mul_f32 v[96:97], v[96:97], v[116:117] op_sel_hi:[1,0]
	v_pk_mul_f32 v[104:105], v[104:105], v[116:117] op_sel_hi:[1,0]
	v_mul_f32_e32 v99, v98, v99
	v_mul_f32_e32 v98, 0xbfb8aa3b, v98
	v_lshl_add_u64 v[118:119], v[106:107], 3, s[4:5]
	v_mul_f32_e32 v107, v114, v115
	v_mul_f32_e32 v114, 0xbfb8aa3b, v114
	v_mul_f32_e32 v101, v100, v101
	v_mul_f32_e32 v100, 0xbfb8aa3b, v100
	v_mul_f32_e32 v109, v108, v109
	v_mul_f32_e32 v108, 0xbfb8aa3b, v108
	v_mul_f32_e32 v103, v102, v103
	v_mul_f32_e32 v102, 0xbfb8aa3b, v102
	v_mul_f32_e32 v111, v110, v111
	v_mul_f32_e32 v110, 0xbfb8aa3b, v110
	v_mul_f32_e32 v97, v96, v97
	v_mul_f32_e32 v96, 0xbfb8aa3b, v96
	v_mul_f32_e32 v105, v104, v105
	v_mul_f32_e32 v104, 0xbfb8aa3b, v104
	v_exp_f32_e32 v98, v98
	v_exp_f32_e32 v114, v114
	v_exp_f32_e32 v100, v100
	v_exp_f32_e32 v108, v108
	v_exp_f32_e32 v102, v102
	v_exp_f32_e32 v110, v110
	v_exp_f32_e32 v96, v96
	v_exp_f32_e32 v104, v104
	v_add_f32_e32 v98, 1.0, v98
	v_add_f32_e32 v114, 1.0, v114
	v_add_f32_e32 v100, 1.0, v100
	v_add_f32_e32 v108, 1.0, v108
	v_add_f32_e32 v102, 1.0, v102
	v_add_f32_e32 v110, 1.0, v110
	v_add_f32_e32 v96, 1.0, v96
; __device__ __forceinline__ u32x4 pack8(const f32x4 a, const f32x4 b) { u32x4 w; w.x = cvt_pk_bf16(a[0], a[1]); w.y = cvt_pk_bf16(a[2], a[3]); w.z = cvt_pk_bf16(b[0], b[1]); w.w = cvt_pk_bf16(b[2], b[3]); return w; }
; __device__ __forceinline__ float row_rstd(const u64* ssq, int r) { return __builtin_amdgcn_rsqf(fx_to_pos(ssq[r]) * (1.0f / 4096.0f) + RMS_EPS); }
;     __device__ __forceinline__ void operator()(const f32x4 (&acc)[2][2][4][2], const Unit& u, int wr, int wc, int fr, int fq) const {
;     ...
;             for (int m = 0; m < 4; ++m) { const int r = row0 + ai * HALF + m * 16; const float rs = row_rstd(ssq, r); f32x4 o[2];
; #pragma unroll
;                 for (int n = 0; n < 2; ++n)
; #pragma unroll
;                     for (int j = 0; j < 4; ++j) { const float g = acc[ai][0][m][n][j] * rs, uu = acc[ai][1][m][n][j] * rs;
;                         o[n][j] = g * uu * __builtin_amdgcn_rcpf(1.0f + __expf(-g)); }
;                 *(u32x4*)(HID + (size_t)r * DFF + col0) = pack8(o[0], o[1]); }
	v_add_f32_e32 v104, 1.0, v104
	v_rcp_f32_e32 v98, v98
	v_rcp_f32_e32 v114, v114
	v_rcp_f32_e32 v100, v100
	v_rcp_f32_e32 v108, v108
	v_rcp_f32_e32 v102, v102
	v_rcp_f32_e32 v110, v110
	v_rcp_f32_e32 v96, v96
	v_rcp_f32_e32 v104, v104
	v_mad_i64_i32 v[112:113], s[22:23], v158, s44, v[120:121]
	v_lshl_add_u64 v[112:113], v[112:113], 0, v[122:123]
	v_mul_f32_e32 v99, v99, v98
	v_mul_f32_e32 v107, v107, v114
	v_mul_f32_e32 v100, v101, v100
	v_mul_f32_e32 v101, v109, v108
	v_mul_f32_e32 v102, v103, v102
	v_mul_f32_e32 v103, v111, v110
	v_mul_f32_e32 v108, v97, v96
	v_mul_f32_e32 v104, v105, v104
	v_cvt_pk_bf16_f32 v96, v107, v100
	v_cvt_pk_bf16_f32 v97, v101, v102
	v_cvt_pk_bf16_f32 v98, v103, v108
	v_cvt_pk_bf16_f32 v99, v104, v99
	global_store_dwordx4 v[112:113], v[96:99], off
	s_nop 1
	v_mov_b32_e32 v136, v233
	v_lshlrev_b64 v[100:101], s45, v[136:137]
	v_mov_b32_e32 v99, v84
	v_mov_b32_e32 v84, v93
	v_mov_b32_e32 v93, v86
	v_mov_b32_e32 v86, v95
	v_mov_b32_e32 v95, v80
	v_mov_b32_e32 v80, v89
	v_mov_b32_e32 v89, v82
	v_mov_b32_e32 v82, v91
	v_min_u32_e32 v91, 1, v100
	v_or_b32_e32 v91, v101, v91
	v_cvt_f32_u32_e32 v91, v91
	v_cvt_f32_u32_e32 v100, v232
	v_mov_b32_e32 v98, v92
	v_mov_b32_e32 v92, v94
	v_ldexp_f32 v91, v91, s13
	v_fmac_f32_e32 v91, 0x2f800000, v100
	v_fmamk_f32 v91, v91, 0x39800000, v157
	v_rsq_f32_e32 v100, v91
	v_mov_b32_e32 v94, v88
	v_mov_b32_e32 v88, v90
	v_or_b32_e32 v90, 48, v146
	v_pk_mul_f32 v[82:83], v[82:83], v[100:101] op_sel_hi:[1,0]
	v_ashrrev_i32_e32 v91, 31, v90
	v_pk_mul_f32 v[98:99], v[98:99], v[100:101] op_sel_hi:[1,0]
	v_pk_mul_f32 v[84:85], v[84:85], v[100:101] op_sel_hi:[1,0]
	v_pk_mul_f32 v[92:93], v[92:93], v[100:101] op_sel_hi:[1,0]
	v_pk_mul_f32 v[86:87], v[86:87], v[100:101] op_sel_hi:[1,0]
	v_pk_mul_f32 v[94:95], v[94:95], v[100:101] op_sel_hi:[1,0]
	v_pk_mul_f32 v[80:81], v[80:81], v[100:101] op_sel_hi:[1,0]
	v_pk_mul_f32 v[88:89], v[88:89], v[100:101] op_sel_hi:[1,0]
	v_mul_f32_e32 v83, v82, v83
	v_mul_f32_e32 v82, 0xbfb8aa3b, v82
	v_lshl_add_u64 v[102:103], v[90:91], 3, s[4:5]
	v_mul_f32_e32 v91, v98, v99
	v_mul_f32_e32 v98, 0xbfb8aa3b, v98
	v_mul_f32_e32 v85, v84, v85
	v_mul_f32_e32 v84, 0xbfb8aa3b, v84
	v_mul_f32_e32 v93, v92, v93
	v_mul_f32_e32 v92, 0xbfb8aa3b, v92
	v_mul_f32_e32 v87, v86, v87
	v_mul_f32_e32 v86, 0xbfb8aa3b, v86
	v_mul_f32_e32 v95, v94, v95
	v_mul_f32_e32 v94, 0xbfb8aa3b, v94
	v_mul_f32_e32 v81, v80, v81
	v_mul_f32_e32 v80, 0xbfb8aa3b, v80
	v_mul_f32_e32 v89, v88, v89
	v_mul_f32_e32 v88, 0xbfb8aa3b, v88
	v_exp_f32_e32 v82, v82
	v_exp_f32_e32 v98, v98
	v_exp_f32_e32 v84, v84
	v_exp_f32_e32 v92, v92
	v_exp_f32_e32 v86, v86
	v_exp_f32_e32 v94, v94
	v_exp_f32_e32 v80, v80
	v_exp_f32_e32 v88, v88
	v_add_f32_e32 v82, 1.0, v82
	v_add_f32_e32 v98, 1.0, v98
	v_add_f32_e32 v84, 1.0, v84
	v_add_f32_e32 v92, 1.0, v92
	v_add_f32_e32 v86, 1.0, v86
	v_add_f32_e32 v94, 1.0, v94
	v_add_f32_e32 v80, 1.0, v80
	v_add_f32_e32 v88, 1.0, v88
	v_rcp_f32_e32 v82, v82
	v_rcp_f32_e32 v98, v98
	v_rcp_f32_e32 v84, v84
	v_rcp_f32_e32 v92, v92
	v_rcp_f32_e32 v86, v86
	v_rcp_f32_e32 v94, v94
	v_rcp_f32_e32 v80, v80
	v_rcp_f32_e32 v88, v88
	v_mad_i64_i32 v[96:97], s[22:23], v106, s44, v[120:121]
	v_lshl_add_u64 v[96:97], v[96:97], 0, v[122:123]
	v_mul_f32_e32 v83, v83, v82
	v_mul_f32_e32 v91, v91, v98
	v_mul_f32_e32 v84, v85, v84
	v_mul_f32_e32 v85, v93, v92
	v_mul_f32_e32 v86, v87, v86
	v_mul_f32_e32 v87, v95, v94
	v_mul_f32_e32 v92, v81, v80
	v_mul_f32_e32 v88, v89, v88
	v_cvt_pk_bf16_f32 v80, v91, v84
	v_cvt_pk_bf16_f32 v81, v85, v86
	v_cvt_pk_bf16_f32 v82, v87, v92
	v_cvt_pk_bf16_f32 v83, v88, v83
	global_store_dwordx4 v[96:97], v[80:83], off
	s_nop 1
	v_mov_b32_e32 v136, v235
	v_lshlrev_b64 v[84:85], s45, v[136:137]
	v_mov_b32_e32 v83, v68
	v_mov_b32_e32 v68, v77
	v_mov_b32_e32 v77, v70
	v_mov_b32_e32 v70, v79
	v_mov_b32_e32 v79, v64
	v_mov_b32_e32 v64, v73
	v_min_u32_e32 v73, 1, v84
	v_or_b32_e32 v73, v85, v73
	v_mov_b32_e32 v82, v76
	v_mov_b32_e32 v76, v78
	v_mov_b32_e32 v78, v72
	v_mov_b32_e32 v72, v74
	v_cvt_f32_u32_e32 v74, v73
	v_cvt_f32_u32_e32 v80, v234
	v_mov_b32_e32 v73, v66
	v_mov_b32_e32 v66, v75
	v_ldexp_f32 v74, v74, s13
	v_fmac_f32_e32 v74, 0x2f800000, v80
	v_fmamk_f32 v74, v74, 0x39800000, v157
	v_rsq_f32_e32 v74, v74
	v_mad_i64_i32 v[80:81], s[22:23], v90, s44, v[120:121]
	v_lshl_add_u64 v[80:81], v[80:81], 0, v[122:123]
	v_pk_mul_f32 v[66:67], v[66:67], v[74:75] op_sel_hi:[1,0]
	v_pk_mul_f32 v[82:83], v[82:83], v[74:75] op_sel_hi:[1,0]
	v_pk_mul_f32 v[68:69], v[68:69], v[74:75] op_sel_hi:[1,0]
	v_pk_mul_f32 v[76:77], v[76:77], v[74:75] op_sel_hi:[1,0]
	v_pk_mul_f32 v[70:71], v[70:71], v[74:75] op_sel_hi:[1,0]
	v_pk_mul_f32 v[78:79], v[78:79], v[74:75] op_sel_hi:[1,0]
	v_pk_mul_f32 v[64:65], v[64:65], v[74:75] op_sel_hi:[1,0]
	v_pk_mul_f32 v[72:73], v[72:73], v[74:75] op_sel_hi:[1,0]
	v_mul_f32_e32 v67, v66, v67
	v_mul_f32_e32 v66, 0xbfb8aa3b, v66
	v_mul_f32_e32 v75, 0xbfb8aa3b, v82
	v_mul_f32_e32 v69, v68, v69
	v_mul_f32_e32 v68, 0xbfb8aa3b, v68
	v_mul_f32_e32 v77, v76, v77
	v_mul_f32_e32 v76, 0xbfb8aa3b, v76
	v_mul_f32_e32 v71, v70, v71
	v_mul_f32_e32 v70, 0xbfb8aa3b, v70
	v_mul_f32_e32 v79, v78, v79
	v_mul_f32_e32 v78, 0xbfb8aa3b, v78
	v_mul_f32_e32 v65, v64, v65
	v_mul_f32_e32 v64, 0xbfb8aa3b, v64
	v_mul_f32_e32 v73, v72, v73
	v_mul_f32_e32 v72, 0xbfb8aa3b, v72
	v_exp_f32_e32 v66, v66
	v_exp_f32_e32 v75, v75
	v_exp_f32_e32 v68, v68
	v_exp_f32_e32 v76, v76
	v_exp_f32_e32 v70, v70
	v_exp_f32_e32 v78, v78
	v_exp_f32_e32 v64, v64
	v_exp_f32_e32 v72, v72
	v_add_f32_e32 v66, 1.0, v66
	v_add_f32_e32 v75, 1.0, v75
	v_add_f32_e32 v68, 1.0, v68
	v_add_f32_e32 v76, 1.0, v76
; __device__ __forceinline__ u32x4 pack8(const f32x4 a, const f32x4 b) { u32x4 w; w.x = cvt_pk_bf16(a[0], a[1]); w.y = cvt_pk_bf16(a[2], a[3]); w.z = cvt_pk_bf16(b[0], b[1]); w.w = cvt_pk_bf16(b[2], b[3]); return w; }
; __device__ __forceinline__ float row_rstd(const u64* ssq, int r) { return __builtin_amdgcn_rsqf(fx_to_pos(ssq[r]) * (1.0f / 4096.0f) + RMS_EPS); }
;     __device__ __forceinline__ void operator()(const f32x4 (&acc)[2][2][4][2], const Unit& u, int wr, int wc, int fr, int fq) const {
;     ...
;             for (int m = 0; m < 4; ++m) { const int r = row0 + ai * HALF + m * 16; const float rs = row_rstd(ssq, r); f32x4 o[2];
; #pragma unroll
;                 for (int n = 0; n < 2; ++n)
; #pragma unroll
;                     for (int j = 0; j < 4; ++j) { const float g = acc[ai][0][m][n][j] * rs, uu = acc[ai][1][m][n][j] * rs;
;                         o[n][j] = g * uu * __builtin_amdgcn_rcpf(1.0f + __expf(-g)); }
;                 *(u32x4*)(HID + (size_t)r * DFF + col0) = pack8(o[0], o[1]); }
	v_add_f32_e32 v70, 1.0, v70
	v_add_f32_e32 v78, 1.0, v78
	v_add_f32_e32 v64, 1.0, v64
	v_add_f32_e32 v72, 1.0, v72
	v_rcp_f32_e32 v66, v66
	v_rcp_f32_e32 v75, v75
	v_rcp_f32_e32 v68, v68
	v_rcp_f32_e32 v76, v76
	v_rcp_f32_e32 v70, v70
	v_rcp_f32_e32 v78, v78
	v_rcp_f32_e32 v64, v64
	v_rcp_f32_e32 v72, v72
	v_mul_f32_e32 v74, v82, v83
	v_mul_f32_e32 v67, v67, v66
	v_mul_f32_e32 v74, v74, v75
	v_mul_f32_e32 v68, v69, v68
	v_mul_f32_e32 v69, v77, v76
	v_mul_f32_e32 v70, v71, v70
	v_mul_f32_e32 v71, v79, v78
	v_mul_f32_e32 v75, v65, v64
	v_mul_f32_e32 v72, v73, v72
	v_cvt_pk_bf16_f32 v64, v74, v68
	v_cvt_pk_bf16_f32 v65, v69, v70
	v_cvt_pk_bf16_f32 v66, v71, v75
	v_cvt_pk_bf16_f32 v67, v72, v67
	global_store_dwordx4 v[80:81], v[64:67], off
	s_nop 1
	v_mov_b32_e32 v136, v237
	v_lshlrev_b64 v[68:69], s45, v[136:137]
	v_mov_b32_e32 v67, v52
	v_mov_b32_e32 v52, v61
	v_mov_b32_e32 v61, v54
	v_mov_b32_e32 v54, v63
	v_mov_b32_e32 v63, v48
	v_mov_b32_e32 v48, v57
	v_mov_b32_e32 v57, v50
	v_min_u32_e32 v50, 1, v68
	v_or_b32_e32 v50, v69, v50
	v_mov_b32_e32 v66, v60
	v_mov_b32_e32 v60, v62
	v_mov_b32_e32 v62, v56
	v_mov_b32_e32 v56, v58
	v_cvt_f32_u32_e32 v58, v50
	v_cvt_f32_u32_e32 v64, v236
	v_mov_b32_e32 v50, v59
	v_add_u32_e32 v59, 0x80, v146
	v_ldexp_f32 v58, v58, s13
	v_fmac_f32_e32 v58, 0x2f800000, v64
	v_fmamk_f32 v58, v58, 0x39800000, v157
	v_rsq_f32_e32 v58, v58
	v_mad_i64_i32 v[64:65], s[22:23], v59, s44, v[120:121]
	v_lshl_add_u64 v[64:65], v[64:65], 0, v[122:123]
	v_pk_mul_f32 v[50:51], v[50:51], v[58:59] op_sel_hi:[1,0]
	v_pk_mul_f32 v[66:67], v[66:67], v[58:59] op_sel_hi:[1,0]
	v_pk_mul_f32 v[52:53], v[52:53], v[58:59] op_sel_hi:[1,0]
	v_pk_mul_f32 v[60:61], v[60:61], v[58:59] op_sel_hi:[1,0]
	v_pk_mul_f32 v[54:55], v[54:55], v[58:59] op_sel_hi:[1,0]
	v_pk_mul_f32 v[62:63], v[62:63], v[58:59] op_sel_hi:[1,0]
	v_pk_mul_f32 v[48:49], v[48:49], v[58:59] op_sel_hi:[1,0]
	v_pk_mul_f32 v[56:57], v[56:57], v[58:59] op_sel_hi:[1,0]
	v_mul_f32_e32 v51, v50, v51
	v_mul_f32_e32 v50, 0xbfb8aa3b, v50
	v_mul_f32_e32 v59, 0xbfb8aa3b, v66
	v_mul_f32_e32 v53, v52, v53
	v_mul_f32_e32 v52, 0xbfb8aa3b, v52
	v_mul_f32_e32 v61, v60, v61
	v_mul_f32_e32 v60, 0xbfb8aa3b, v60
	v_mul_f32_e32 v55, v54, v55
	v_mul_f32_e32 v54, 0xbfb8aa3b, v54
	v_mul_f32_e32 v63, v62, v63
	v_mul_f32_e32 v62, 0xbfb8aa3b, v62
	v_mul_f32_e32 v49, v48, v49
	v_mul_f32_e32 v48, 0xbfb8aa3b, v48
	v_mul_f32_e32 v57, v56, v57
	v_mul_f32_e32 v56, 0xbfb8aa3b, v56
	v_exp_f32_e32 v50, v50
	v_exp_f32_e32 v59, v59
	v_exp_f32_e32 v52, v52
	v_exp_f32_e32 v60, v60
	v_exp_f32_e32 v54, v54
	v_exp_f32_e32 v62, v62
	v_exp_f32_e32 v48, v48
	v_exp_f32_e32 v56, v56
	v_add_f32_e32 v50, 1.0, v50
	v_add_f32_e32 v59, 1.0, v59
	v_add_f32_e32 v52, 1.0, v52
	v_add_f32_e32 v60, 1.0, v60
	v_add_f32_e32 v54, 1.0, v54
	v_add_f32_e32 v62, 1.0, v62
	v_add_f32_e32 v48, 1.0, v48
	v_add_f32_e32 v56, 1.0, v56
	v_rcp_f32_e32 v50, v50
	v_rcp_f32_e32 v59, v59
	v_rcp_f32_e32 v52, v52
	v_rcp_f32_e32 v60, v60
	v_rcp_f32_e32 v54, v54
	v_rcp_f32_e32 v62, v62
	v_rcp_f32_e32 v48, v48
	v_rcp_f32_e32 v56, v56
	v_mul_f32_e32 v58, v66, v67
	v_mul_f32_e32 v51, v51, v50
	v_mul_f32_e32 v58, v58, v59
	v_mul_f32_e32 v52, v53, v52
	v_mul_f32_e32 v53, v61, v60
	v_mul_f32_e32 v54, v55, v54
	v_mul_f32_e32 v55, v63, v62
	v_mul_f32_e32 v59, v49, v48
	v_mul_f32_e32 v56, v57, v56
	v_cvt_pk_bf16_f32 v48, v58, v52
	v_cvt_pk_bf16_f32 v49, v53, v54
	v_cvt_pk_bf16_f32 v50, v55, v59
	v_cvt_pk_bf16_f32 v51, v56, v51
	global_store_dwordx4 v[64:65], v[48:51], off
	s_nop 1
	v_mov_b32_e32 v136, v239
	v_lshlrev_b64 v[52:53], s45, v[136:137]
	v_mov_b32_e32 v51, v36
	v_mov_b32_e32 v36, v45
	v_mov_b32_e32 v45, v38
	v_mov_b32_e32 v38, v47
	v_mov_b32_e32 v47, v32
	v_mov_b32_e32 v32, v41
	v_mov_b32_e32 v41, v34
	v_min_u32_e32 v34, 1, v52
	v_or_b32_e32 v34, v53, v34
	v_mov_b32_e32 v50, v44
	v_mov_b32_e32 v44, v46
	v_mov_b32_e32 v46, v40
	v_mov_b32_e32 v40, v42
	v_cvt_f32_u32_e32 v42, v34
	v_cvt_f32_u32_e32 v48, v238
	v_mov_b32_e32 v34, v43
	v_add_u32_e32 v43, 0x90, v146
	v_ldexp_f32 v42, v42, s13
	v_fmac_f32_e32 v42, 0x2f800000, v48
	v_fmamk_f32 v42, v42, 0x39800000, v157
	v_rsq_f32_e32 v42, v42
	v_mad_i64_i32 v[48:49], s[22:23], v43, s44, v[120:121]
	v_lshl_add_u64 v[48:49], v[48:49], 0, v[122:123]
	v_pk_mul_f32 v[34:35], v[34:35], v[42:43] op_sel_hi:[1,0]
	v_pk_mul_f32 v[50:51], v[50:51], v[42:43] op_sel_hi:[1,0]
	v_pk_mul_f32 v[36:37], v[36:37], v[42:43] op_sel_hi:[1,0]
	v_pk_mul_f32 v[44:45], v[44:45], v[42:43] op_sel_hi:[1,0]
	v_pk_mul_f32 v[38:39], v[38:39], v[42:43] op_sel_hi:[1,0]
	v_pk_mul_f32 v[46:47], v[46:47], v[42:43] op_sel_hi:[1,0]
	v_pk_mul_f32 v[32:33], v[32:33], v[42:43] op_sel_hi:[1,0]
	v_pk_mul_f32 v[40:41], v[40:41], v[42:43] op_sel_hi:[1,0]
	v_mul_f32_e32 v35, v34, v35
	v_mul_f32_e32 v34, 0xbfb8aa3b, v34
	v_mul_f32_e32 v43, 0xbfb8aa3b, v50
	v_mul_f32_e32 v37, v36, v37
	v_mul_f32_e32 v36, 0xbfb8aa3b, v36
	v_mul_f32_e32 v45, v44, v45
	v_mul_f32_e32 v44, 0xbfb8aa3b, v44
	v_mul_f32_e32 v39, v38, v39
	v_mul_f32_e32 v38, 0xbfb8aa3b, v38
	v_mul_f32_e32 v47, v46, v47
	v_mul_f32_e32 v46, 0xbfb8aa3b, v46
	v_mul_f32_e32 v33, v32, v33
	v_mul_f32_e32 v32, 0xbfb8aa3b, v32
	v_mul_f32_e32 v41, v40, v41
	v_mul_f32_e32 v40, 0xbfb8aa3b, v40
	v_exp_f32_e32 v34, v34
	v_exp_f32_e32 v43, v43
	v_exp_f32_e32 v36, v36
	v_exp_f32_e32 v44, v44
	v_exp_f32_e32 v38, v38
	v_exp_f32_e32 v46, v46
	v_exp_f32_e32 v32, v32
	v_exp_f32_e32 v40, v40
	v_add_f32_e32 v34, 1.0, v34
	v_add_f32_e32 v43, 1.0, v43
	v_add_f32_e32 v36, 1.0, v36
	v_add_f32_e32 v44, 1.0, v44
	v_add_f32_e32 v38, 1.0, v38
	v_add_f32_e32 v46, 1.0, v46
	v_add_f32_e32 v32, 1.0, v32
	v_add_f32_e32 v40, 1.0, v40
; __device__ __forceinline__ float fx_to_pos(u64 x) { return (float)(unsigned)(x >> 32) + (float)(unsigned)x * (1.0f / 4294967296.0f); }
; __device__ __forceinline__ u32x4 pack8(const f32x4 a, const f32x4 b) { u32x4 w; w.x = cvt_pk_bf16(a[0], a[1]); w.y = cvt_pk_bf16(a[2], a[3]); w.z = cvt_pk_bf16(b[0], b[1]); w.w = cvt_pk_bf16(b[2], b[3]); return w; }
; __device__ __forceinline__ float row_rstd(const u64* ssq, int r) { return __builtin_amdgcn_rsqf(fx_to_pos(ssq[r]) * (1.0f / 4096.0f) + RMS_EPS); }
;     __device__ __forceinline__ void operator()(const f32x4 (&acc)[2][2][4][2], const Unit& u, int wr, int wc, int fr, int fq) const {
;     ...
;             for (int m = 0; m < 4; ++m) { const int r = row0 + ai * HALF + m * 16; const float rs = row_rstd(ssq, r); f32x4 o[2];
; #pragma unroll
;                 for (int n = 0; n < 2; ++n)
; #pragma unroll
;                     for (int j = 0; j < 4; ++j) { const float g = acc[ai][0][m][n][j] * rs, uu = acc[ai][1][m][n][j] * rs;
;                         o[n][j] = g * uu * __builtin_amdgcn_rcpf(1.0f + __expf(-g)); }
;                 *(u32x4*)(HID + (size_t)r * DFF + col0) = pack8(o[0], o[1]); }
	v_rcp_f32_e32 v34, v34
	v_rcp_f32_e32 v43, v43
	v_rcp_f32_e32 v36, v36
	v_rcp_f32_e32 v44, v44
	v_rcp_f32_e32 v38, v38
	v_rcp_f32_e32 v46, v46
	v_rcp_f32_e32 v32, v32
	v_rcp_f32_e32 v40, v40
	v_mul_f32_e32 v42, v50, v51
	v_mul_f32_e32 v35, v35, v34
	v_mul_f32_e32 v42, v42, v43
	v_mul_f32_e32 v36, v37, v36
	v_mul_f32_e32 v37, v45, v44
	v_mul_f32_e32 v38, v39, v38
	v_mul_f32_e32 v39, v47, v46
	v_mul_f32_e32 v43, v33, v32
	v_mul_f32_e32 v40, v41, v40
	v_cvt_pk_bf16_f32 v32, v42, v36
	v_cvt_pk_bf16_f32 v33, v37, v38
	v_cvt_pk_bf16_f32 v34, v39, v43
	v_cvt_pk_bf16_f32 v35, v40, v35
	global_store_dwordx4 v[48:49], v[32:35], off
	s_nop 1
	v_mov_b32_e32 v136, v241
	v_lshlrev_b64 v[36:37], s45, v[136:137]
	v_mov_b32_e32 v35, v20
	v_mov_b32_e32 v20, v29
	v_mov_b32_e32 v29, v22
	v_mov_b32_e32 v22, v31
	v_mov_b32_e32 v31, v16
	v_mov_b32_e32 v16, v25
	v_mov_b32_e32 v25, v18
	v_min_u32_e32 v18, 1, v36
	v_or_b32_e32 v18, v37, v18
	v_mov_b32_e32 v34, v28
	v_mov_b32_e32 v28, v30
	v_mov_b32_e32 v30, v24
	v_mov_b32_e32 v24, v26
	v_cvt_f32_u32_e32 v26, v18
	v_cvt_f32_u32_e32 v32, v240
	v_mov_b32_e32 v18, v27
	v_add_u32_e32 v27, 0xa0, v146
	v_ldexp_f32 v26, v26, s13
	v_fmac_f32_e32 v26, 0x2f800000, v32
	v_fmamk_f32 v26, v26, 0x39800000, v157
	v_rsq_f32_e32 v26, v26
	v_mad_i64_i32 v[32:33], s[22:23], v27, s44, v[120:121]
	v_lshl_add_u64 v[32:33], v[32:33], 0, v[122:123]
	v_pk_mul_f32 v[18:19], v[18:19], v[26:27] op_sel_hi:[1,0]
	v_pk_mul_f32 v[34:35], v[34:35], v[26:27] op_sel_hi:[1,0]
	v_pk_mul_f32 v[20:21], v[20:21], v[26:27] op_sel_hi:[1,0]
	v_pk_mul_f32 v[28:29], v[28:29], v[26:27] op_sel_hi:[1,0]
	v_pk_mul_f32 v[22:23], v[22:23], v[26:27] op_sel_hi:[1,0]
	v_pk_mul_f32 v[30:31], v[30:31], v[26:27] op_sel_hi:[1,0]
	v_pk_mul_f32 v[16:17], v[16:17], v[26:27] op_sel_hi:[1,0]
	v_pk_mul_f32 v[24:25], v[24:25], v[26:27] op_sel_hi:[1,0]
	v_mul_f32_e32 v19, v18, v19
	v_mul_f32_e32 v18, 0xbfb8aa3b, v18
	v_mul_f32_e32 v27, 0xbfb8aa3b, v34
	v_mul_f32_e32 v21, v20, v21
	v_mul_f32_e32 v20, 0xbfb8aa3b, v20
	v_mul_f32_e32 v29, v28, v29
	v_mul_f32_e32 v28, 0xbfb8aa3b, v28
	v_mul_f32_e32 v23, v22, v23
	v_mul_f32_e32 v22, 0xbfb8aa3b, v22
	v_mul_f32_e32 v31, v30, v31
	v_mul_f32_e32 v30, 0xbfb8aa3b, v30
	v_mul_f32_e32 v17, v16, v17
	v_mul_f32_e32 v16, 0xbfb8aa3b, v16
	v_mul_f32_e32 v25, v24, v25
	v_mul_f32_e32 v24, 0xbfb8aa3b, v24
	v_exp_f32_e32 v18, v18
	v_exp_f32_e32 v27, v27
	v_exp_f32_e32 v20, v20
	v_exp_f32_e32 v28, v28
	v_exp_f32_e32 v22, v22
	v_exp_f32_e32 v30, v30
	v_exp_f32_e32 v16, v16
	v_exp_f32_e32 v24, v24
	v_add_f32_e32 v18, 1.0, v18
	v_add_f32_e32 v27, 1.0, v27
	v_add_f32_e32 v20, 1.0, v20
	v_add_f32_e32 v28, 1.0, v28
	v_add_f32_e32 v22, 1.0, v22
	v_add_f32_e32 v30, 1.0, v30
	v_add_f32_e32 v16, 1.0, v16
	v_add_f32_e32 v24, 1.0, v24
	v_rcp_f32_e32 v18, v18
	v_rcp_f32_e32 v27, v27
	v_rcp_f32_e32 v20, v20
	v_rcp_f32_e32 v28, v28
	v_rcp_f32_e32 v22, v22
	v_rcp_f32_e32 v30, v30
	v_rcp_f32_e32 v16, v16
	v_rcp_f32_e32 v24, v24
	v_mul_f32_e32 v26, v34, v35
	v_mul_f32_e32 v19, v19, v18
	v_mul_f32_e32 v26, v26, v27
	v_mul_f32_e32 v20, v21, v20
	v_mul_f32_e32 v21, v29, v28
	v_mul_f32_e32 v22, v23, v22
	v_mul_f32_e32 v23, v31, v30
	v_mul_f32_e32 v27, v17, v16
	v_mul_f32_e32 v24, v25, v24
	v_cvt_pk_bf16_f32 v16, v26, v20
	v_cvt_pk_bf16_f32 v17, v21, v22
	v_cvt_pk_bf16_f32 v18, v23, v27
	v_cvt_pk_bf16_f32 v19, v24, v19
	global_store_dwordx4 v[32:33], v[16:19], off
	s_nop 1
	v_mov_b32_e32 v136, v243
	v_mov_b32_e32 v18, v12
	v_mov_b32_e32 v19, v4
	v_mov_b32_e32 v4, v13
	v_mov_b32_e32 v12, v14
	v_mov_b32_e32 v13, v6
	v_mov_b32_e32 v6, v15
	v_mov_b32_e32 v14, v8
	v_mov_b32_e32 v15, v0
	v_mov_b32_e32 v0, v9
	v_mov_b32_e32 v8, v10
	v_mov_b32_e32 v9, v2
	v_mov_b32_e32 v2, v11
	v_lshlrev_b64 v[10:11], s45, v[136:137]
	v_min_u32_e32 v10, 1, v10
	v_or_b32_e32 v10, v11, v10
	v_cvt_f32_u32_e32 v10, v10
	v_cvt_f32_u32_e32 v11, v242
	v_add_u32_e32 v16, 0xb0, v146
	v_mad_i64_i32 v[16:17], s[22:23], v16, s44, v[120:121]
	v_ldexp_f32 v10, v10, s13
	v_fmac_f32_e32 v10, 0x2f800000, v11
	v_fmamk_f32 v10, v10, 0x39800000, v157
	v_rsq_f32_e32 v10, v10
	v_lshl_add_u64 v[16:17], v[16:17], 0, v[122:123]
	v_pk_mul_f32 v[2:3], v[2:3], v[10:11] op_sel_hi:[1,0]
	v_pk_mul_f32 v[18:19], v[18:19], v[10:11] op_sel_hi:[1,0]
	v_pk_mul_f32 v[4:5], v[4:5], v[10:11] op_sel_hi:[1,0]
	v_pk_mul_f32 v[12:13], v[12:13], v[10:11] op_sel_hi:[1,0]
	v_pk_mul_f32 v[6:7], v[6:7], v[10:11] op_sel_hi:[1,0]
	v_pk_mul_f32 v[14:15], v[14:15], v[10:11] op_sel_hi:[1,0]
	v_pk_mul_f32 v[0:1], v[0:1], v[10:11] op_sel_hi:[1,0]
	v_pk_mul_f32 v[8:9], v[8:9], v[10:11] op_sel_hi:[1,0]
	v_mul_f32_e32 v3, v2, v3
	v_mul_f32_e32 v2, 0xbfb8aa3b, v2
	v_mul_f32_e32 v11, 0xbfb8aa3b, v18
	v_mul_f32_e32 v5, v4, v5
	v_mul_f32_e32 v4, 0xbfb8aa3b, v4
	v_mul_f32_e32 v13, v12, v13
	v_mul_f32_e32 v12, 0xbfb8aa3b, v12
	v_mul_f32_e32 v7, v6, v7
	v_mul_f32_e32 v6, 0xbfb8aa3b, v6
	v_mul_f32_e32 v15, v14, v15
	v_mul_f32_e32 v14, 0xbfb8aa3b, v14
	v_mul_f32_e32 v1, v0, v1
	v_mul_f32_e32 v0, 0xbfb8aa3b, v0
	v_mul_f32_e32 v9, v8, v9
	v_mul_f32_e32 v8, 0xbfb8aa3b, v8
	v_exp_f32_e32 v2, v2
	v_exp_f32_e32 v11, v11
	v_exp_f32_e32 v4, v4
	v_exp_f32_e32 v12, v12
	v_exp_f32_e32 v6, v6
	v_exp_f32_e32 v14, v14
	v_exp_f32_e32 v0, v0
	v_exp_f32_e32 v8, v8
	v_add_f32_e32 v2, 1.0, v2
	v_add_f32_e32 v11, 1.0, v11
	v_add_f32_e32 v4, 1.0, v4
	v_add_f32_e32 v12, 1.0, v12
	v_add_f32_e32 v6, 1.0, v6
	v_add_f32_e32 v14, 1.0, v14
	v_add_f32_e32 v0, 1.0, v0
	v_add_f32_e32 v8, 1.0, v8
	v_rcp_f32_e32 v2, v2
	v_rcp_f32_e32 v11, v11
	v_rcp_f32_e32 v4, v4
	v_rcp_f32_e32 v12, v12
	v_rcp_f32_e32 v6, v6
	v_rcp_f32_e32 v14, v14
	v_rcp_f32_e32 v0, v0
	v_rcp_f32_e32 v8, v8
	v_mul_f32_e32 v10, v18, v19
	v_mul_f32_e32 v3, v3, v2
	v_mul_f32_e32 v10, v10, v11
	v_mul_f32_e32 v4, v5, v4
	v_mul_f32_e32 v5, v13, v12
	v_mul_f32_e32 v6, v7, v6
	v_mul_f32_e32 v7, v15, v14
	v_mul_f32_e32 v11, v1, v0
	v_mul_f32_e32 v8, v9, v8
	v_cvt_pk_bf16_f32 v0, v10, v4
	v_cvt_pk_bf16_f32 v1, v5, v6
	v_cvt_pk_bf16_f32 v2, v7, v11
	v_cvt_pk_bf16_f32 v3, v8, v3
	global_store_dwordx4 v[16:17], v[0:3], off
	s_cbranch_vccnz .LBB0_1760
	s_andn2_b64 vcc, exec, s[6:7]
	s_cbranch_vccnz .LBB0_1759
	s_barrier
	s_branch .LBB0_1759

; __global__ void __launch_bounds__(NTHREADS, 2) hybrid_fwd(Args args) {
	.amdhsa_kernel _Z10hybrid_fwd4Args
		.amdhsa_group_segment_fixed_size 0
		.amdhsa_private_segment_fixed_size 0
		.amdhsa_kernarg_size 464
		.amdhsa_user_sgpr_count 2
		.amdhsa_user_sgpr_dispatch_ptr 0
		.amdhsa_user_sgpr_queue_ptr 0
		.amdhsa_user_sgpr_kernarg_segment_ptr 1
		.amdhsa_user_sgpr_dispatch_id 0
		.amdhsa_user_sgpr_kernarg_preload_length 0
		.amdhsa_user_sgpr_kernarg_preload_offset 0
		.amdhsa_user_sgpr_private_segment_size 0
		.amdhsa_uses_dynamic_stack 0
		.amdhsa_enable_private_segment 0
		.amdhsa_system_sgpr_workgroup_id_x 1
		.amdhsa_system_sgpr_workgroup_id_y 0
		.amdhsa_system_sgpr_workgroup_id_z 0
		.amdhsa_system_sgpr_workgroup_info 0
		.amdhsa_system_vgpr_workitem_id 0
		.amdhsa_next_free_vgpr 256
		.amdhsa_next_free_sgpr 98
		.amdhsa_accum_offset 256
		.amdhsa_reserve_vcc 1
		.amdhsa_float_round_mode_32 0
		.amdhsa_float_round_mode_16_64 0
		.amdhsa_float_denorm_mode_32 3
		.amdhsa_float_denorm_mode_16_64 3
		.amdhsa_dx10_clamp 1
		.amdhsa_ieee_mode 1
		.amdhsa_fp16_overflow 0
		.amdhsa_tg_split 0
		.amdhsa_exception_fp_ieee_invalid_op 0
		.amdhsa_exception_fp_denorm_src 0
		.amdhsa_exception_fp_ieee_div_zero 0
		.amdhsa_exception_fp_ieee_overflow 0
		.amdhsa_exception_fp_ieee_underflow 0
		.amdhsa_exception_fp_ieee_inexact 0
		.amdhsa_exception_int_div_zero 0
	.end_amdhsa_kernel

; __global__ void __launch_bounds__(NTHREADS, 2) hybrid_fwd(Args args) {
amdhsa.kernels:
  - .agpr_count:     0
    .args:
      - .offset:         0
        .size:           208
        .value_kind:     by_value
      - .offset:         208
        .size:           4
        .value_kind:     hidden_block_count_x
      - .offset:         212
        .size:           4
        .value_kind:     hidden_block_count_y
      - .offset:         216
        .size:           4
        .value_kind:     hidden_block_count_z
      - .offset:         220
        .size:           2
        .value_kind:     hidden_group_size_x
      - .offset:         222
        .size:           2
        .value_kind:     hidden_group_size_y
      - .offset:         224
        .size:           2
        .value_kind:     hidden_group_size_z
      - .offset:         226
        .size:           2
        .value_kind:     hidden_remainder_x
      - .offset:         228
        .size:           2
        .value_kind:     hidden_remainder_y
      - .offset:         230
        .size:           2
        .value_kind:     hidden_remainder_z
      - .offset:         248
        .size:           8
        .value_kind:     hidden_global_offset_x
      - .offset:         256
        .size:           8
        .value_kind:     hidden_global_offset_y
      - .offset:         264
        .size:           8
        .value_kind:     hidden_global_offset_z
      - .offset:         272
        .size:           2
        .value_kind:     hidden_grid_dims
      - .offset:         328
        .size:           4
        .value_kind:     hidden_dynamic_lds_size
    .group_segment_fixed_size: 0
    .kernarg_segment_align: 8
    .kernarg_segment_size: 464
    .language:       OpenCL C
    .language_version:
      - 2
      - 0
    .max_flat_workgroup_size: 512
    .name:           _Z10hybrid_fwd4Args
    .private_segment_fixed_size: 0
    .sgpr_count:     104
    .sgpr_spill_count: 94
    .symbol:         _Z10hybrid_fwd4Args.kd
    .uniform_work_group_size: 1
    .uses_dynamic_stack: false
    .vgpr_count:     256
    .vgpr_spill_count: 0
    .wavefront_size: 64
